# v16 plus: K-loop B-fragment LDS read base precomputed once per unit (4 VALU address adds per iteration removed; reads use immediate offsets)
# baseline (speedup 1.0000x reference)
; #define PG8_STAGE(bufoff, gbase, voff) do { _Pragma("unroll") for (int _i = 0; _i < 2; ++_i) \
;         __builtin_amdgcn_global_load_lds((const unsigned*)((const char*)(gbase) + (voff)[_i]), (LAS unsigned*)(lds + (bufoff) + ldsw + _i * 8192), 16, 0, 0); } while (0)
; #define PG8_LDA(dst, b, h) do { _Pragma("unroll") for (int m = 0; m < 4; ++m) _Pragma("unroll") for (int k = 0; k < 2; ++k) dst[m][k] = *(const LAS bf16x8*)(lds + PG8_SA(b, h) + aoff + m * 2048 + k * 1024); } while (0)
; #define PG8_LDB(dst, b, h) do { _Pragma("unroll") for (int n = 0; n < 2; ++n) _Pragma("unroll") for (int k = 0; k < 2; ++k) dst[n][k] = *(const LAS bf16x8*)(lds + PG8_SB(b, h) + boff + n * 2048 + k * 1024); } while (0)
; #define PG8_MMA(ai, bj, At, Bt) do { __builtin_amdgcn_s_setprio(1); _Pragma("unroll") for (int m = 0; m < 4; ++m) _Pragma("unroll") for (int n = 0; n < 2; ++n) _Pragma("unroll") for (int k = 0; k < 2; ++k) \
;         acc[ai][bj][m][n] = __builtin_amdgcn_mfma_f32_16x16x32_bf16(Bt[n][k], At[m][k], acc[ai][bj][m][n], 0, 0, 0); __builtin_amdgcn_s_setprio(0); } while (0)
; template <class Epi, class Sched>
; __device__ __forceinline__ void gemm_phase(LAS unsigned char* lds, const Gemm g, const Sched& S, const Epi& E) {
;     ...
;         const bool has_next = S.next(ui + 1, nxt);
;         const char* nA = has_next ? (const char*)g.A + (size_t)nxt.pm * tstep + (size_t)nxt.kt0 * kstep : cA; const char* nB = has_next ? (const char*)g.Bt + (size_t)nxt.pn * tstep + (size_t)nxt.kt0 * kstep : cB;
;         const int nt = cur.nkt;
;         for (int t = 0; t < nt; t += 2) {
;             const bool last = (t == nt - 2);
;             const char* a1 = cA + (size_t)(t + 1) * kstep;
;             const char* a2 = last ? nA : cA + (size_t)(t + 2) * kstep; const char* b2 = last ? nB : cB + (size_t)(t + 2) * kstep;
;             const char* a3 = a2 + kstep; const char* b3 = b2 + kstep;
;             PG8_LDB(B0, 0, 0); PG8_SCHED; PG8_LDA(At, 0, 0); PG8_STAGE(PG8_SA(1, 1), a1 + hstep, voffA);
;             PG8_WAIT_L(8); PG8_BAR; PG8_WAIT_L(0); PG8_MMA(0, 0, At, B0); PG8_BAR; PG8_SCHED;
;     ...
;         for (int a = 0; a < 2; ++a)
; #pragma unroll
;             for (int b = 0; b < 2; ++b)
; #pragma unroll
;                 for (int m = 0; m < 4; ++m)
; #pragma unroll
;                     for (int n = 0; n < 2; ++n) acc[a][b][m][n] = (f32x4){0.f, 0.f, 0.f, 0.f};
.LBB0_124:
	v_mov_b64_e32 v[0:1], 0x154
	s_ashr_i32 s7, s6, 31
	v_cmp_lt_i64_e32 vcc, s[12:13], v[0:1]
	s_lshl_b64 s[12:13], s[6:7], 20
	v_readlane_b32 s5, v253, 15
	s_add_u32 s12, s5, s12
	v_readlane_b32 s5, v253, 16
	s_addc_u32 s13, s5, s13
	s_and_b64 s[14:15], vcc, exec
	s_cselect_b32 s7, s13, s17
	s_cselect_b32 s40, s12, s16
	s_ashr_i32 s5, s4, 31
	s_lshl_b64 s[14:15], s[4:5], 20
	s_add_u32 s14, s25, s14
	s_addc_u32 s15, s27, s15
	s_and_b64 s[22:23], vcc, exec
	s_cselect_b32 s5, s15, s21
	s_cselect_b32 s41, s14, s20
	s_add_u32 s16, s16, 0x80080
	s_addc_u32 s17, s17, 0
	s_add_u32 s42, s20, 0x100
	v_mov_b32_e32 v0, 0
	s_addc_u32 s43, s21, 0
	s_mov_b32 s44, -2
	v_mov_b32_e32 v1, v0
	v_mov_b32_e32 v2, v0
	v_mov_b32_e32 v3, v0
	v_mov_b32_e32 v4, v0
	v_mov_b32_e32 v5, v0
	v_mov_b32_e32 v6, v0
	v_mov_b32_e32 v7, v0
	v_mov_b32_e32 v8, v0
	v_mov_b32_e32 v9, v0
	v_mov_b32_e32 v10, v0
	v_mov_b32_e32 v11, v0
	v_mov_b32_e32 v16, v0
	v_mov_b32_e32 v17, v0
	v_mov_b32_e32 v18, v0
	v_mov_b32_e32 v19, v0
	v_mov_b32_e32 v24, v0
	v_mov_b32_e32 v25, v0
	v_mov_b32_e32 v26, v0
	v_mov_b32_e32 v27, v0
	v_mov_b32_e32 v32, v0
	v_mov_b32_e32 v33, v0
	v_mov_b32_e32 v34, v0
	v_mov_b32_e32 v35, v0
	v_mov_b32_e32 v40, v0
	v_mov_b32_e32 v41, v0
	v_mov_b32_e32 v42, v0
	v_mov_b32_e32 v43, v0
	v_mov_b32_e32 v48, v0
	v_mov_b32_e32 v49, v0
	v_mov_b32_e32 v50, v0
	v_mov_b32_e32 v51, v0
	v_mov_b32_e32 v12, v0
	v_mov_b32_e32 v13, v0
	v_mov_b32_e32 v14, v0
	v_mov_b32_e32 v15, v0
	v_mov_b32_e32 v20, v0
	v_mov_b32_e32 v21, v0
	v_mov_b32_e32 v22, v0
	v_mov_b32_e32 v23, v0
	v_mov_b32_e32 v28, v0
	v_mov_b32_e32 v29, v0
	v_mov_b32_e32 v30, v0
	v_mov_b32_e32 v31, v0
	v_mov_b32_e32 v36, v0
	v_mov_b32_e32 v37, v0
	v_mov_b32_e32 v38, v0
	v_mov_b32_e32 v39, v0
	v_mov_b32_e32 v44, v0
	v_mov_b32_e32 v45, v0
	v_mov_b32_e32 v46, v0
	v_mov_b32_e32 v47, v0
	v_mov_b32_e32 v52, v0
	v_mov_b32_e32 v53, v0
	v_mov_b32_e32 v54, v0
	v_mov_b32_e32 v55, v0
	v_mov_b32_e32 v56, v0
	v_mov_b32_e32 v57, v0
	v_mov_b32_e32 v58, v0
	v_mov_b32_e32 v59, v0
	v_mov_b32_e32 v60, v0
	v_mov_b32_e32 v61, v0
	v_mov_b32_e32 v62, v0
	v_mov_b32_e32 v63, v0
	v_mov_b32_e32 v64, v0
	v_mov_b32_e32 v65, v0
	v_mov_b32_e32 v66, v0
	v_mov_b32_e32 v67, v0
	v_mov_b32_e32 v68, v0
	v_mov_b32_e32 v69, v0
	v_mov_b32_e32 v70, v0
	v_mov_b32_e32 v71, v0
	v_mov_b32_e32 v72, v0
	v_mov_b32_e32 v73, v0
	v_mov_b32_e32 v74, v0
	v_mov_b32_e32 v75, v0
	v_mov_b32_e32 v80, v0
	v_mov_b32_e32 v81, v0
	v_mov_b32_e32 v82, v0
	v_mov_b32_e32 v83, v0
	v_mov_b32_e32 v88, v0
	v_mov_b32_e32 v89, v0
	v_mov_b32_e32 v90, v0
	v_mov_b32_e32 v91, v0
	v_mov_b32_e32 v96, v0
	v_mov_b32_e32 v97, v0
	v_mov_b32_e32 v98, v0
	v_mov_b32_e32 v99, v0
	v_mov_b32_e32 v104, v0
	v_mov_b32_e32 v105, v0
	v_mov_b32_e32 v106, v0
	v_mov_b32_e32 v107, v0
	v_mov_b32_e32 v112, v0
	v_mov_b32_e32 v113, v0
	v_mov_b32_e32 v114, v0
	v_mov_b32_e32 v115, v0
	v_mov_b32_e32 v76, v0
	v_mov_b32_e32 v77, v0
	v_mov_b32_e32 v78, v0
	v_mov_b32_e32 v79, v0
	v_mov_b32_e32 v84, v0
	v_mov_b32_e32 v85, v0
	v_mov_b32_e32 v86, v0
	v_mov_b32_e32 v87, v0
	v_mov_b32_e32 v92, v0
	v_mov_b32_e32 v93, v0
	v_mov_b32_e32 v94, v0
	v_mov_b32_e32 v95, v0
	v_mov_b32_e32 v100, v0
	v_mov_b32_e32 v101, v0
	v_mov_b32_e32 v102, v0
	v_mov_b32_e32 v103, v0
	v_mov_b32_e32 v108, v0
	v_mov_b32_e32 v109, v0
	v_mov_b32_e32 v110, v0
	v_mov_b32_e32 v111, v0
	v_mov_b32_e32 v116, v0
	v_mov_b32_e32 v117, v0
	v_mov_b32_e32 v118, v0
	v_mov_b32_e32 v119, v0
	v_mov_b32_e32 v120, v0
	v_mov_b32_e32 v121, v0
	v_mov_b32_e32 v122, v0
	v_mov_b32_e32 v123, v0
	v_mov_b32_e32 v124, v0
	v_mov_b32_e32 v125, v0
	v_mov_b32_e32 v126, v0
	v_mov_b32_e32 v127, v0
	v_add_u32_e32 v129, 0x10000, v143
.LBB0_125:
	s_add_u32 s20, s16, 0xfff80080
	s_addc_u32 s21, s17, -1
	s_add_i32 s45, 0, 0x10000
	ds_read_b128 v[138:141], v129
	ds_read_b128 v[160:163], v129 offset:1024
	ds_read_b128 v[164:167], v129 offset:2048
	ds_read_b128 v[168:171], v129 offset:3072
	s_cmp_eq_u32 s44, 28
	s_cselect_b32 s23, s7, s21
	s_cselect_b32 s22, s40, s20
	s_cselect_b32 s21, s5, s43
	s_cselect_b32 s20, s41, s42
	s_add_i32 m0, s30, 0xc000
	ds_read_b128 v[172:175], v145
	ds_read_b128 v[200:203], v145 offset:1024
	ds_read_b128 v[204:207], v145 offset:2048
	ds_read_b128 v[208:211], v145 offset:3072
	ds_read_b128 v[212:215], v145 offset:4096
	ds_read_b128 v[216:219], v145 offset:5120
	ds_read_b128 v[220:223], v145 offset:6144
	ds_read_b128 v[224:227], v145 offset:7168
	global_load_lds_dwordx4 v134, s[16:17]
	s_add_i32 m0, s30, 0xe000
	s_nop 0
	global_load_lds_dwordx4 v136, s[16:17]
	s_waitcnt lgkmcnt(8)
	s_barrier
	s_waitcnt lgkmcnt(0)
	s_waitcnt lgkmcnt(0)
	v_mfma_f32_16x16x32_bf16 v[124:127], v[138:141], v[172:175], v[124:127]
	v_mfma_f32_16x16x32_bf16 v[120:123], v[164:167], v[172:175], v[120:123]
	v_mfma_f32_16x16x32_bf16 v[116:119], v[138:141], v[204:207], v[116:119]
	v_mfma_f32_16x16x32_bf16 v[108:111], v[164:167], v[204:207], v[108:111]
	v_mfma_f32_16x16x32_bf16 v[100:103], v[138:141], v[212:215], v[100:103]
	v_mfma_f32_16x16x32_bf16 v[92:95], v[164:167], v[212:215], v[92:95]
	v_mfma_f32_16x16x32_bf16 v[84:87], v[138:141], v[220:223], v[84:87]
	v_mfma_f32_16x16x32_bf16 v[76:79], v[164:167], v[220:223], v[76:79]
	v_mfma_f32_16x16x32_bf16 v[124:127], v[160:163], v[200:203], v[124:127]
	v_mfma_f32_16x16x32_bf16 v[120:123], v[168:171], v[200:203], v[120:123]
	v_mfma_f32_16x16x32_bf16 v[116:119], v[160:163], v[208:211], v[116:119]
	v_mfma_f32_16x16x32_bf16 v[108:111], v[168:171], v[208:211], v[108:111]
	v_mfma_f32_16x16x32_bf16 v[100:103], v[160:163], v[216:219], v[100:103]
	v_mfma_f32_16x16x32_bf16 v[92:95], v[168:171], v[216:219], v[92:95]
	v_mfma_f32_16x16x32_bf16 v[84:87], v[160:163], v[224:227], v[84:87]
	v_mfma_f32_16x16x32_bf16 v[76:79], v[168:171], v[224:227], v[76:79]
	s_barrier
; #define PG8_STAGE(bufoff, gbase, voff) do { _Pragma("unroll") for (int _i = 0; _i < 2; ++_i) \
;         __builtin_amdgcn_global_load_lds((const unsigned*)((const char*)(gbase) + (voff)[_i]), (LAS unsigned*)(lds + (bufoff) + ldsw + _i * 8192), 16, 0, 0); } while (0)
; #define PG8_LDA(dst, b, h) do { _Pragma("unroll") for (int m = 0; m < 4; ++m) _Pragma("unroll") for (int k = 0; k < 2; ++k) dst[m][k] = *(const LAS bf16x8*)(lds + PG8_SA(b, h) + aoff + m * 2048 + k * 1024); } while (0)
; #define PG8_LDB(dst, b, h) do { _Pragma("unroll") for (int n = 0; n < 2; ++n) _Pragma("unroll") for (int k = 0; k < 2; ++k) dst[n][k] = *(const LAS bf16x8*)(lds + PG8_SB(b, h) + boff + n * 2048 + k * 1024); } while (0)
; #define PG8_MMA(ai, bj, At, Bt) do { __builtin_amdgcn_s_setprio(1); _Pragma("unroll") for (int m = 0; m < 4; ++m) _Pragma("unroll") for (int n = 0; n < 2; ++n) _Pragma("unroll") for (int k = 0; k < 2; ++k) \
;         acc[ai][bj][m][n] = __builtin_amdgcn_mfma_f32_16x16x32_bf16(Bt[n][k], At[m][k], acc[ai][bj][m][n], 0, 0, 0); __builtin_amdgcn_s_setprio(0); } while (0)
; #define PG8_WAIT_V(n) asm volatile("s_waitcnt vmcnt(" #n ")" ::: "memory")
; #define PG8_WAIT_L(n) asm volatile("s_waitcnt lgkmcnt(" #n ")" ::: "memory")
; #define PG8_BAR __builtin_amdgcn_s_barrier()
; #define PG8_SCHED __builtin_amdgcn_sched_barrier(0)
; template <class Epi, class Sched>
; __device__ __forceinline__ void gemm_phase(LAS unsigned char* lds, const Gemm g, const Sched& S, const Epi& E) {
;     ...
;             PG8_LDB(B1, 0, 1); PG8_STAGE(PG8_SB(0, 0), b2, voffB);
;             PG8_BAR; PG8_WAIT_L(0); PG8_MMA(0, 1, At, B1); PG8_BAR;
;             PG8_LDA(At, 0, 1); PG8_STAGE(PG8_SA(0, 0), a2, voffA);
;             PG8_BAR; PG8_WAIT_L(0); PG8_MMA(1, 0, At, B0); PG8_BAR; PG8_SCHED;
;             PG8_STAGE(PG8_SB(0, 1), b2 + hstep, voffB);
;             PG8_WAIT_V(6); PG8_BAR; PG8_MMA(1, 1, At, B1); PG8_BAR;
;             PG8_LDB(B0, 1, 0); PG8_SCHED; PG8_LDA(At, 1, 0); PG8_STAGE(PG8_SA(0, 1), a2 + hstep, voffA);
;             PG8_WAIT_L(8); PG8_BAR; PG8_WAIT_L(0); PG8_MMA(0, 0, At, B0); PG8_BAR; PG8_SCHED;
;             PG8_LDB(B1, 1, 1); PG8_STAGE(PG8_SB(1, 0), b3, voffB);
	s_add_i32 s48, 0, 0x14000
	s_add_i32 s45, s45, s29
	ds_read_b128 v[228:231], v129 offset:16384
	ds_read_b128 v[232:235], v129 offset:17408
	ds_read_b128 v[236:239], v129 offset:18432
	ds_read_b128 v[240:243], v129 offset:19456
	s_add_u32 s84, s20, 0x80
	s_addc_u32 s85, s21, 0
	s_mov_b32 m0, s45
	s_nop 0
	global_load_lds_dwordx4 v148, s[20:21]
	s_add_i32 m0, s45, 0x2000
	s_nop 0
	global_load_lds_dwordx4 v128, s[20:21]
	s_barrier
	s_waitcnt lgkmcnt(0)
	s_waitcnt lgkmcnt(0)
	v_mfma_f32_16x16x32_bf16 v[112:115], v[228:231], v[172:175], v[112:115]
	v_mfma_f32_16x16x32_bf16 v[104:107], v[236:239], v[172:175], v[104:107]
	v_mfma_f32_16x16x32_bf16 v[96:99], v[228:231], v[204:207], v[96:99]
	v_mfma_f32_16x16x32_bf16 v[88:91], v[236:239], v[204:207], v[88:91]
	v_mfma_f32_16x16x32_bf16 v[80:83], v[228:231], v[212:215], v[80:83]
	v_mfma_f32_16x16x32_bf16 v[72:75], v[236:239], v[212:215], v[72:75]
	v_mfma_f32_16x16x32_bf16 v[68:71], v[228:231], v[220:223], v[68:71]
	v_mfma_f32_16x16x32_bf16 v[64:67], v[236:239], v[220:223], v[64:67]
	v_mfma_f32_16x16x32_bf16 v[112:115], v[232:235], v[200:203], v[112:115]
	v_mfma_f32_16x16x32_bf16 v[104:107], v[240:243], v[200:203], v[104:107]
	v_mfma_f32_16x16x32_bf16 v[96:99], v[232:235], v[208:211], v[96:99]
	v_mfma_f32_16x16x32_bf16 v[88:91], v[240:243], v[208:211], v[88:91]
	v_mfma_f32_16x16x32_bf16 v[80:83], v[232:235], v[216:219], v[80:83]
	v_mfma_f32_16x16x32_bf16 v[72:75], v[240:243], v[216:219], v[72:75]
	v_mfma_f32_16x16x32_bf16 v[68:71], v[232:235], v[224:227], v[68:71]
	v_mfma_f32_16x16x32_bf16 v[64:67], v[240:243], v[224:227], v[64:67]
	s_mov_b32 m0, s30
	s_add_u32 s86, s22, 0x80
	s_addc_u32 s87, s23, 0
	s_barrier
	ds_read_b128 v[172:175], v145 offset:16384
	ds_read_b128 v[200:203], v145 offset:17408
	ds_read_b128 v[204:207], v145 offset:18432
	ds_read_b128 v[208:211], v145 offset:19456
	ds_read_b128 v[212:215], v145 offset:20480
	ds_read_b128 v[216:219], v145 offset:21504
	ds_read_b128 v[220:223], v145 offset:22528
	ds_read_b128 v[224:227], v145 offset:23552
	global_load_lds_dwordx4 v132, s[22:23]
	s_mov_b32 m0, s31
	s_nop 0
	global_load_lds_dwordx4 v130, s[22:23]
	s_barrier
	s_waitcnt lgkmcnt(0)
	s_waitcnt lgkmcnt(0)
	v_mfma_f32_16x16x32_bf16 v[60:63], v[138:141], v[172:175], v[60:63]
	v_mfma_f32_16x16x32_bf16 v[56:59], v[164:167], v[172:175], v[56:59]
	v_mfma_f32_16x16x32_bf16 v[52:55], v[138:141], v[204:207], v[52:55]
	v_mfma_f32_16x16x32_bf16 v[44:47], v[164:167], v[204:207], v[44:47]
	v_mfma_f32_16x16x32_bf16 v[36:39], v[138:141], v[212:215], v[36:39]
	v_mfma_f32_16x16x32_bf16 v[28:31], v[164:167], v[212:215], v[28:31]
	v_mfma_f32_16x16x32_bf16 v[20:23], v[138:141], v[220:223], v[20:23]
	v_mfma_f32_16x16x32_bf16 v[12:15], v[164:167], v[220:223], v[12:15]
	v_mfma_f32_16x16x32_bf16 v[60:63], v[160:163], v[200:203], v[60:63]
	v_mfma_f32_16x16x32_bf16 v[56:59], v[168:171], v[200:203], v[56:59]
	v_mfma_f32_16x16x32_bf16 v[52:55], v[160:163], v[208:211], v[52:55]
	v_mfma_f32_16x16x32_bf16 v[44:47], v[168:171], v[208:211], v[44:47]
	v_mfma_f32_16x16x32_bf16 v[36:39], v[160:163], v[216:219], v[36:39]
	v_mfma_f32_16x16x32_bf16 v[28:31], v[168:171], v[216:219], v[28:31]
	v_mfma_f32_16x16x32_bf16 v[20:23], v[160:163], v[224:227], v[20:23]
	v_mfma_f32_16x16x32_bf16 v[12:15], v[168:171], v[224:227], v[12:15]
	s_barrier
	s_add_u32 s46, s20, 0x80000
	s_addc_u32 s47, s21, 0
	s_add_i32 s45, s48, s29
	s_mov_b32 m0, s45
	s_nop 0
	global_load_lds_dwordx4 v148, s[46:47]
	s_add_i32 m0, s45, 0x2000
	s_nop 0
	global_load_lds_dwordx4 v128, s[46:47]
	s_waitcnt vmcnt(6)
	s_barrier
	v_mfma_f32_16x16x32_bf16 v[48:51], v[228:231], v[172:175], v[48:51]
	v_mfma_f32_16x16x32_bf16 v[40:43], v[236:239], v[172:175], v[40:43]
	v_mfma_f32_16x16x32_bf16 v[32:35], v[228:231], v[204:207], v[32:35]
	v_mfma_f32_16x16x32_bf16 v[24:27], v[236:239], v[204:207], v[24:27]
	v_mfma_f32_16x16x32_bf16 v[16:19], v[228:231], v[212:215], v[16:19]
	v_mfma_f32_16x16x32_bf16 v[8:11], v[236:239], v[212:215], v[8:11]
	v_mfma_f32_16x16x32_bf16 v[4:7], v[228:231], v[220:223], v[4:7]
	v_mfma_f32_16x16x32_bf16 v[0:3], v[236:239], v[220:223], v[0:3]
	v_mfma_f32_16x16x32_bf16 v[48:51], v[232:235], v[200:203], v[48:51]
	v_mfma_f32_16x16x32_bf16 v[40:43], v[240:243], v[200:203], v[40:43]
	v_mfma_f32_16x16x32_bf16 v[32:35], v[232:235], v[208:211], v[32:35]
	v_mfma_f32_16x16x32_bf16 v[24:27], v[240:243], v[208:211], v[24:27]
	v_mfma_f32_16x16x32_bf16 v[16:19], v[232:235], v[216:219], v[16:19]
	v_mfma_f32_16x16x32_bf16 v[8:11], v[240:243], v[216:219], v[8:11]
	v_mfma_f32_16x16x32_bf16 v[4:7], v[232:235], v[224:227], v[4:7]
	v_mfma_f32_16x16x32_bf16 v[0:3], v[240:243], v[224:227], v[0:3]
	s_add_i32 s45, 0, 0x18000
	s_barrier
	ds_read_b128 v[138:141], v129 offset:32768
	ds_read_b128 v[160:163], v129 offset:33792
	ds_read_b128 v[164:167], v129 offset:34816
	ds_read_b128 v[168:171], v129 offset:35840
	s_add_u32 s22, s22, 0x80000
	s_addc_u32 s23, s23, 0
	s_mov_b32 m0, s33
	ds_read_b128 v[172:175], v145 offset:32768
	ds_read_b128 v[200:203], v145 offset:33792
	ds_read_b128 v[204:207], v145 offset:34816
	ds_read_b128 v[208:211], v145 offset:35840
	ds_read_b128 v[212:215], v145 offset:36864
	ds_read_b128 v[216:219], v145 offset:37888
	ds_read_b128 v[220:223], v145 offset:38912
	ds_read_b128 v[224:227], v145 offset:39936
	global_load_lds_dwordx4 v132, s[22:23]
	s_mov_b32 m0, s34
	s_nop 0
	global_load_lds_dwordx4 v130, s[22:23]
	s_waitcnt lgkmcnt(8)
	s_barrier
; #define PG8_STAGE(bufoff, gbase, voff) do { _Pragma("unroll") for (int _i = 0; _i < 2; ++_i) \
;         __builtin_amdgcn_global_load_lds((const unsigned*)((const char*)(gbase) + (voff)[_i]), (LAS unsigned*)(lds + (bufoff) + ldsw + _i * 8192), 16, 0, 0); } while (0)
; #define PG8_LDA(dst, b, h) do { _Pragma("unroll") for (int m = 0; m < 4; ++m) _Pragma("unroll") for (int k = 0; k < 2; ++k) dst[m][k] = *(const LAS bf16x8*)(lds + PG8_SA(b, h) + aoff + m * 2048 + k * 1024); } while (0)
; #define PG8_LDB(dst, b, h) do { _Pragma("unroll") for (int n = 0; n < 2; ++n) _Pragma("unroll") for (int k = 0; k < 2; ++k) dst[n][k] = *(const LAS bf16x8*)(lds + PG8_SB(b, h) + boff + n * 2048 + k * 1024); } while (0)
; #define PG8_MMA(ai, bj, At, Bt) do { __builtin_amdgcn_s_setprio(1); _Pragma("unroll") for (int m = 0; m < 4; ++m) _Pragma("unroll") for (int n = 0; n < 2; ++n) _Pragma("unroll") for (int k = 0; k < 2; ++k) \
;         acc[ai][bj][m][n] = __builtin_amdgcn_mfma_f32_16x16x32_bf16(Bt[n][k], At[m][k], acc[ai][bj][m][n], 0, 0, 0); __builtin_amdgcn_s_setprio(0); } while (0)
; #define PG8_WAIT_V(n) asm volatile("s_waitcnt vmcnt(" #n ")" ::: "memory")
; #define PG8_WAIT_L(n) asm volatile("s_waitcnt lgkmcnt(" #n ")" ::: "memory")
; #define PG8_BAR __builtin_amdgcn_s_barrier()
; #define PG8_SCHED __builtin_amdgcn_sched_barrier(0)
; template <class Epi, class Sched>
; __device__ __forceinline__ void gemm_phase(LAS unsigned char* lds, const Gemm g, const Sched& S, const Epi& E) {
;     ...
;             PG8_LDB(B1, 1, 1); PG8_STAGE(PG8_SB(1, 0), b3, voffB);
;             PG8_BAR; PG8_WAIT_L(0); PG8_MMA(0, 1, At, B1); PG8_BAR;
;             PG8_LDA(At, 1, 1); PG8_STAGE(PG8_SA(1, 0), a3, voffA);
;             PG8_BAR; PG8_WAIT_L(0); PG8_MMA(1, 0, At, B0); PG8_BAR; PG8_SCHED;
;             PG8_STAGE(PG8_SB(1, 1), b3 + hstep, voffB);
;             PG8_WAIT_V(6); PG8_BAR; PG8_MMA(1, 1, At, B1); PG8_BAR;
	s_waitcnt lgkmcnt(0)
	s_waitcnt lgkmcnt(0)
	v_mfma_f32_16x16x32_bf16 v[124:127], v[138:141], v[172:175], v[124:127]
	v_mfma_f32_16x16x32_bf16 v[120:123], v[164:167], v[172:175], v[120:123]
	v_mfma_f32_16x16x32_bf16 v[116:119], v[138:141], v[204:207], v[116:119]
	v_mfma_f32_16x16x32_bf16 v[108:111], v[164:167], v[204:207], v[108:111]
	v_mfma_f32_16x16x32_bf16 v[100:103], v[138:141], v[212:215], v[100:103]
	v_mfma_f32_16x16x32_bf16 v[92:95], v[164:167], v[212:215], v[92:95]
	v_mfma_f32_16x16x32_bf16 v[84:87], v[138:141], v[220:223], v[84:87]
	v_mfma_f32_16x16x32_bf16 v[76:79], v[164:167], v[220:223], v[76:79]
	v_mfma_f32_16x16x32_bf16 v[124:127], v[160:163], v[200:203], v[124:127]
	v_mfma_f32_16x16x32_bf16 v[120:123], v[168:171], v[200:203], v[120:123]
	v_mfma_f32_16x16x32_bf16 v[116:119], v[160:163], v[208:211], v[116:119]
	v_mfma_f32_16x16x32_bf16 v[108:111], v[168:171], v[208:211], v[108:111]
	v_mfma_f32_16x16x32_bf16 v[100:103], v[160:163], v[216:219], v[100:103]
	v_mfma_f32_16x16x32_bf16 v[92:95], v[168:171], v[216:219], v[92:95]
	v_mfma_f32_16x16x32_bf16 v[84:87], v[160:163], v[224:227], v[84:87]
	v_mfma_f32_16x16x32_bf16 v[76:79], v[168:171], v[224:227], v[76:79]
	s_barrier
	s_add_i32 s22, 0, 0x1c000
	s_add_i32 s23, s45, s29
	s_mov_b32 m0, s23
	ds_read_b128 v[228:231], v129 offset:49152
	ds_read_b128 v[232:235], v129 offset:50176
	ds_read_b128 v[236:239], v129 offset:51200
	ds_read_b128 v[240:243], v129 offset:52224
	global_load_lds_dwordx4 v148, s[84:85]
	s_add_i32 m0, s23, 0x2000
	s_nop 0
	global_load_lds_dwordx4 v128, s[84:85]
	s_barrier
	s_waitcnt lgkmcnt(0)
	s_waitcnt lgkmcnt(0)
	v_mfma_f32_16x16x32_bf16 v[112:115], v[228:231], v[172:175], v[112:115]
	v_mfma_f32_16x16x32_bf16 v[104:107], v[236:239], v[172:175], v[104:107]
	v_mfma_f32_16x16x32_bf16 v[96:99], v[228:231], v[204:207], v[96:99]
	v_mfma_f32_16x16x32_bf16 v[88:91], v[236:239], v[204:207], v[88:91]
	v_mfma_f32_16x16x32_bf16 v[80:83], v[228:231], v[212:215], v[80:83]
	v_mfma_f32_16x16x32_bf16 v[72:75], v[236:239], v[212:215], v[72:75]
	v_mfma_f32_16x16x32_bf16 v[68:71], v[228:231], v[220:223], v[68:71]
	v_mfma_f32_16x16x32_bf16 v[64:67], v[236:239], v[220:223], v[64:67]
	v_mfma_f32_16x16x32_bf16 v[112:115], v[232:235], v[200:203], v[112:115]
	v_mfma_f32_16x16x32_bf16 v[104:107], v[240:243], v[200:203], v[104:107]
	v_mfma_f32_16x16x32_bf16 v[96:99], v[232:235], v[208:211], v[96:99]
	v_mfma_f32_16x16x32_bf16 v[88:91], v[240:243], v[208:211], v[88:91]
	v_mfma_f32_16x16x32_bf16 v[80:83], v[232:235], v[216:219], v[80:83]
	v_mfma_f32_16x16x32_bf16 v[72:75], v[240:243], v[216:219], v[72:75]
	v_mfma_f32_16x16x32_bf16 v[68:71], v[232:235], v[224:227], v[68:71]
	v_mfma_f32_16x16x32_bf16 v[64:67], v[240:243], v[224:227], v[64:67]
	s_mov_b32 m0, s35
	s_barrier
	ds_read_b128 v[172:175], v145 offset:49152
	ds_read_b128 v[200:203], v145 offset:50176
	ds_read_b128 v[204:207], v145 offset:51200
	ds_read_b128 v[208:211], v145 offset:52224
	ds_read_b128 v[212:215], v145 offset:53248
	ds_read_b128 v[216:219], v145 offset:54272
	ds_read_b128 v[220:223], v145 offset:55296
	ds_read_b128 v[224:227], v145 offset:56320
	global_load_lds_dwordx4 v132, s[86:87]
	s_mov_b32 m0, s36
	s_nop 0
	global_load_lds_dwordx4 v130, s[86:87]
	s_barrier
	s_waitcnt lgkmcnt(0)
	s_waitcnt lgkmcnt(0)
	v_mfma_f32_16x16x32_bf16 v[60:63], v[138:141], v[172:175], v[60:63]
	v_mfma_f32_16x16x32_bf16 v[56:59], v[164:167], v[172:175], v[56:59]
	v_mfma_f32_16x16x32_bf16 v[52:55], v[138:141], v[204:207], v[52:55]
	v_mfma_f32_16x16x32_bf16 v[44:47], v[164:167], v[204:207], v[44:47]
	v_mfma_f32_16x16x32_bf16 v[36:39], v[138:141], v[212:215], v[36:39]
	v_mfma_f32_16x16x32_bf16 v[28:31], v[164:167], v[212:215], v[28:31]
	v_mfma_f32_16x16x32_bf16 v[20:23], v[138:141], v[220:223], v[20:23]
	v_mfma_f32_16x16x32_bf16 v[12:15], v[164:167], v[220:223], v[12:15]
	v_mfma_f32_16x16x32_bf16 v[60:63], v[160:163], v[200:203], v[60:63]
	v_mfma_f32_16x16x32_bf16 v[56:59], v[168:171], v[200:203], v[56:59]
	v_mfma_f32_16x16x32_bf16 v[52:55], v[160:163], v[208:211], v[52:55]
	v_mfma_f32_16x16x32_bf16 v[44:47], v[168:171], v[208:211], v[44:47]
	v_mfma_f32_16x16x32_bf16 v[36:39], v[160:163], v[216:219], v[36:39]
	v_mfma_f32_16x16x32_bf16 v[28:31], v[168:171], v[216:219], v[28:31]
	v_mfma_f32_16x16x32_bf16 v[20:23], v[160:163], v[224:227], v[20:23]
	v_mfma_f32_16x16x32_bf16 v[12:15], v[168:171], v[224:227], v[12:15]
	s_barrier
	s_add_u32 s20, s20, 0x80080
	s_addc_u32 s21, s21, 0
	s_add_i32 s22, s22, s29
	s_mov_b32 m0, s22
	s_nop 0
	global_load_lds_dwordx4 v148, s[20:21]
	s_add_i32 m0, s22, 0x2000
	s_nop 0
	global_load_lds_dwordx4 v128, s[20:21]
	s_waitcnt vmcnt(6)
	s_barrier
; __device__ __forceinline__ unsigned cvt_pk_bf16(float lo, float hi) { unsigned r; asm("v_cvt_pk_bf16_f32 %0, %1, %2" : "=v"(r) : "v"(lo), "v"(hi)); return r; }
; #define PG8_MMA(ai, bj, At, Bt) do { __builtin_amdgcn_s_setprio(1); _Pragma("unroll") for (int m = 0; m < 4; ++m) _Pragma("unroll") for (int n = 0; n < 2; ++n) _Pragma("unroll") for (int k = 0; k < 2; ++k) \
;         acc[ai][bj][m][n] = __builtin_amdgcn_mfma_f32_16x16x32_bf16(Bt[n][k], At[m][k], acc[ai][bj][m][n], 0, 0, 0); __builtin_amdgcn_s_setprio(0); } while (0)
; #define PG8_WAIT_V(n) asm volatile("s_waitcnt vmcnt(" #n ")" ::: "memory")
; #define PG8_BAR __builtin_amdgcn_s_barrier()
;     __device__ __forceinline__ void operator()(const f32x4 (&acc)[2][2][4][2], const Unit& u, int wr, int wc, int fr, int fq) const {
;         const int row0 = u.pm * BM + wr * 64 + fr, col0 = u.pn * BM + wc * 32 + 8 * fq;
; #pragma unroll
;         for (int ai = 0; ai < 2; ++ai)
; #pragma unroll
;             for (int m = 0; m < 4; ++m) { bf16_t* rowp = O + (size_t)(row0 + ai * HALF + m * 16) * ldc + col0;
; #pragma unroll
;                 for (int bj = 0; bj < 2; ++bj) { const f32x4 v0 = acc[ai][bj][m][0], v1 = acc[ai][bj][m][1];
;                     u32x4 w; w.x = cvt_pk_bf16(v0[0], v0[1]); w.y = cvt_pk_bf16(v0[2], v0[3]); w.z = cvt_pk_bf16(v1[0], v1[1]); w.w = cvt_pk_bf16(v1[2], v1[3]);
;                     *(u32x4*)(rowp + bj * HALF) = w; } }
; template <class Epi, class Sched>
; __device__ __forceinline__ void gemm_phase(LAS unsigned char* lds, const Gemm g, const Sched& S, const Epi& E) {
;     ...
;             PG8_WAIT_V(6); PG8_BAR; PG8_MMA(1, 1, At, B1); PG8_BAR;
;         }
;         E(acc, cur, wr, wc, fr, fq);
;         if (!has_next) break;
	v_mfma_f32_16x16x32_bf16 v[48:51], v[228:231], v[172:175], v[48:51]
	v_mfma_f32_16x16x32_bf16 v[40:43], v[236:239], v[172:175], v[40:43]
	v_mfma_f32_16x16x32_bf16 v[32:35], v[228:231], v[204:207], v[32:35]
	v_mfma_f32_16x16x32_bf16 v[24:27], v[236:239], v[204:207], v[24:27]
	v_mfma_f32_16x16x32_bf16 v[16:19], v[228:231], v[212:215], v[16:19]
	v_mfma_f32_16x16x32_bf16 v[8:11], v[236:239], v[212:215], v[8:11]
	v_mfma_f32_16x16x32_bf16 v[4:7], v[228:231], v[220:223], v[4:7]
	v_mfma_f32_16x16x32_bf16 v[0:3], v[236:239], v[220:223], v[0:3]
	v_mfma_f32_16x16x32_bf16 v[48:51], v[232:235], v[200:203], v[48:51]
	v_mfma_f32_16x16x32_bf16 v[40:43], v[240:243], v[200:203], v[40:43]
	v_mfma_f32_16x16x32_bf16 v[32:35], v[232:235], v[208:211], v[32:35]
	v_mfma_f32_16x16x32_bf16 v[24:27], v[240:243], v[208:211], v[24:27]
	v_mfma_f32_16x16x32_bf16 v[16:19], v[232:235], v[216:219], v[16:19]
	v_mfma_f32_16x16x32_bf16 v[8:11], v[240:243], v[216:219], v[8:11]
	v_mfma_f32_16x16x32_bf16 v[4:7], v[232:235], v[224:227], v[4:7]
	v_mfma_f32_16x16x32_bf16 v[0:3], v[240:243], v[224:227], v[0:3]
	s_add_i32 s44, s44, 2
	s_add_u32 s16, s16, 0x100
	s_addc_u32 s17, s17, 0
	s_add_u32 s42, s42, 0x100
	s_addc_u32 s43, s43, 0
	s_cmp_gt_u32 s44, 29
	s_barrier
	s_cbranch_scc0 .LBB0_125
	v_lshl_add_u32 v160, s39, 8, v142
	v_lshl_or_b32 v140, s38, 8, v144
	v_ashrrev_i32_e32 v141, 31, v140
	v_mov_b64_e32 v[138:139], s[2:3]
	v_cvt_pk_bf16_f32 v68, v68, v69
	v_cvt_pk_bf16_f32 v69, v70, v71
	v_cvt_pk_bf16_f32 v70, v64, v65
	v_add_u32_e32 v64, 0x80, v160
	v_mad_i64_i32 v[146:147], s[16:17], v160, s56, v[138:139]
	v_lshlrev_b64 v[140:141], 1, v[140:141]
	v_cvt_pk_bf16_f32 v112, v112, v113
	v_cvt_pk_bf16_f32 v113, v114, v115
	v_cvt_pk_bf16_f32 v114, v104, v105
	v_or_b32_e32 v104, 16, v160
	v_mad_i64_i32 v[64:65], s[16:17], v64, s56, v[138:139]
	v_cvt_pk_bf16_f32 v48, v48, v49
	v_cvt_pk_bf16_f32 v49, v50, v51
	v_cvt_pk_bf16_f32 v50, v40, v41
	v_add_u32_e32 v40, 0x90, v160
	v_lshl_add_u64 v[146:147], v[146:147], 0, v[140:141]
	v_mad_i64_i32 v[104:105], s[16:17], v104, s56, v[138:139]
	v_cvt_pk_bf16_f32 v96, v96, v97
	v_cvt_pk_bf16_f32 v97, v98, v99
	v_cvt_pk_bf16_f32 v98, v88, v89
	v_or_b32_e32 v88, 32, v160
	v_lshl_add_u64 v[64:65], v[64:65], 0, v[140:141]
	v_mad_i64_i32 v[40:41], s[16:17], v40, s56, v[138:139]
	v_cvt_pk_bf16_f32 v32, v32, v33
	v_cvt_pk_bf16_f32 v33, v34, v35
	v_cvt_pk_bf16_f32 v34, v24, v25
	v_add_u32_e32 v24, 0xa0, v160
	v_cvt_pk_bf16_f32 v115, v106, v107
	global_store_dwordx4 v[146:147], v[112:115], off offset:256
	v_mad_i64_i32 v[88:89], s[16:17], v88, s56, v[138:139]
	s_nop 0
	v_lshl_add_u64 v[112:113], v[104:105], 0, v[140:141]
	v_cvt_pk_bf16_f32 v80, v80, v81
	v_cvt_pk_bf16_f32 v81, v82, v83
	v_cvt_pk_bf16_f32 v82, v72, v73
	v_or_b32_e32 v72, 48, v160
	v_cvt_pk_bf16_f32 v51, v42, v43
	global_store_dwordx4 v[64:65], v[48:51], off offset:256
	v_mad_i64_i32 v[24:25], s[16:17], v24, s56, v[138:139]
	s_nop 0
	v_lshl_add_u64 v[48:49], v[40:41], 0, v[140:141]
	v_cvt_pk_bf16_f32 v16, v16, v17
	v_cvt_pk_bf16_f32 v17, v18, v19
	v_cvt_pk_bf16_f32 v18, v8, v9
	v_add_u32_e32 v8, 0xb0, v160
	v_cvt_pk_bf16_f32 v99, v90, v91
	global_store_dwordx4 v[112:113], v[96:99], off offset:256
	v_mad_i64_i32 v[72:73], s[16:17], v72, s56, v[138:139]
	s_nop 0
	v_lshl_add_u64 v[96:97], v[88:89], 0, v[140:141]
	v_cvt_pk_bf16_f32 v35, v26, v27
	global_store_dwordx4 v[48:49], v[32:35], off offset:256
	v_mad_i64_i32 v[8:9], s[16:17], v8, s56, v[138:139]
	s_nop 0
	v_lshl_add_u64 v[32:33], v[24:25], 0, v[140:141]
	v_cvt_pk_bf16_f32 v83, v74, v75
	global_store_dwordx4 v[96:97], v[80:83], off offset:256
	v_cvt_pk_bf16_f32 v19, v10, v11
	global_store_dwordx4 v[32:33], v[16:19], off offset:256
	s_and_b64 vcc, exec, s[0:1]
	v_lshl_add_u64 v[80:81], v[72:73], 0, v[140:141]
	v_lshl_add_u64 v[16:17], v[8:9], 0, v[140:141]
	s_mov_b32 s38, s4
	s_mov_b32 s39, s6
	s_mov_b64 s[20:21], s[14:15]
	s_mov_b64 s[16:17], s[12:13]
	v_cvt_pk_bf16_f32 v124, v124, v125
	v_cvt_pk_bf16_f32 v125, v126, v127
	v_cvt_pk_bf16_f32 v126, v120, v121
	v_cvt_pk_bf16_f32 v127, v122, v123
	global_store_dwordx4 v[146:147], v[124:127], off
	v_cvt_pk_bf16_f32 v104, v116, v117
	v_cvt_pk_bf16_f32 v105, v118, v119
	v_cvt_pk_bf16_f32 v106, v108, v109
	v_cvt_pk_bf16_f32 v107, v110, v111
	global_store_dwordx4 v[112:113], v[104:107], off
	v_cvt_pk_bf16_f32 v88, v100, v101
	v_cvt_pk_bf16_f32 v89, v102, v103
	v_cvt_pk_bf16_f32 v90, v92, v93
	v_cvt_pk_bf16_f32 v91, v94, v95
	global_store_dwordx4 v[96:97], v[88:91], off
	v_cvt_pk_bf16_f32 v72, v84, v85
	v_cvt_pk_bf16_f32 v73, v86, v87
	v_cvt_pk_bf16_f32 v74, v76, v77
	v_cvt_pk_bf16_f32 v75, v78, v79
	global_store_dwordx4 v[80:81], v[72:75], off
	v_cvt_pk_bf16_f32 v71, v66, v67
	global_store_dwordx4 v[80:81], v[68:71], off offset:256
	v_cvt_pk_bf16_f32 v60, v60, v61
	v_cvt_pk_bf16_f32 v61, v62, v63
	v_cvt_pk_bf16_f32 v62, v56, v57
	v_cvt_pk_bf16_f32 v63, v58, v59
	global_store_dwordx4 v[64:65], v[60:63], off
	v_cvt_pk_bf16_f32 v40, v52, v53
	v_cvt_pk_bf16_f32 v41, v54, v55
	v_cvt_pk_bf16_f32 v42, v44, v45
	v_cvt_pk_bf16_f32 v43, v46, v47
	global_store_dwordx4 v[48:49], v[40:43], off
	v_cvt_pk_bf16_f32 v24, v36, v37
	v_cvt_pk_bf16_f32 v25, v38, v39
	v_cvt_pk_bf16_f32 v26, v28, v29
	v_cvt_pk_bf16_f32 v27, v30, v31
	global_store_dwordx4 v[32:33], v[24:27], off
	v_cvt_pk_bf16_f32 v8, v20, v21
	v_cvt_pk_bf16_f32 v9, v22, v23
	v_cvt_pk_bf16_f32 v10, v12, v13
	v_cvt_pk_bf16_f32 v11, v14, v15
	global_store_dwordx4 v[16:17], v[8:11], off
	v_cvt_pk_bf16_f32 v4, v4, v5
	v_cvt_pk_bf16_f32 v5, v6, v7
	v_cvt_pk_bf16_f32 v6, v0, v1
	v_cvt_pk_bf16_f32 v7, v2, v3
	global_store_dwordx4 v[16:17], v[4:7], off offset:256
	s_cbranch_vccz .LBB0_118
	s_waitcnt vmcnt(0)
	s_cmpk_gt_u32 s24, 0xff
	s_cbranch_scc1 .LBB0_129
	s_barrier

; #define PG8_STAGE(bufoff, gbase, voff) do { _Pragma("unroll") for (int _i = 0; _i < 2; ++_i) \
;         __builtin_amdgcn_global_load_lds((const unsigned*)((const char*)(gbase) + (voff)[_i]), (LAS unsigned*)(lds + (bufoff) + ldsw + _i * 8192), 16, 0, 0); } while (0)
; #define PG8_LDA(dst, b, h) do { _Pragma("unroll") for (int m = 0; m < 4; ++m) _Pragma("unroll") for (int k = 0; k < 2; ++k) dst[m][k] = *(const LAS bf16x8*)(lds + PG8_SA(b, h) + aoff + m * 2048 + k * 1024); } while (0)
; #define PG8_LDB(dst, b, h) do { _Pragma("unroll") for (int n = 0; n < 2; ++n) _Pragma("unroll") for (int k = 0; k < 2; ++k) dst[n][k] = *(const LAS bf16x8*)(lds + PG8_SB(b, h) + boff + n * 2048 + k * 1024); } while (0)
; #define PG8_MMA(ai, bj, At, Bt) do { __builtin_amdgcn_s_setprio(1); _Pragma("unroll") for (int m = 0; m < 4; ++m) _Pragma("unroll") for (int n = 0; n < 2; ++n) _Pragma("unroll") for (int k = 0; k < 2; ++k) \
;         acc[ai][bj][m][n] = __builtin_amdgcn_mfma_f32_16x16x32_bf16(Bt[n][k], At[m][k], acc[ai][bj][m][n], 0, 0, 0); __builtin_amdgcn_s_setprio(0); } while (0)
; #define PG8_WAIT_L(n) asm volatile("s_waitcnt lgkmcnt(" #n ")" ::: "memory")
; #define PG8_BAR __builtin_amdgcn_s_barrier()
; template <class Epi, class Sched>
; __device__ __forceinline__ void gemm_phase(LAS unsigned char* lds, const Gemm g, const Sched& S, const Epi& E) {
;     ...
;         const int nt = cur.nkt;
;         for (int t = 0; t < nt; t += 2) {
;             const bool last = (t == nt - 2);
;             const char* a1 = cA + (size_t)(t + 1) * kstep;
;             const char* a2 = last ? nA : cA + (size_t)(t + 2) * kstep; const char* b2 = last ? nB : cB + (size_t)(t + 2) * kstep;
;             const char* a3 = a2 + kstep; const char* b3 = b2 + kstep;
;             PG8_LDB(B0, 0, 0); PG8_SCHED; PG8_LDA(At, 0, 0); PG8_STAGE(PG8_SA(1, 1), a1 + hstep, voffA);
;             PG8_WAIT_L(8); PG8_BAR; PG8_WAIT_L(0); PG8_MMA(0, 0, At, B0); PG8_BAR; PG8_SCHED;
;             PG8_LDB(B1, 0, 1); PG8_STAGE(PG8_SB(0, 0), b2, voffB);
;             PG8_BAR; PG8_WAIT_L(0); PG8_MMA(0, 1, At, B1); PG8_BAR;
;     ...
;         for (int a = 0; a < 2; ++a)
; #pragma unroll
;             for (int b = 0; b < 2; ++b)
; #pragma unroll
;                 for (int m = 0; m < 4; ++m)
; #pragma unroll
;                     for (int n = 0; n < 2; ++n) acc[a][b][m][n] = (f32x4){0.f, 0.f, 0.f, 0.f};
.LBB0_169:
	s_add_i32 s15, s50, -2
	s_add_u32 s51, s20, 0x100
	v_mov_b32_e32 v0, 0
	s_addc_u32 s52, s21, 0
	s_mov_b32 s22, 0
	v_mov_b32_e32 v1, v0
	v_mov_b32_e32 v2, v0
	v_mov_b32_e32 v3, v0
	v_mov_b32_e32 v4, v0
	v_mov_b32_e32 v5, v0
	v_mov_b32_e32 v6, v0
	v_mov_b32_e32 v7, v0
	v_mov_b32_e32 v8, v0
	v_mov_b32_e32 v9, v0
	v_mov_b32_e32 v10, v0
	v_mov_b32_e32 v11, v0
	v_mov_b32_e32 v12, v0
	v_mov_b32_e32 v13, v0
	v_mov_b32_e32 v14, v0
	v_mov_b32_e32 v15, v0
	v_mov_b32_e32 v24, v0
	v_mov_b32_e32 v25, v0
	v_mov_b32_e32 v26, v0
	v_mov_b32_e32 v27, v0
	v_mov_b32_e32 v28, v0
	v_mov_b32_e32 v29, v0
	v_mov_b32_e32 v30, v0
	v_mov_b32_e32 v31, v0
	v_mov_b32_e32 v40, v0
	v_mov_b32_e32 v41, v0
	v_mov_b32_e32 v42, v0
	v_mov_b32_e32 v43, v0
	v_mov_b32_e32 v44, v0
	v_mov_b32_e32 v45, v0
	v_mov_b32_e32 v46, v0
	v_mov_b32_e32 v47, v0
	v_mov_b32_e32 v16, v0
	v_mov_b32_e32 v17, v0
	v_mov_b32_e32 v18, v0
	v_mov_b32_e32 v19, v0
	v_mov_b32_e32 v20, v0
	v_mov_b32_e32 v21, v0
	v_mov_b32_e32 v22, v0
	v_mov_b32_e32 v23, v0
	v_mov_b32_e32 v32, v0
	v_mov_b32_e32 v33, v0
	v_mov_b32_e32 v34, v0
	v_mov_b32_e32 v35, v0
	v_mov_b32_e32 v36, v0
	v_mov_b32_e32 v37, v0
	v_mov_b32_e32 v38, v0
	v_mov_b32_e32 v39, v0
	v_mov_b32_e32 v48, v0
	v_mov_b32_e32 v49, v0
	v_mov_b32_e32 v50, v0
	v_mov_b32_e32 v51, v0
	v_mov_b32_e32 v52, v0
	v_mov_b32_e32 v53, v0
	v_mov_b32_e32 v54, v0
	v_mov_b32_e32 v55, v0
	v_mov_b32_e32 v56, v0
	v_mov_b32_e32 v57, v0
	v_mov_b32_e32 v58, v0
	v_mov_b32_e32 v59, v0
	v_mov_b32_e32 v60, v0
	v_mov_b32_e32 v61, v0
	v_mov_b32_e32 v62, v0
	v_mov_b32_e32 v63, v0
	v_mov_b32_e32 v64, v0
	v_mov_b32_e32 v65, v0
	v_mov_b32_e32 v66, v0
	v_mov_b32_e32 v67, v0
	v_mov_b32_e32 v68, v0
	v_mov_b32_e32 v69, v0
	v_mov_b32_e32 v70, v0
	v_mov_b32_e32 v71, v0
	v_mov_b32_e32 v72, v0
	v_mov_b32_e32 v73, v0
	v_mov_b32_e32 v74, v0
	v_mov_b32_e32 v75, v0
	v_mov_b32_e32 v76, v0
	v_mov_b32_e32 v77, v0
	v_mov_b32_e32 v78, v0
	v_mov_b32_e32 v79, v0
	v_mov_b32_e32 v88, v0
	v_mov_b32_e32 v89, v0
	v_mov_b32_e32 v90, v0
	v_mov_b32_e32 v91, v0
	v_mov_b32_e32 v92, v0
	v_mov_b32_e32 v93, v0
	v_mov_b32_e32 v94, v0
	v_mov_b32_e32 v95, v0
	v_mov_b32_e32 v104, v0
	v_mov_b32_e32 v105, v0
	v_mov_b32_e32 v106, v0
	v_mov_b32_e32 v107, v0
	v_mov_b32_e32 v108, v0
	v_mov_b32_e32 v109, v0
	v_mov_b32_e32 v110, v0
	v_mov_b32_e32 v111, v0
	v_mov_b32_e32 v80, v0
	v_mov_b32_e32 v81, v0
	v_mov_b32_e32 v82, v0
	v_mov_b32_e32 v83, v0
	v_mov_b32_e32 v84, v0
	v_mov_b32_e32 v85, v0
	v_mov_b32_e32 v86, v0
	v_mov_b32_e32 v87, v0
	v_mov_b32_e32 v96, v0
	v_mov_b32_e32 v97, v0
	v_mov_b32_e32 v98, v0
	v_mov_b32_e32 v99, v0
	v_mov_b32_e32 v100, v0
	v_mov_b32_e32 v101, v0
	v_mov_b32_e32 v102, v0
	v_mov_b32_e32 v103, v0
	v_mov_b32_e32 v112, v0
	v_mov_b32_e32 v113, v0
	v_mov_b32_e32 v114, v0
	v_mov_b32_e32 v115, v0
	v_mov_b32_e32 v116, v0
	v_mov_b32_e32 v117, v0
	v_mov_b32_e32 v118, v0
	v_mov_b32_e32 v119, v0
	v_mov_b32_e32 v120, v0
	v_mov_b32_e32 v121, v0
	v_mov_b32_e32 v122, v0
	v_mov_b32_e32 v123, v0
	v_mov_b32_e32 v124, v0
	v_mov_b32_e32 v125, v0
	v_mov_b32_e32 v126, v0
	v_mov_b32_e32 v127, v0
	v_add_u32_e32 v141, 0x10000, v171
.LBB0_170:
	s_add_i32 s53, s22, 2
	s_add_u32 s20, s16, 0x100
	s_addc_u32 s21, s17, 0
	s_add_i32 s54, 0, 0x10000
	ds_read_b128 v[128:131], v141
	ds_read_b128 v[132:135], v141 offset:1024
	ds_read_b128 v[136:139], v141 offset:2048
	ds_read_b128 v[160:163], v141 offset:3072
	s_cmp_eq_u32 s15, s22
	s_cselect_b32 s22, s4, s51
	s_cselect_b32 s25, s7, s21
	s_cselect_b32 s24, s6, s20
	s_cselect_b32 s23, s5, s52
	s_add_i32 m0, s35, 0xc000
	ds_read_b128 v[164:167], v173
	ds_read_b128 v[174:177], v173 offset:1024
	ds_read_b128 v[200:203], v173 offset:2048
	ds_read_b128 v[204:207], v173 offset:3072
	ds_read_b128 v[208:211], v173 offset:4096
	ds_read_b128 v[212:215], v173 offset:5120
	ds_read_b128 v[216:219], v173 offset:6144
	ds_read_b128 v[220:223], v173 offset:7168
	global_load_lds_dwordx4 v142, s[16:17]
	s_add_i32 m0, s35, 0xe000
	s_nop 0
	global_load_lds_dwordx4 v144, s[16:17]
	s_waitcnt lgkmcnt(8)
	s_barrier
	s_waitcnt lgkmcnt(0)
	s_waitcnt lgkmcnt(0)
	v_mfma_f32_16x16x32_bf16 v[124:127], v[128:131], v[164:167], v[124:127]
	v_mfma_f32_16x16x32_bf16 v[120:123], v[136:139], v[164:167], v[120:123]
	v_mfma_f32_16x16x32_bf16 v[116:119], v[128:131], v[200:203], v[116:119]
	v_mfma_f32_16x16x32_bf16 v[112:115], v[136:139], v[200:203], v[112:115]
	v_mfma_f32_16x16x32_bf16 v[100:103], v[128:131], v[208:211], v[100:103]
	v_mfma_f32_16x16x32_bf16 v[96:99], v[136:139], v[208:211], v[96:99]
	v_mfma_f32_16x16x32_bf16 v[84:87], v[128:131], v[216:219], v[84:87]
	v_mfma_f32_16x16x32_bf16 v[80:83], v[136:139], v[216:219], v[80:83]
	v_mfma_f32_16x16x32_bf16 v[124:127], v[132:135], v[174:177], v[124:127]
	v_mfma_f32_16x16x32_bf16 v[120:123], v[160:163], v[174:177], v[120:123]
	v_mfma_f32_16x16x32_bf16 v[116:119], v[132:135], v[204:207], v[116:119]
	v_mfma_f32_16x16x32_bf16 v[112:115], v[160:163], v[204:207], v[112:115]
	v_mfma_f32_16x16x32_bf16 v[100:103], v[132:135], v[212:215], v[100:103]
	v_mfma_f32_16x16x32_bf16 v[96:99], v[160:163], v[212:215], v[96:99]
	v_mfma_f32_16x16x32_bf16 v[84:87], v[132:135], v[220:223], v[84:87]
	v_mfma_f32_16x16x32_bf16 v[80:83], v[160:163], v[220:223], v[80:83]
	s_barrier
	s_add_i32 s55, 0, 0x14000
	s_add_i32 s16, s54, s29
	ds_read_b128 v[224:227], v141 offset:16384
	ds_read_b128 v[228:231], v141 offset:17408
	ds_read_b128 v[232:235], v141 offset:18432
	ds_read_b128 v[236:239], v141 offset:19456
	s_add_u32 s84, s22, 0x80
	s_addc_u32 s85, s23, 0
	s_mov_b32 m0, s16
	s_nop 0
	global_load_lds_dwordx4 v148, s[22:23]
	s_add_i32 m0, s16, 0x2000
	s_nop 0
	global_load_lds_dwordx4 v140, s[22:23]
	s_barrier
; #define PG8_STAGE(bufoff, gbase, voff) do { _Pragma("unroll") for (int _i = 0; _i < 2; ++_i) \
;         __builtin_amdgcn_global_load_lds((const unsigned*)((const char*)(gbase) + (voff)[_i]), (LAS unsigned*)(lds + (bufoff) + ldsw + _i * 8192), 16, 0, 0); } while (0)
; #define PG8_LDA(dst, b, h) do { _Pragma("unroll") for (int m = 0; m < 4; ++m) _Pragma("unroll") for (int k = 0; k < 2; ++k) dst[m][k] = *(const LAS bf16x8*)(lds + PG8_SA(b, h) + aoff + m * 2048 + k * 1024); } while (0)
; #define PG8_LDB(dst, b, h) do { _Pragma("unroll") for (int n = 0; n < 2; ++n) _Pragma("unroll") for (int k = 0; k < 2; ++k) dst[n][k] = *(const LAS bf16x8*)(lds + PG8_SB(b, h) + boff + n * 2048 + k * 1024); } while (0)
; #define PG8_MMA(ai, bj, At, Bt) do { __builtin_amdgcn_s_setprio(1); _Pragma("unroll") for (int m = 0; m < 4; ++m) _Pragma("unroll") for (int n = 0; n < 2; ++n) _Pragma("unroll") for (int k = 0; k < 2; ++k) \
;         acc[ai][bj][m][n] = __builtin_amdgcn_mfma_f32_16x16x32_bf16(Bt[n][k], At[m][k], acc[ai][bj][m][n], 0, 0, 0); __builtin_amdgcn_s_setprio(0); } while (0)
; #define PG8_WAIT_V(n) asm volatile("s_waitcnt vmcnt(" #n ")" ::: "memory")
; #define PG8_WAIT_L(n) asm volatile("s_waitcnt lgkmcnt(" #n ")" ::: "memory")
; #define PG8_BAR __builtin_amdgcn_s_barrier()
; #define PG8_SCHED __builtin_amdgcn_sched_barrier(0)
; template <class Epi, class Sched>
; __device__ __forceinline__ void gemm_phase(LAS unsigned char* lds, const Gemm g, const Sched& S, const Epi& E) {
;     ...
;             PG8_BAR; PG8_WAIT_L(0); PG8_MMA(0, 1, At, B1); PG8_BAR;
;             PG8_LDA(At, 0, 1); PG8_STAGE(PG8_SA(0, 0), a2, voffA);
;             PG8_BAR; PG8_WAIT_L(0); PG8_MMA(1, 0, At, B0); PG8_BAR; PG8_SCHED;
;             PG8_STAGE(PG8_SB(0, 1), b2 + hstep, voffB);
;             PG8_WAIT_V(6); PG8_BAR; PG8_MMA(1, 1, At, B1); PG8_BAR;
;             PG8_LDB(B0, 1, 0); PG8_SCHED; PG8_LDA(At, 1, 0); PG8_STAGE(PG8_SA(0, 1), a2 + hstep, voffA);
;             PG8_WAIT_L(8); PG8_BAR; PG8_WAIT_L(0); PG8_MMA(0, 0, At, B0); PG8_BAR; PG8_SCHED;
;             PG8_LDB(B1, 1, 1); PG8_STAGE(PG8_SB(1, 0), b3, voffB);
;             PG8_BAR; PG8_WAIT_L(0); PG8_MMA(0, 1, At, B1); PG8_BAR;
;             PG8_LDA(At, 1, 1); PG8_STAGE(PG8_SA(1, 0), a3, voffA);
	s_waitcnt lgkmcnt(0)
	s_waitcnt lgkmcnt(0)
	v_mfma_f32_16x16x32_bf16 v[108:111], v[224:227], v[164:167], v[108:111]
	v_mfma_f32_16x16x32_bf16 v[104:107], v[232:235], v[164:167], v[104:107]
	v_mfma_f32_16x16x32_bf16 v[92:95], v[224:227], v[200:203], v[92:95]
	v_mfma_f32_16x16x32_bf16 v[88:91], v[232:235], v[200:203], v[88:91]
	v_mfma_f32_16x16x32_bf16 v[76:79], v[224:227], v[208:211], v[76:79]
	v_mfma_f32_16x16x32_bf16 v[72:75], v[232:235], v[208:211], v[72:75]
	v_mfma_f32_16x16x32_bf16 v[68:71], v[224:227], v[216:219], v[68:71]
	v_mfma_f32_16x16x32_bf16 v[64:67], v[232:235], v[216:219], v[64:67]
	v_mfma_f32_16x16x32_bf16 v[108:111], v[228:231], v[174:177], v[108:111]
	v_mfma_f32_16x16x32_bf16 v[104:107], v[236:239], v[174:177], v[104:107]
	v_mfma_f32_16x16x32_bf16 v[92:95], v[228:231], v[204:207], v[92:95]
	v_mfma_f32_16x16x32_bf16 v[88:91], v[236:239], v[204:207], v[88:91]
	v_mfma_f32_16x16x32_bf16 v[76:79], v[228:231], v[212:215], v[76:79]
	v_mfma_f32_16x16x32_bf16 v[72:75], v[236:239], v[212:215], v[72:75]
	v_mfma_f32_16x16x32_bf16 v[68:71], v[228:231], v[220:223], v[68:71]
	v_mfma_f32_16x16x32_bf16 v[64:67], v[236:239], v[220:223], v[64:67]
	s_mov_b32 m0, s35
	s_add_u32 s86, s24, 0x80
	s_addc_u32 s87, s25, 0
	s_barrier
	ds_read_b128 v[164:167], v173 offset:16384
	ds_read_b128 v[174:177], v173 offset:17408
	ds_read_b128 v[200:203], v173 offset:18432
	ds_read_b128 v[204:207], v173 offset:19456
	ds_read_b128 v[208:211], v173 offset:20480
	ds_read_b128 v[212:215], v173 offset:21504
	ds_read_b128 v[216:219], v173 offset:22528
	ds_read_b128 v[220:223], v173 offset:23552
	global_load_lds_dwordx4 v148, s[24:25]
	s_mov_b32 m0, s36
	s_nop 0
	global_load_lds_dwordx4 v140, s[24:25]
	s_barrier
	s_waitcnt lgkmcnt(0)
	s_waitcnt lgkmcnt(0)
	v_mfma_f32_16x16x32_bf16 v[60:63], v[128:131], v[164:167], v[60:63]
	v_mfma_f32_16x16x32_bf16 v[56:59], v[136:139], v[164:167], v[56:59]
	v_mfma_f32_16x16x32_bf16 v[52:55], v[128:131], v[200:203], v[52:55]
	v_mfma_f32_16x16x32_bf16 v[48:51], v[136:139], v[200:203], v[48:51]
	v_mfma_f32_16x16x32_bf16 v[36:39], v[128:131], v[208:211], v[36:39]
	v_mfma_f32_16x16x32_bf16 v[32:35], v[136:139], v[208:211], v[32:35]
	v_mfma_f32_16x16x32_bf16 v[20:23], v[128:131], v[216:219], v[20:23]
	v_mfma_f32_16x16x32_bf16 v[16:19], v[136:139], v[216:219], v[16:19]
	v_mfma_f32_16x16x32_bf16 v[60:63], v[132:135], v[174:177], v[60:63]
	v_mfma_f32_16x16x32_bf16 v[56:59], v[160:163], v[174:177], v[56:59]
	v_mfma_f32_16x16x32_bf16 v[52:55], v[132:135], v[204:207], v[52:55]
	v_mfma_f32_16x16x32_bf16 v[48:51], v[160:163], v[204:207], v[48:51]
	v_mfma_f32_16x16x32_bf16 v[36:39], v[132:135], v[212:215], v[36:39]
	v_mfma_f32_16x16x32_bf16 v[32:35], v[160:163], v[212:215], v[32:35]
	v_mfma_f32_16x16x32_bf16 v[20:23], v[132:135], v[220:223], v[20:23]
	v_mfma_f32_16x16x32_bf16 v[16:19], v[160:163], v[220:223], v[16:19]
	s_barrier
	s_add_u32 s16, s22, 0x160000
	s_addc_u32 s17, s23, 0
	s_add_i32 s54, s55, s29
	s_mov_b32 m0, s54
	s_nop 0
	global_load_lds_dwordx4 v148, s[16:17]
	s_add_i32 m0, s54, 0x2000
	s_nop 0
	global_load_lds_dwordx4 v140, s[16:17]
	s_waitcnt vmcnt(6)
	s_barrier
	v_mfma_f32_16x16x32_bf16 v[44:47], v[224:227], v[164:167], v[44:47]
	v_mfma_f32_16x16x32_bf16 v[40:43], v[232:235], v[164:167], v[40:43]
	v_mfma_f32_16x16x32_bf16 v[28:31], v[224:227], v[200:203], v[28:31]
	v_mfma_f32_16x16x32_bf16 v[24:27], v[232:235], v[200:203], v[24:27]
	v_mfma_f32_16x16x32_bf16 v[12:15], v[224:227], v[208:211], v[12:15]
	v_mfma_f32_16x16x32_bf16 v[8:11], v[232:235], v[208:211], v[8:11]
	v_mfma_f32_16x16x32_bf16 v[4:7], v[224:227], v[216:219], v[4:7]
	v_mfma_f32_16x16x32_bf16 v[0:3], v[232:235], v[216:219], v[0:3]
	v_mfma_f32_16x16x32_bf16 v[44:47], v[228:231], v[174:177], v[44:47]
	v_mfma_f32_16x16x32_bf16 v[40:43], v[236:239], v[174:177], v[40:43]
	v_mfma_f32_16x16x32_bf16 v[28:31], v[228:231], v[204:207], v[28:31]
	v_mfma_f32_16x16x32_bf16 v[24:27], v[236:239], v[204:207], v[24:27]
	v_mfma_f32_16x16x32_bf16 v[12:15], v[228:231], v[212:215], v[12:15]
	v_mfma_f32_16x16x32_bf16 v[8:11], v[236:239], v[212:215], v[8:11]
	v_mfma_f32_16x16x32_bf16 v[4:7], v[228:231], v[220:223], v[4:7]
	v_mfma_f32_16x16x32_bf16 v[0:3], v[236:239], v[220:223], v[0:3]
	s_add_i32 s54, 0, 0x18000
	s_barrier
	ds_read_b128 v[128:131], v141 offset:32768
	ds_read_b128 v[132:135], v141 offset:33792
	ds_read_b128 v[136:139], v141 offset:34816
	ds_read_b128 v[160:163], v141 offset:35840
	s_add_u32 s16, s24, 0x160000
	s_addc_u32 s17, s25, 0
	s_mov_b32 m0, s37
	ds_read_b128 v[164:167], v173 offset:32768
	ds_read_b128 v[174:177], v173 offset:33792
	ds_read_b128 v[200:203], v173 offset:34816
	ds_read_b128 v[204:207], v173 offset:35840
	ds_read_b128 v[208:211], v173 offset:36864
	ds_read_b128 v[212:215], v173 offset:37888
	ds_read_b128 v[216:219], v173 offset:38912
	ds_read_b128 v[220:223], v173 offset:39936
	global_load_lds_dwordx4 v148, s[16:17]
	s_mov_b32 m0, s38
	s_nop 0
	global_load_lds_dwordx4 v140, s[16:17]
	s_waitcnt lgkmcnt(8)
	s_barrier
	s_waitcnt lgkmcnt(0)
	s_waitcnt lgkmcnt(0)
	v_mfma_f32_16x16x32_bf16 v[124:127], v[128:131], v[164:167], v[124:127]
	v_mfma_f32_16x16x32_bf16 v[120:123], v[136:139], v[164:167], v[120:123]
	v_mfma_f32_16x16x32_bf16 v[116:119], v[128:131], v[200:203], v[116:119]
	v_mfma_f32_16x16x32_bf16 v[112:115], v[136:139], v[200:203], v[112:115]
	v_mfma_f32_16x16x32_bf16 v[100:103], v[128:131], v[208:211], v[100:103]
	v_mfma_f32_16x16x32_bf16 v[96:99], v[136:139], v[208:211], v[96:99]
	v_mfma_f32_16x16x32_bf16 v[84:87], v[128:131], v[216:219], v[84:87]
	v_mfma_f32_16x16x32_bf16 v[80:83], v[136:139], v[216:219], v[80:83]
	v_mfma_f32_16x16x32_bf16 v[124:127], v[132:135], v[174:177], v[124:127]
	v_mfma_f32_16x16x32_bf16 v[120:123], v[160:163], v[174:177], v[120:123]
	v_mfma_f32_16x16x32_bf16 v[116:119], v[132:135], v[204:207], v[116:119]
	v_mfma_f32_16x16x32_bf16 v[112:115], v[160:163], v[204:207], v[112:115]
	v_mfma_f32_16x16x32_bf16 v[100:103], v[132:135], v[212:215], v[100:103]
	v_mfma_f32_16x16x32_bf16 v[96:99], v[160:163], v[212:215], v[96:99]
	v_mfma_f32_16x16x32_bf16 v[84:87], v[132:135], v[220:223], v[84:87]
	v_mfma_f32_16x16x32_bf16 v[80:83], v[160:163], v[220:223], v[80:83]
	s_barrier
; #define PG8_STAGE(bufoff, gbase, voff) do { _Pragma("unroll") for (int _i = 0; _i < 2; ++_i) \
;         __builtin_amdgcn_global_load_lds((const unsigned*)((const char*)(gbase) + (voff)[_i]), (LAS unsigned*)(lds + (bufoff) + ldsw + _i * 8192), 16, 0, 0); } while (0)
; #define PG8_LDA(dst, b, h) do { _Pragma("unroll") for (int m = 0; m < 4; ++m) _Pragma("unroll") for (int k = 0; k < 2; ++k) dst[m][k] = *(const LAS bf16x8*)(lds + PG8_SA(b, h) + aoff + m * 2048 + k * 1024); } while (0)
; #define PG8_MMA(ai, bj, At, Bt) do { __builtin_amdgcn_s_setprio(1); _Pragma("unroll") for (int m = 0; m < 4; ++m) _Pragma("unroll") for (int n = 0; n < 2; ++n) _Pragma("unroll") for (int k = 0; k < 2; ++k) \
;         acc[ai][bj][m][n] = __builtin_amdgcn_mfma_f32_16x16x32_bf16(Bt[n][k], At[m][k], acc[ai][bj][m][n], 0, 0, 0); __builtin_amdgcn_s_setprio(0); } while (0)
; #define PG8_WAIT_V(n) asm volatile("s_waitcnt vmcnt(" #n ")" ::: "memory")
; #define PG8_WAIT_L(n) asm volatile("s_waitcnt lgkmcnt(" #n ")" ::: "memory")
; #define PG8_BAR __builtin_amdgcn_s_barrier()
; #define PG8_SCHED __builtin_amdgcn_sched_barrier(0)
; template <class Epi, class Sched>
; __device__ __forceinline__ void gemm_phase(LAS unsigned char* lds, const Gemm g, const Sched& S, const Epi& E) {
;     ...
;             PG8_LDA(At, 1, 1); PG8_STAGE(PG8_SA(1, 0), a3, voffA);
;             PG8_BAR; PG8_WAIT_L(0); PG8_MMA(1, 0, At, B0); PG8_BAR; PG8_SCHED;
;             PG8_STAGE(PG8_SB(1, 1), b3 + hstep, voffB);
;             PG8_WAIT_V(6); PG8_BAR; PG8_MMA(1, 1, At, B1); PG8_BAR;
;         }
;         E(acc, cur, wr, wc, fr, fq);
;         if (!has_next) break;
	s_add_i32 s24, 0, 0x1c000
	s_add_i32 s16, s54, s29
	s_mov_b32 m0, s16
	ds_read_b128 v[224:227], v141 offset:49152
	ds_read_b128 v[228:231], v141 offset:50176
	ds_read_b128 v[232:235], v141 offset:51200
	ds_read_b128 v[236:239], v141 offset:52224
	global_load_lds_dwordx4 v148, s[84:85]
	s_add_i32 m0, s16, 0x2000
	s_nop 0
	global_load_lds_dwordx4 v140, s[84:85]
	s_barrier
	s_waitcnt lgkmcnt(0)
	s_waitcnt lgkmcnt(0)
	v_mfma_f32_16x16x32_bf16 v[108:111], v[224:227], v[164:167], v[108:111]
	v_mfma_f32_16x16x32_bf16 v[104:107], v[232:235], v[164:167], v[104:107]
	v_mfma_f32_16x16x32_bf16 v[92:95], v[224:227], v[200:203], v[92:95]
	v_mfma_f32_16x16x32_bf16 v[88:91], v[232:235], v[200:203], v[88:91]
	v_mfma_f32_16x16x32_bf16 v[76:79], v[224:227], v[208:211], v[76:79]
	v_mfma_f32_16x16x32_bf16 v[72:75], v[232:235], v[208:211], v[72:75]
	v_mfma_f32_16x16x32_bf16 v[68:71], v[224:227], v[216:219], v[68:71]
	v_mfma_f32_16x16x32_bf16 v[64:67], v[232:235], v[216:219], v[64:67]
	v_mfma_f32_16x16x32_bf16 v[108:111], v[228:231], v[174:177], v[108:111]
	v_mfma_f32_16x16x32_bf16 v[104:107], v[236:239], v[174:177], v[104:107]
	v_mfma_f32_16x16x32_bf16 v[92:95], v[228:231], v[204:207], v[92:95]
	v_mfma_f32_16x16x32_bf16 v[88:91], v[236:239], v[204:207], v[88:91]
	v_mfma_f32_16x16x32_bf16 v[76:79], v[228:231], v[212:215], v[76:79]
	v_mfma_f32_16x16x32_bf16 v[72:75], v[236:239], v[212:215], v[72:75]
	v_mfma_f32_16x16x32_bf16 v[68:71], v[228:231], v[220:223], v[68:71]
	v_mfma_f32_16x16x32_bf16 v[64:67], v[236:239], v[220:223], v[64:67]
	s_mov_b32 m0, s41
	s_barrier
	ds_read_b128 v[164:167], v173 offset:49152
	ds_read_b128 v[174:177], v173 offset:50176
	ds_read_b128 v[200:203], v173 offset:51200
	ds_read_b128 v[204:207], v173 offset:52224
	ds_read_b128 v[208:211], v173 offset:53248
	ds_read_b128 v[212:215], v173 offset:54272
	ds_read_b128 v[216:219], v173 offset:55296
	ds_read_b128 v[220:223], v173 offset:56320
	global_load_lds_dwordx4 v148, s[86:87]
	s_mov_b32 m0, s42
	s_nop 0
	global_load_lds_dwordx4 v140, s[86:87]
	s_barrier
	s_waitcnt lgkmcnt(0)
	s_waitcnt lgkmcnt(0)
	v_mfma_f32_16x16x32_bf16 v[60:63], v[128:131], v[164:167], v[60:63]
	v_mfma_f32_16x16x32_bf16 v[56:59], v[136:139], v[164:167], v[56:59]
	v_mfma_f32_16x16x32_bf16 v[52:55], v[128:131], v[200:203], v[52:55]
	v_mfma_f32_16x16x32_bf16 v[48:51], v[136:139], v[200:203], v[48:51]
	v_mfma_f32_16x16x32_bf16 v[36:39], v[128:131], v[208:211], v[36:39]
	v_mfma_f32_16x16x32_bf16 v[32:35], v[136:139], v[208:211], v[32:35]
	v_mfma_f32_16x16x32_bf16 v[20:23], v[128:131], v[216:219], v[20:23]
	v_mfma_f32_16x16x32_bf16 v[16:19], v[136:139], v[216:219], v[16:19]
	v_mfma_f32_16x16x32_bf16 v[60:63], v[132:135], v[174:177], v[60:63]
	v_mfma_f32_16x16x32_bf16 v[56:59], v[160:163], v[174:177], v[56:59]
	v_mfma_f32_16x16x32_bf16 v[52:55], v[132:135], v[204:207], v[52:55]
	v_mfma_f32_16x16x32_bf16 v[48:51], v[160:163], v[204:207], v[48:51]
	v_mfma_f32_16x16x32_bf16 v[36:39], v[132:135], v[212:215], v[36:39]
	v_mfma_f32_16x16x32_bf16 v[32:35], v[160:163], v[212:215], v[32:35]
	v_mfma_f32_16x16x32_bf16 v[20:23], v[132:135], v[220:223], v[20:23]
	v_mfma_f32_16x16x32_bf16 v[16:19], v[160:163], v[220:223], v[16:19]
	s_barrier
	s_add_u32 s16, s22, 0x160080
	s_addc_u32 s17, s23, 0
	s_add_i32 s22, s24, s29
	s_mov_b32 m0, s22
	s_nop 0
	global_load_lds_dwordx4 v148, s[16:17]
	s_add_i32 m0, s22, 0x2000
	s_nop 0
	global_load_lds_dwordx4 v140, s[16:17]
	s_waitcnt vmcnt(6)
	s_barrier
	v_mfma_f32_16x16x32_bf16 v[44:47], v[224:227], v[164:167], v[44:47]
	v_mfma_f32_16x16x32_bf16 v[40:43], v[232:235], v[164:167], v[40:43]
	v_mfma_f32_16x16x32_bf16 v[28:31], v[224:227], v[200:203], v[28:31]
	v_mfma_f32_16x16x32_bf16 v[24:27], v[232:235], v[200:203], v[24:27]
	v_mfma_f32_16x16x32_bf16 v[12:15], v[224:227], v[208:211], v[12:15]
	v_mfma_f32_16x16x32_bf16 v[8:11], v[232:235], v[208:211], v[8:11]
	v_mfma_f32_16x16x32_bf16 v[4:7], v[224:227], v[216:219], v[4:7]
	v_mfma_f32_16x16x32_bf16 v[0:3], v[232:235], v[216:219], v[0:3]
	v_mfma_f32_16x16x32_bf16 v[44:47], v[228:231], v[174:177], v[44:47]
	v_mfma_f32_16x16x32_bf16 v[40:43], v[236:239], v[174:177], v[40:43]
	v_mfma_f32_16x16x32_bf16 v[28:31], v[228:231], v[204:207], v[28:31]
	v_mfma_f32_16x16x32_bf16 v[24:27], v[236:239], v[204:207], v[24:27]
	v_mfma_f32_16x16x32_bf16 v[12:15], v[228:231], v[212:215], v[12:15]
	v_mfma_f32_16x16x32_bf16 v[8:11], v[236:239], v[212:215], v[8:11]
	v_mfma_f32_16x16x32_bf16 v[4:7], v[228:231], v[220:223], v[4:7]
	v_mfma_f32_16x16x32_bf16 v[0:3], v[236:239], v[220:223], v[0:3]
	s_add_u32 s51, s51, 0x100
	s_addc_u32 s52, s52, 0
	s_cmp_ge_i32 s53, s50
	s_mov_b64 s[16:17], s[20:21]
	s_mov_b32 s22, s53
	s_barrier
	s_cbranch_scc0 .LBB0_170
	v_lshl_add_u32 v146, s48, 8, v170
	v_lshl_or_b32 v160, s49, 8, v172
	s_mov_b64 s[16:17], -1
	s_cmp_lt_i32 s82, 0
	v_ashrrev_i32_e32 v161, 31, v160
	v_ashrrev_i32_e32 v147, 31, v146
	s_cbranch_scc0 .LBB0_173
;     __device__ __forceinline__ void operator()(const f32x4 (&acc)[2][2][4][2], const Unit& u, int wr, int wc, int fr, int fq) const {
;     ...
;         const float* base = (u.pm < 32) ? base_lo : base_hi;
; #pragma unroll
;         for (int ai = 0; ai < 2; ++ai) {
;             f32x4 bs[4][2][2];
; #pragma unroll
;             for (int m = 0; m < 4; ++m) { const size_t off = (size_t)(row0 + ai * HALF + m * 16) * DM + col0;
; #pragma unroll
;                 for (int bj = 0; bj < 2; ++bj)
; #pragma unroll
;                     for (int n = 0; n < 2; ++n) bs[m][bj][n] = *(const f32x4*)(base + off + bj * HALF + n * 16); }
; #pragma unroll
;             for (int m = 0; m < 4; ++m) { const size_t off = (size_t)(row0 + ai * HALF + m * 16) * DM + col0;
; #pragma unroll
;                 for (int bj = 0; bj < 2; ++bj)
; #pragma unroll
;                     for (int n = 0; n < 2; ++n) *(f32x4*)(out + off + bj * HALF + n * 16) = bs[m][bj][n] + scale * acc[ai][bj][m][n]; }
	s_cmp_lt_i32 s48, 32
	s_cselect_b32 s17, s13, s61
	s_cselect_b32 s16, s12, s60
	v_lshlrev_b64 v[162:163], 2, v[160:161]
	v_lshl_add_u64 v[164:165], s[16:17], 0, v[162:163]
	v_lshlrev_b64 v[166:167], 13, v[146:147]
	v_lshl_add_u64 v[128:129], v[164:165], 0, v[166:167]
	global_load_dwordx4 v[174:177], v[128:129], off
	global_load_dwordx4 v[200:203], v[128:129], off offset:64
	global_load_dwordx4 v[204:207], v[128:129], off offset:512
	global_load_dwordx4 v[208:211], v[128:129], off offset:576
	v_or_b32_e32 v128, 16, v146
	v_ashrrev_i32_e32 v129, 31, v128
	v_lshlrev_b64 v[248:249], 13, v[128:129]
	v_lshl_add_u64 v[128:129], v[164:165], 0, v[248:249]
	global_load_dwordx4 v[212:215], v[128:129], off
	global_load_dwordx4 v[216:219], v[128:129], off offset:64
	global_load_dwordx4 v[220:223], v[128:129], off offset:512
	global_load_dwordx4 v[224:227], v[128:129], off offset:576
	v_or_b32_e32 v128, 32, v146
	v_ashrrev_i32_e32 v129, 31, v128
	v_lshlrev_b64 v[188:189], 13, v[128:129]
	v_lshl_add_u64 v[128:129], v[164:165], 0, v[188:189]
	global_load_dwordx4 v[228:231], v[128:129], off
	global_load_dwordx4 v[232:235], v[128:129], off offset:64
	global_load_dwordx4 v[236:239], v[128:129], off offset:512
	global_load_dwordx4 v[240:243], v[128:129], off offset:576
	v_or_b32_e32 v128, 48, v146
	v_ashrrev_i32_e32 v129, 31, v128
	v_lshlrev_b64 v[168:169], 13, v[128:129]
	v_lshl_add_u64 v[128:129], v[164:165], 0, v[168:169]
	global_load_dwordx4 v[244:247], v[128:129], off
	global_load_dwordx4 v[136:139], v[128:129], off offset:64
	global_load_dwordx4 v[132:135], v[128:129], off offset:512
	s_nop 0
	global_load_dwordx4 v[128:131], v[128:129], off offset:576
	v_lshl_add_u64 v[190:191], s[60:61], 0, v[166:167]
	v_lshl_add_u64 v[190:191], v[190:191], 0, v[162:163]
	v_lshl_add_u64 v[188:189], s[60:61], 0, v[188:189]
	v_lshl_add_u64 v[188:189], v[188:189], 0, v[162:163]
	v_lshl_add_u64 v[168:169], s[60:61], 0, v[168:169]
	v_lshl_add_u64 v[168:169], v[168:169], 0, v[162:163]
	s_mov_b64 s[16:17], 0x100000
	s_waitcnt vmcnt(0)
	v_pk_fma_f32 v[176:177], v[126:127], 0.5, v[176:177] op_sel_hi:[1,0,1]
	v_pk_fma_f32 v[174:175], v[124:125], 0.5, v[174:175] op_sel_hi:[1,0,1]
	global_store_dwordx4 v[190:191], v[174:177], off
	v_pk_fma_f32 v[138:139], v[82:83], 0.5, v[138:139] op_sel_hi:[1,0,1]
	s_nop 0
	v_pk_fma_f32 v[176:177], v[122:123], 0.5, v[202:203] op_sel_hi:[1,0,1]
	v_pk_fma_f32 v[174:175], v[120:121], 0.5, v[200:201] op_sel_hi:[1,0,1]
	global_store_dwordx4 v[190:191], v[174:177], off offset:64
	v_pk_fma_f32 v[136:137], v[80:81], 0.5, v[136:137] op_sel_hi:[1,0,1]
	v_pk_fma_f32 v[134:135], v[70:71], 0.5, v[134:135] op_sel_hi:[1,0,1]
	v_pk_fma_f32 v[176:177], v[110:111], 0.5, v[206:207] op_sel_hi:[1,0,1]
	v_pk_fma_f32 v[174:175], v[108:109], 0.5, v[204:205] op_sel_hi:[1,0,1]
	global_store_dwordx4 v[190:191], v[174:177], off offset:512
	v_pk_fma_f32 v[132:133], v[68:69], 0.5, v[132:133] op_sel_hi:[1,0,1]
	v_pk_fma_f32 v[130:131], v[66:67], 0.5, v[130:131] op_sel_hi:[1,0,1]
	v_pk_fma_f32 v[176:177], v[106:107], 0.5, v[210:211] op_sel_hi:[1,0,1]
	v_pk_fma_f32 v[174:175], v[104:105], 0.5, v[208:209] op_sel_hi:[1,0,1]
	global_store_dwordx4 v[190:191], v[174:177], off offset:576
	v_lshl_add_u64 v[190:191], s[60:61], 0, v[248:249]
	v_lshl_add_u64 v[190:191], v[190:191], 0, v[162:163]
	v_pk_fma_f32 v[176:177], v[118:119], 0.5, v[214:215] op_sel_hi:[1,0,1]
	v_pk_fma_f32 v[174:175], v[116:117], 0.5, v[212:213] op_sel_hi:[1,0,1]
	global_store_dwordx4 v[190:191], v[174:177], off
	v_pk_fma_f32 v[128:129], v[64:65], 0.5, v[128:129] op_sel_hi:[1,0,1]
	global_store_dwordx4 v[168:169], v[136:139], off offset:64
	v_pk_fma_f32 v[176:177], v[114:115], 0.5, v[218:219] op_sel_hi:[1,0,1]
	v_pk_fma_f32 v[174:175], v[112:113], 0.5, v[216:217] op_sel_hi:[1,0,1]
	global_store_dwordx4 v[190:191], v[174:177], off offset:64
	global_store_dwordx4 v[168:169], v[132:135], off offset:512
	global_store_dwordx4 v[168:169], v[128:131], off offset:576
	v_pk_fma_f32 v[176:177], v[94:95], 0.5, v[222:223] op_sel_hi:[1,0,1]
	v_pk_fma_f32 v[174:175], v[92:93], 0.5, v[220:221] op_sel_hi:[1,0,1]
	global_store_dwordx4 v[190:191], v[174:177], off offset:512
	s_nop 1
	v_pk_fma_f32 v[176:177], v[90:91], 0.5, v[226:227] op_sel_hi:[1,0,1]
	v_pk_fma_f32 v[174:175], v[88:89], 0.5, v[224:225] op_sel_hi:[1,0,1]
	global_store_dwordx4 v[190:191], v[174:177], off offset:576
	s_nop 1
	v_pk_fma_f32 v[176:177], v[102:103], 0.5, v[230:231] op_sel_hi:[1,0,1]
	v_pk_fma_f32 v[174:175], v[100:101], 0.5, v[228:229] op_sel_hi:[1,0,1]
	global_store_dwordx4 v[188:189], v[174:177], off
	s_nop 1
	v_pk_fma_f32 v[176:177], v[98:99], 0.5, v[234:235] op_sel_hi:[1,0,1]
	v_pk_fma_f32 v[174:175], v[96:97], 0.5, v[232:233] op_sel_hi:[1,0,1]
	global_store_dwordx4 v[188:189], v[174:177], off offset:64
	s_nop 1
	v_pk_fma_f32 v[176:177], v[78:79], 0.5, v[238:239] op_sel_hi:[1,0,1]
	v_pk_fma_f32 v[174:175], v[76:77], 0.5, v[236:237] op_sel_hi:[1,0,1]
	global_store_dwordx4 v[188:189], v[174:177], off offset:512
	s_nop 1
	v_pk_fma_f32 v[176:177], v[74:75], 0.5, v[242:243] op_sel_hi:[1,0,1]
	v_pk_fma_f32 v[174:175], v[72:73], 0.5, v[240:241] op_sel_hi:[1,0,1]
	global_store_dwordx4 v[188:189], v[174:177], off offset:576
	s_nop 1
	v_pk_fma_f32 v[176:177], v[86:87], 0.5, v[246:247] op_sel_hi:[1,0,1]
	v_pk_fma_f32 v[174:175], v[84:85], 0.5, v[244:245] op_sel_hi:[1,0,1]
	global_store_dwordx4 v[168:169], v[174:177], off
	v_lshl_add_u64 v[168:169], v[166:167], 0, s[16:17]
	v_lshl_add_u64 v[128:129], v[164:165], 0, v[168:169]
	global_load_dwordx4 v[174:177], v[128:129], off
	global_load_dwordx4 v[200:203], v[128:129], off offset:64
	global_load_dwordx4 v[204:207], v[128:129], off offset:512
	global_load_dwordx4 v[208:211], v[128:129], off offset:576
	s_mov_b64 s[16:17], 0x120000
	v_lshl_add_u64 v[188:189], v[166:167], 0, s[16:17]
	v_lshl_add_u64 v[128:129], v[164:165], 0, v[188:189]
	global_load_dwordx4 v[212:215], v[128:129], off
	global_load_dwordx4 v[216:219], v[128:129], off offset:64
	global_load_dwordx4 v[220:223], v[128:129], off offset:512
	global_load_dwordx4 v[224:227], v[128:129], off offset:576
	s_mov_b64 s[16:17], 0x140000
	v_lshl_add_u64 v[190:191], v[166:167], 0, s[16:17]
	v_lshl_add_u64 v[128:129], v[164:165], 0, v[190:191]
	s_mov_b64 s[16:17], 0x160000
	global_load_dwordx4 v[228:231], v[128:129], off
	global_load_dwordx4 v[232:235], v[128:129], off offset:64
	global_load_dwordx4 v[236:239], v[128:129], off offset:512
	global_load_dwordx4 v[240:243], v[128:129], off offset:576
	v_lshl_add_u64 v[166:167], v[166:167], 0, s[16:17]
	v_lshl_add_u64 v[128:129], v[164:165], 0, v[166:167]
	global_load_dwordx4 v[244:247], v[128:129], off
	global_load_dwordx4 v[136:139], v[128:129], off offset:64
	global_load_dwordx4 v[132:135], v[128:129], off offset:512
	s_nop 0
	global_load_dwordx4 v[128:131], v[128:129], off offset:576
	v_lshl_add_u64 v[164:165], s[60:61], 0, v[168:169]
	v_lshl_add_u64 v[164:165], v[164:165], 0, v[162:163]
	s_mov_b64 s[16:17], 0
	s_waitcnt vmcnt(0)
;     __device__ __forceinline__ void operator()(const f32x4 (&acc)[2][2][4][2], const Unit& u, int wr, int wc, int fr, int fq) const {
;     ...
;             for (int m = 0; m < 4; ++m) { const size_t off = (size_t)(row0 + ai * HALF + m * 16) * DM + col0;
; #pragma unroll
;                 for (int bj = 0; bj < 2; ++bj)
; #pragma unroll
;                     for (int n = 0; n < 2; ++n) *(f32x4*)(out + off + bj * HALF + n * 16) = bs[m][bj][n] + scale * acc[ai][bj][m][n]; }
	v_pk_fma_f32 v[176:177], v[62:63], 0.5, v[176:177] op_sel_hi:[1,0,1]
	v_pk_fma_f32 v[174:175], v[60:61], 0.5, v[174:175] op_sel_hi:[1,0,1]
	global_store_dwordx4 v[164:165], v[174:177], off
	v_pk_fma_f32 v[138:139], v[18:19], 0.5, v[138:139] op_sel_hi:[1,0,1]
	s_nop 0
	v_pk_fma_f32 v[176:177], v[58:59], 0.5, v[202:203] op_sel_hi:[1,0,1]
	v_pk_fma_f32 v[174:175], v[56:57], 0.5, v[200:201] op_sel_hi:[1,0,1]
	global_store_dwordx4 v[164:165], v[174:177], off offset:64
	v_pk_fma_f32 v[136:137], v[16:17], 0.5, v[136:137] op_sel_hi:[1,0,1]
	v_pk_fma_f32 v[134:135], v[6:7], 0.5, v[134:135] op_sel_hi:[1,0,1]
	v_pk_fma_f32 v[176:177], v[46:47], 0.5, v[206:207] op_sel_hi:[1,0,1]
	v_pk_fma_f32 v[174:175], v[44:45], 0.5, v[204:205] op_sel_hi:[1,0,1]
	global_store_dwordx4 v[164:165], v[174:177], off offset:512
	v_pk_fma_f32 v[132:133], v[4:5], 0.5, v[132:133] op_sel_hi:[1,0,1]
	v_pk_fma_f32 v[130:131], v[2:3], 0.5, v[130:131] op_sel_hi:[1,0,1]
	v_pk_fma_f32 v[176:177], v[42:43], 0.5, v[210:211] op_sel_hi:[1,0,1]
	v_pk_fma_f32 v[174:175], v[40:41], 0.5, v[208:209] op_sel_hi:[1,0,1]
	global_store_dwordx4 v[164:165], v[174:177], off offset:576
	v_lshl_add_u64 v[164:165], s[60:61], 0, v[188:189]
	v_lshl_add_u64 v[164:165], v[164:165], 0, v[162:163]
	v_pk_fma_f32 v[176:177], v[54:55], 0.5, v[214:215] op_sel_hi:[1,0,1]
	v_pk_fma_f32 v[174:175], v[52:53], 0.5, v[212:213] op_sel_hi:[1,0,1]
	global_store_dwordx4 v[164:165], v[174:177], off
	v_pk_fma_f32 v[128:129], v[0:1], 0.5, v[128:129] op_sel_hi:[1,0,1]
	s_nop 0
	v_pk_fma_f32 v[176:177], v[50:51], 0.5, v[218:219] op_sel_hi:[1,0,1]
	v_pk_fma_f32 v[174:175], v[48:49], 0.5, v[216:217] op_sel_hi:[1,0,1]
	global_store_dwordx4 v[164:165], v[174:177], off offset:64
	s_nop 1
	v_pk_fma_f32 v[176:177], v[30:31], 0.5, v[222:223] op_sel_hi:[1,0,1]
	v_pk_fma_f32 v[174:175], v[28:29], 0.5, v[220:221] op_sel_hi:[1,0,1]
	global_store_dwordx4 v[164:165], v[174:177], off offset:512
	s_nop 1
	v_pk_fma_f32 v[176:177], v[26:27], 0.5, v[226:227] op_sel_hi:[1,0,1]
	v_pk_fma_f32 v[174:175], v[24:25], 0.5, v[224:225] op_sel_hi:[1,0,1]
	global_store_dwordx4 v[164:165], v[174:177], off offset:576
	v_lshl_add_u64 v[164:165], s[60:61], 0, v[190:191]
	v_lshl_add_u64 v[164:165], v[164:165], 0, v[162:163]
	v_pk_fma_f32 v[176:177], v[38:39], 0.5, v[230:231] op_sel_hi:[1,0,1]
	v_pk_fma_f32 v[174:175], v[36:37], 0.5, v[228:229] op_sel_hi:[1,0,1]
	global_store_dwordx4 v[164:165], v[174:177], off
	s_nop 1
	v_pk_fma_f32 v[176:177], v[34:35], 0.5, v[234:235] op_sel_hi:[1,0,1]
	v_pk_fma_f32 v[174:175], v[32:33], 0.5, v[232:233] op_sel_hi:[1,0,1]
	global_store_dwordx4 v[164:165], v[174:177], off offset:64
	s_nop 1
	v_pk_fma_f32 v[176:177], v[14:15], 0.5, v[238:239] op_sel_hi:[1,0,1]
	v_pk_fma_f32 v[174:175], v[12:13], 0.5, v[236:237] op_sel_hi:[1,0,1]
	global_store_dwordx4 v[164:165], v[174:177], off offset:512
	s_nop 1
	v_pk_fma_f32 v[176:177], v[10:11], 0.5, v[242:243] op_sel_hi:[1,0,1]
	v_pk_fma_f32 v[174:175], v[8:9], 0.5, v[240:241] op_sel_hi:[1,0,1]
	global_store_dwordx4 v[164:165], v[174:177], off offset:576
	v_lshl_add_u64 v[164:165], s[60:61], 0, v[166:167]
	v_lshl_add_u64 v[162:163], v[164:165], 0, v[162:163]
	v_pk_fma_f32 v[176:177], v[22:23], 0.5, v[246:247] op_sel_hi:[1,0,1]
	v_pk_fma_f32 v[174:175], v[20:21], 0.5, v[244:245] op_sel_hi:[1,0,1]
	global_store_dwordx4 v[162:163], v[174:177], off
	global_store_dwordx4 v[162:163], v[136:139], off offset:64
	global_store_dwordx4 v[162:163], v[132:135], off offset:512
	global_store_dwordx4 v[162:163], v[128:131], off offset:576

; #define PG8_STAGE(bufoff, gbase, voff) do { _Pragma("unroll") for (int _i = 0; _i < 2; ++_i) \
;         __builtin_amdgcn_global_load_lds((const unsigned*)((const char*)(gbase) + (voff)[_i]), (LAS unsigned*)(lds + (bufoff) + ldsw + _i * 8192), 16, 0, 0); } while (0)
; #define PG8_LDA(dst, b, h) do { _Pragma("unroll") for (int m = 0; m < 4; ++m) _Pragma("unroll") for (int k = 0; k < 2; ++k) dst[m][k] = *(const LAS bf16x8*)(lds + PG8_SA(b, h) + aoff + m * 2048 + k * 1024); } while (0)
; #define PG8_LDB(dst, b, h) do { _Pragma("unroll") for (int n = 0; n < 2; ++n) _Pragma("unroll") for (int k = 0; k < 2; ++k) dst[n][k] = *(const LAS bf16x8*)(lds + PG8_SB(b, h) + boff + n * 2048 + k * 1024); } while (0)
; #define PG8_MMA(ai, bj, At, Bt) do { __builtin_amdgcn_s_setprio(1); _Pragma("unroll") for (int m = 0; m < 4; ++m) _Pragma("unroll") for (int n = 0; n < 2; ++n) _Pragma("unroll") for (int k = 0; k < 2; ++k) \
;         acc[ai][bj][m][n] = __builtin_amdgcn_mfma_f32_16x16x32_bf16(Bt[n][k], At[m][k], acc[ai][bj][m][n], 0, 0, 0); __builtin_amdgcn_s_setprio(0); } while (0)
; template <class Epi, class Sched>
; __device__ __forceinline__ void gemm_phase(LAS unsigned char* lds, const Gemm g, const Sched& S, const Epi& E) {
;     ...
;         const bool has_next = S.next(ui + 1, nxt);
;         const char* nA = has_next ? (const char*)g.A + (size_t)nxt.pm * tstep + (size_t)nxt.kt0 * kstep : cA; const char* nB = has_next ? (const char*)g.Bt + (size_t)nxt.pn * tstep + (size_t)nxt.kt0 * kstep : cB;
;         const int nt = cur.nkt;
;         for (int t = 0; t < nt; t += 2) {
;             const bool last = (t == nt - 2);
;             const char* a1 = cA + (size_t)(t + 1) * kstep;
;             const char* a2 = last ? nA : cA + (size_t)(t + 2) * kstep; const char* b2 = last ? nB : cB + (size_t)(t + 2) * kstep;
;             const char* a3 = a2 + kstep; const char* b3 = b2 + kstep;
;             PG8_LDB(B0, 0, 0); PG8_SCHED; PG8_LDA(At, 0, 0); PG8_STAGE(PG8_SA(1, 1), a1 + hstep, voffA);
;             PG8_WAIT_L(8); PG8_BAR; PG8_WAIT_L(0); PG8_MMA(0, 0, At, B0); PG8_BAR; PG8_SCHED;
;     ...
;         for (int a = 0; a < 2; ++a)
; #pragma unroll
;             for (int b = 0; b < 2; ++b)
; #pragma unroll
;                 for (int m = 0; m < 4; ++m)
; #pragma unroll
;                     for (int n = 0; n < 2; ++n) acc[a][b][m][n] = (f32x4){0.f, 0.f, 0.f, 0.f};
.LBB0_212:
	s_ashr_i32 s11, s10, 31
	v_cmp_lt_i64_e32 vcc, s[12:13], v[158:159]
	s_lshl_b64 s[12:13], s[10:11], 20
	v_readlane_b32 s7, v253, 15
	s_add_u32 s12, s7, s12
	v_readlane_b32 s7, v253, 16
	s_addc_u32 s13, s7, s13
	s_and_b64 s[14:15], vcc, exec
	s_cselect_b32 s11, s13, s17
	s_cselect_b32 s40, s12, s16
	s_ashr_i32 s7, s6, 31
	s_lshl_b64 s[14:15], s[6:7], 20
	s_add_u32 s14, s25, s14
	s_addc_u32 s15, s27, s15
	s_and_b64 s[22:23], vcc, exec
	s_cselect_b32 s7, s15, s21
	s_cselect_b32 s41, s14, s20
	s_add_u32 s16, s16, 0x80080
	s_addc_u32 s17, s17, 0
	s_add_u32 s42, s20, 0x100
	v_mov_b32_e32 v0, 0
	s_addc_u32 s43, s21, 0
	s_mov_b32 s44, -2
	v_mov_b32_e32 v1, v0
	v_mov_b32_e32 v2, v0
	v_mov_b32_e32 v3, v0
	v_mov_b32_e32 v8, v0
	v_mov_b32_e32 v9, v0
	v_mov_b32_e32 v10, v0
	v_mov_b32_e32 v11, v0
	v_mov_b32_e32 v16, v0
	v_mov_b32_e32 v17, v0
	v_mov_b32_e32 v18, v0
	v_mov_b32_e32 v19, v0
	v_mov_b32_e32 v24, v0
	v_mov_b32_e32 v25, v0
	v_mov_b32_e32 v26, v0
	v_mov_b32_e32 v27, v0
	v_mov_b32_e32 v32, v0
	v_mov_b32_e32 v33, v0
	v_mov_b32_e32 v34, v0
	v_mov_b32_e32 v35, v0
	v_mov_b32_e32 v40, v0
	v_mov_b32_e32 v41, v0
	v_mov_b32_e32 v42, v0
	v_mov_b32_e32 v43, v0
	v_mov_b32_e32 v48, v0
	v_mov_b32_e32 v49, v0
	v_mov_b32_e32 v50, v0
	v_mov_b32_e32 v51, v0
	v_mov_b32_e32 v56, v0
	v_mov_b32_e32 v57, v0
	v_mov_b32_e32 v58, v0
	v_mov_b32_e32 v59, v0
	v_mov_b32_e32 v4, v0
	v_mov_b32_e32 v5, v0
	v_mov_b32_e32 v6, v0
	v_mov_b32_e32 v7, v0
	v_mov_b32_e32 v12, v0
	v_mov_b32_e32 v13, v0
	v_mov_b32_e32 v14, v0
	v_mov_b32_e32 v15, v0
	v_mov_b32_e32 v20, v0
	v_mov_b32_e32 v21, v0
	v_mov_b32_e32 v22, v0
	v_mov_b32_e32 v23, v0
	v_mov_b32_e32 v28, v0
	v_mov_b32_e32 v29, v0
	v_mov_b32_e32 v30, v0
	v_mov_b32_e32 v31, v0
	v_mov_b32_e32 v36, v0
	v_mov_b32_e32 v37, v0
	v_mov_b32_e32 v38, v0
	v_mov_b32_e32 v39, v0
	v_mov_b32_e32 v44, v0
	v_mov_b32_e32 v45, v0
	v_mov_b32_e32 v46, v0
	v_mov_b32_e32 v47, v0
	v_mov_b32_e32 v52, v0
	v_mov_b32_e32 v53, v0
	v_mov_b32_e32 v54, v0
	v_mov_b32_e32 v55, v0
	v_mov_b32_e32 v60, v0
	v_mov_b32_e32 v61, v0
	v_mov_b32_e32 v62, v0
	v_mov_b32_e32 v63, v0
	v_mov_b32_e32 v64, v0
	v_mov_b32_e32 v65, v0
	v_mov_b32_e32 v66, v0
	v_mov_b32_e32 v67, v0
	v_mov_b32_e32 v72, v0
	v_mov_b32_e32 v73, v0
	v_mov_b32_e32 v74, v0
	v_mov_b32_e32 v75, v0
	v_mov_b32_e32 v80, v0
	v_mov_b32_e32 v81, v0
	v_mov_b32_e32 v82, v0
	v_mov_b32_e32 v83, v0
	v_mov_b32_e32 v88, v0
	v_mov_b32_e32 v89, v0
	v_mov_b32_e32 v90, v0
	v_mov_b32_e32 v91, v0
	v_mov_b32_e32 v96, v0
	v_mov_b32_e32 v97, v0
	v_mov_b32_e32 v98, v0
	v_mov_b32_e32 v99, v0
	v_mov_b32_e32 v104, v0
	v_mov_b32_e32 v105, v0
	v_mov_b32_e32 v106, v0
	v_mov_b32_e32 v107, v0
	v_mov_b32_e32 v112, v0
	v_mov_b32_e32 v113, v0
	v_mov_b32_e32 v114, v0
	v_mov_b32_e32 v115, v0
	v_mov_b32_e32 v120, v0
	v_mov_b32_e32 v121, v0
	v_mov_b32_e32 v122, v0
	v_mov_b32_e32 v123, v0
	v_mov_b32_e32 v68, v0
	v_mov_b32_e32 v69, v0
	v_mov_b32_e32 v70, v0
	v_mov_b32_e32 v71, v0
	v_mov_b32_e32 v76, v0
	v_mov_b32_e32 v77, v0
	v_mov_b32_e32 v78, v0
	v_mov_b32_e32 v79, v0
	v_mov_b32_e32 v84, v0
	v_mov_b32_e32 v85, v0
	v_mov_b32_e32 v86, v0
	v_mov_b32_e32 v87, v0
	v_mov_b32_e32 v92, v0
	v_mov_b32_e32 v93, v0
	v_mov_b32_e32 v94, v0
	v_mov_b32_e32 v95, v0
	v_mov_b32_e32 v100, v0
	v_mov_b32_e32 v101, v0
	v_mov_b32_e32 v102, v0
	v_mov_b32_e32 v103, v0
	v_mov_b32_e32 v108, v0
	v_mov_b32_e32 v109, v0
	v_mov_b32_e32 v110, v0
	v_mov_b32_e32 v111, v0
	v_mov_b32_e32 v116, v0
	v_mov_b32_e32 v117, v0
	v_mov_b32_e32 v118, v0
	v_mov_b32_e32 v119, v0
	v_mov_b32_e32 v124, v0
	v_mov_b32_e32 v125, v0
	v_mov_b32_e32 v126, v0
	v_mov_b32_e32 v127, v0
	v_add_u32_e32 v129, 0x10000, v141
.LBB0_213:
	s_add_u32 s20, s16, 0xfff80080
	s_addc_u32 s21, s17, -1
	s_add_i32 s45, 0, 0x10000
	ds_read_b128 v[144:147], v129
	ds_read_b128 v[160:163], v129 offset:1024
	ds_read_b128 v[164:167], v129 offset:2048
	ds_read_b128 v[168:171], v129 offset:3072
	s_cmp_eq_u32 s44, 28
	s_cselect_b32 s23, s11, s21
	s_cselect_b32 s22, s40, s20
	s_cselect_b32 s21, s7, s43
	s_cselect_b32 s20, s41, s42
	s_add_i32 m0, s30, 0xc000
	ds_read_b128 v[172:175], v143
	ds_read_b128 v[200:203], v143 offset:1024
	ds_read_b128 v[204:207], v143 offset:2048
	ds_read_b128 v[208:211], v143 offset:3072
	ds_read_b128 v[212:215], v143 offset:4096
	ds_read_b128 v[216:219], v143 offset:5120
	ds_read_b128 v[220:223], v143 offset:6144
	ds_read_b128 v[224:227], v143 offset:7168
	global_load_lds_dwordx4 v134, s[16:17]
	s_add_i32 m0, s30, 0xe000
	s_nop 0
	global_load_lds_dwordx4 v136, s[16:17]
	s_waitcnt lgkmcnt(8)
	s_barrier
	s_waitcnt lgkmcnt(0)
	s_waitcnt lgkmcnt(0)
	v_mfma_f32_16x16x32_bf16 v[124:127], v[144:147], v[172:175], v[124:127]
	v_mfma_f32_16x16x32_bf16 v[116:119], v[164:167], v[172:175], v[116:119]
	v_mfma_f32_16x16x32_bf16 v[108:111], v[144:147], v[204:207], v[108:111]
	v_mfma_f32_16x16x32_bf16 v[100:103], v[164:167], v[204:207], v[100:103]
	v_mfma_f32_16x16x32_bf16 v[92:95], v[144:147], v[212:215], v[92:95]
	v_mfma_f32_16x16x32_bf16 v[84:87], v[164:167], v[212:215], v[84:87]
	v_mfma_f32_16x16x32_bf16 v[76:79], v[144:147], v[220:223], v[76:79]
	v_mfma_f32_16x16x32_bf16 v[68:71], v[164:167], v[220:223], v[68:71]
	v_mfma_f32_16x16x32_bf16 v[124:127], v[160:163], v[200:203], v[124:127]
	v_mfma_f32_16x16x32_bf16 v[116:119], v[168:171], v[200:203], v[116:119]
	v_mfma_f32_16x16x32_bf16 v[108:111], v[160:163], v[208:211], v[108:111]
	v_mfma_f32_16x16x32_bf16 v[100:103], v[168:171], v[208:211], v[100:103]
	v_mfma_f32_16x16x32_bf16 v[92:95], v[160:163], v[216:219], v[92:95]
	v_mfma_f32_16x16x32_bf16 v[84:87], v[168:171], v[216:219], v[84:87]
	v_mfma_f32_16x16x32_bf16 v[76:79], v[160:163], v[224:227], v[76:79]
	v_mfma_f32_16x16x32_bf16 v[68:71], v[168:171], v[224:227], v[68:71]
	s_barrier
; #define PG8_STAGE(bufoff, gbase, voff) do { _Pragma("unroll") for (int _i = 0; _i < 2; ++_i) \
;         __builtin_amdgcn_global_load_lds((const unsigned*)((const char*)(gbase) + (voff)[_i]), (LAS unsigned*)(lds + (bufoff) + ldsw + _i * 8192), 16, 0, 0); } while (0)
; #define PG8_LDA(dst, b, h) do { _Pragma("unroll") for (int m = 0; m < 4; ++m) _Pragma("unroll") for (int k = 0; k < 2; ++k) dst[m][k] = *(const LAS bf16x8*)(lds + PG8_SA(b, h) + aoff + m * 2048 + k * 1024); } while (0)
; #define PG8_LDB(dst, b, h) do { _Pragma("unroll") for (int n = 0; n < 2; ++n) _Pragma("unroll") for (int k = 0; k < 2; ++k) dst[n][k] = *(const LAS bf16x8*)(lds + PG8_SB(b, h) + boff + n * 2048 + k * 1024); } while (0)
; #define PG8_MMA(ai, bj, At, Bt) do { __builtin_amdgcn_s_setprio(1); _Pragma("unroll") for (int m = 0; m < 4; ++m) _Pragma("unroll") for (int n = 0; n < 2; ++n) _Pragma("unroll") for (int k = 0; k < 2; ++k) \
;         acc[ai][bj][m][n] = __builtin_amdgcn_mfma_f32_16x16x32_bf16(Bt[n][k], At[m][k], acc[ai][bj][m][n], 0, 0, 0); __builtin_amdgcn_s_setprio(0); } while (0)
; #define PG8_WAIT_V(n) asm volatile("s_waitcnt vmcnt(" #n ")" ::: "memory")
; #define PG8_WAIT_L(n) asm volatile("s_waitcnt lgkmcnt(" #n ")" ::: "memory")
; #define PG8_BAR __builtin_amdgcn_s_barrier()
; #define PG8_SCHED __builtin_amdgcn_sched_barrier(0)
; template <class Epi, class Sched>
; __device__ __forceinline__ void gemm_phase(LAS unsigned char* lds, const Gemm g, const Sched& S, const Epi& E) {
;     ...
;             PG8_LDB(B1, 0, 1); PG8_STAGE(PG8_SB(0, 0), b2, voffB);
;             PG8_BAR; PG8_WAIT_L(0); PG8_MMA(0, 1, At, B1); PG8_BAR;
;             PG8_LDA(At, 0, 1); PG8_STAGE(PG8_SA(0, 0), a2, voffA);
;             PG8_BAR; PG8_WAIT_L(0); PG8_MMA(1, 0, At, B0); PG8_BAR; PG8_SCHED;
;             PG8_STAGE(PG8_SB(0, 1), b2 + hstep, voffB);
;             PG8_WAIT_V(6); PG8_BAR; PG8_MMA(1, 1, At, B1); PG8_BAR;
;             PG8_LDB(B0, 1, 0); PG8_SCHED; PG8_LDA(At, 1, 0); PG8_STAGE(PG8_SA(0, 1), a2 + hstep, voffA);
;             PG8_WAIT_L(8); PG8_BAR; PG8_WAIT_L(0); PG8_MMA(0, 0, At, B0); PG8_BAR; PG8_SCHED;
;             PG8_LDB(B1, 1, 1); PG8_STAGE(PG8_SB(1, 0), b3, voffB);
	s_add_i32 s48, 0, 0x14000
	s_add_i32 s45, s45, s29
	ds_read_b128 v[228:231], v129 offset:16384
	ds_read_b128 v[232:235], v129 offset:17408
	ds_read_b128 v[236:239], v129 offset:18432
	ds_read_b128 v[240:243], v129 offset:19456
	s_add_u32 s84, s20, 0x80
	s_addc_u32 s85, s21, 0
	s_mov_b32 m0, s45
	s_nop 0
	global_load_lds_dwordx4 v148, s[20:21]
	s_add_i32 m0, s45, 0x2000
	s_nop 0
	global_load_lds_dwordx4 v128, s[20:21]
	s_barrier
	s_waitcnt lgkmcnt(0)
	s_waitcnt lgkmcnt(0)
	v_mfma_f32_16x16x32_bf16 v[120:123], v[228:231], v[172:175], v[120:123]
	v_mfma_f32_16x16x32_bf16 v[112:115], v[236:239], v[172:175], v[112:115]
	v_mfma_f32_16x16x32_bf16 v[104:107], v[228:231], v[204:207], v[104:107]
	v_mfma_f32_16x16x32_bf16 v[96:99], v[236:239], v[204:207], v[96:99]
	v_mfma_f32_16x16x32_bf16 v[88:91], v[228:231], v[212:215], v[88:91]
	v_mfma_f32_16x16x32_bf16 v[80:83], v[236:239], v[212:215], v[80:83]
	v_mfma_f32_16x16x32_bf16 v[72:75], v[228:231], v[220:223], v[72:75]
	v_mfma_f32_16x16x32_bf16 v[64:67], v[236:239], v[220:223], v[64:67]
	v_mfma_f32_16x16x32_bf16 v[120:123], v[232:235], v[200:203], v[120:123]
	v_mfma_f32_16x16x32_bf16 v[112:115], v[240:243], v[200:203], v[112:115]
	v_mfma_f32_16x16x32_bf16 v[104:107], v[232:235], v[208:211], v[104:107]
	v_mfma_f32_16x16x32_bf16 v[96:99], v[240:243], v[208:211], v[96:99]
	v_mfma_f32_16x16x32_bf16 v[88:91], v[232:235], v[216:219], v[88:91]
	v_mfma_f32_16x16x32_bf16 v[80:83], v[240:243], v[216:219], v[80:83]
	v_mfma_f32_16x16x32_bf16 v[72:75], v[232:235], v[224:227], v[72:75]
	v_mfma_f32_16x16x32_bf16 v[64:67], v[240:243], v[224:227], v[64:67]
	s_mov_b32 m0, s30
	s_add_u32 s86, s22, 0x80
	s_addc_u32 s87, s23, 0
	s_barrier
	ds_read_b128 v[172:175], v143 offset:16384
	ds_read_b128 v[200:203], v143 offset:17408
	ds_read_b128 v[204:207], v143 offset:18432
	ds_read_b128 v[208:211], v143 offset:19456
	ds_read_b128 v[212:215], v143 offset:20480
	ds_read_b128 v[216:219], v143 offset:21504
	ds_read_b128 v[220:223], v143 offset:22528
	ds_read_b128 v[224:227], v143 offset:23552
	global_load_lds_dwordx4 v132, s[22:23]
	s_mov_b32 m0, s31
	s_nop 0
	global_load_lds_dwordx4 v130, s[22:23]
	s_barrier
	s_waitcnt lgkmcnt(0)
	s_waitcnt lgkmcnt(0)
	v_mfma_f32_16x16x32_bf16 v[60:63], v[144:147], v[172:175], v[60:63]
	v_mfma_f32_16x16x32_bf16 v[52:55], v[164:167], v[172:175], v[52:55]
	v_mfma_f32_16x16x32_bf16 v[44:47], v[144:147], v[204:207], v[44:47]
	v_mfma_f32_16x16x32_bf16 v[36:39], v[164:167], v[204:207], v[36:39]
	v_mfma_f32_16x16x32_bf16 v[28:31], v[144:147], v[212:215], v[28:31]
	v_mfma_f32_16x16x32_bf16 v[20:23], v[164:167], v[212:215], v[20:23]
	v_mfma_f32_16x16x32_bf16 v[12:15], v[144:147], v[220:223], v[12:15]
	v_mfma_f32_16x16x32_bf16 v[4:7], v[164:167], v[220:223], v[4:7]
	v_mfma_f32_16x16x32_bf16 v[60:63], v[160:163], v[200:203], v[60:63]
	v_mfma_f32_16x16x32_bf16 v[52:55], v[168:171], v[200:203], v[52:55]
	v_mfma_f32_16x16x32_bf16 v[44:47], v[160:163], v[208:211], v[44:47]
	v_mfma_f32_16x16x32_bf16 v[36:39], v[168:171], v[208:211], v[36:39]
	v_mfma_f32_16x16x32_bf16 v[28:31], v[160:163], v[216:219], v[28:31]
	v_mfma_f32_16x16x32_bf16 v[20:23], v[168:171], v[216:219], v[20:23]
	v_mfma_f32_16x16x32_bf16 v[12:15], v[160:163], v[224:227], v[12:15]
	v_mfma_f32_16x16x32_bf16 v[4:7], v[168:171], v[224:227], v[4:7]
	s_barrier
	s_add_u32 s46, s20, 0x80000
	s_addc_u32 s47, s21, 0
	s_add_i32 s45, s48, s29
	s_mov_b32 m0, s45
	s_nop 0
	global_load_lds_dwordx4 v148, s[46:47]
	s_add_i32 m0, s45, 0x2000
	s_nop 0
	global_load_lds_dwordx4 v128, s[46:47]
	s_waitcnt vmcnt(6)
	s_barrier
	v_mfma_f32_16x16x32_bf16 v[56:59], v[228:231], v[172:175], v[56:59]
	v_mfma_f32_16x16x32_bf16 v[48:51], v[236:239], v[172:175], v[48:51]
	v_mfma_f32_16x16x32_bf16 v[40:43], v[228:231], v[204:207], v[40:43]
	v_mfma_f32_16x16x32_bf16 v[32:35], v[236:239], v[204:207], v[32:35]
	v_mfma_f32_16x16x32_bf16 v[24:27], v[228:231], v[212:215], v[24:27]
	v_mfma_f32_16x16x32_bf16 v[16:19], v[236:239], v[212:215], v[16:19]
	v_mfma_f32_16x16x32_bf16 v[8:11], v[228:231], v[220:223], v[8:11]
	v_mfma_f32_16x16x32_bf16 v[0:3], v[236:239], v[220:223], v[0:3]
	v_mfma_f32_16x16x32_bf16 v[56:59], v[232:235], v[200:203], v[56:59]
	v_mfma_f32_16x16x32_bf16 v[48:51], v[240:243], v[200:203], v[48:51]
	v_mfma_f32_16x16x32_bf16 v[40:43], v[232:235], v[208:211], v[40:43]
	v_mfma_f32_16x16x32_bf16 v[32:35], v[240:243], v[208:211], v[32:35]
	v_mfma_f32_16x16x32_bf16 v[24:27], v[232:235], v[216:219], v[24:27]
	v_mfma_f32_16x16x32_bf16 v[16:19], v[240:243], v[216:219], v[16:19]
	v_mfma_f32_16x16x32_bf16 v[8:11], v[232:235], v[224:227], v[8:11]
	v_mfma_f32_16x16x32_bf16 v[0:3], v[240:243], v[224:227], v[0:3]
	s_add_i32 s45, 0, 0x18000
	s_barrier
	ds_read_b128 v[144:147], v129 offset:32768
	ds_read_b128 v[160:163], v129 offset:33792
	ds_read_b128 v[164:167], v129 offset:34816
	ds_read_b128 v[168:171], v129 offset:35840
	s_add_u32 s22, s22, 0x80000
	s_addc_u32 s23, s23, 0
	s_mov_b32 m0, s33
	ds_read_b128 v[172:175], v143 offset:32768
	ds_read_b128 v[200:203], v143 offset:33792
	ds_read_b128 v[204:207], v143 offset:34816
	ds_read_b128 v[208:211], v143 offset:35840
	ds_read_b128 v[212:215], v143 offset:36864
	ds_read_b128 v[216:219], v143 offset:37888
	ds_read_b128 v[220:223], v143 offset:38912
	ds_read_b128 v[224:227], v143 offset:39936
	global_load_lds_dwordx4 v132, s[22:23]
	s_mov_b32 m0, s34
	s_nop 0
	global_load_lds_dwordx4 v130, s[22:23]
	s_waitcnt lgkmcnt(8)
	s_barrier
; #define PG8_STAGE(bufoff, gbase, voff) do { _Pragma("unroll") for (int _i = 0; _i < 2; ++_i) \
;         __builtin_amdgcn_global_load_lds((const unsigned*)((const char*)(gbase) + (voff)[_i]), (LAS unsigned*)(lds + (bufoff) + ldsw + _i * 8192), 16, 0, 0); } while (0)
; #define PG8_LDA(dst, b, h) do { _Pragma("unroll") for (int m = 0; m < 4; ++m) _Pragma("unroll") for (int k = 0; k < 2; ++k) dst[m][k] = *(const LAS bf16x8*)(lds + PG8_SA(b, h) + aoff + m * 2048 + k * 1024); } while (0)
; #define PG8_LDB(dst, b, h) do { _Pragma("unroll") for (int n = 0; n < 2; ++n) _Pragma("unroll") for (int k = 0; k < 2; ++k) dst[n][k] = *(const LAS bf16x8*)(lds + PG8_SB(b, h) + boff + n * 2048 + k * 1024); } while (0)
; #define PG8_MMA(ai, bj, At, Bt) do { __builtin_amdgcn_s_setprio(1); _Pragma("unroll") for (int m = 0; m < 4; ++m) _Pragma("unroll") for (int n = 0; n < 2; ++n) _Pragma("unroll") for (int k = 0; k < 2; ++k) \
;         acc[ai][bj][m][n] = __builtin_amdgcn_mfma_f32_16x16x32_bf16(Bt[n][k], At[m][k], acc[ai][bj][m][n], 0, 0, 0); __builtin_amdgcn_s_setprio(0); } while (0)
; #define PG8_WAIT_V(n) asm volatile("s_waitcnt vmcnt(" #n ")" ::: "memory")
; #define PG8_WAIT_L(n) asm volatile("s_waitcnt lgkmcnt(" #n ")" ::: "memory")
; #define PG8_BAR __builtin_amdgcn_s_barrier()
; #define PG8_SCHED __builtin_amdgcn_sched_barrier(0)
; template <class Epi, class Sched>
; __device__ __forceinline__ void gemm_phase(LAS unsigned char* lds, const Gemm g, const Sched& S, const Epi& E) {
;     ...
;             PG8_LDB(B1, 1, 1); PG8_STAGE(PG8_SB(1, 0), b3, voffB);
;             PG8_BAR; PG8_WAIT_L(0); PG8_MMA(0, 1, At, B1); PG8_BAR;
;             PG8_LDA(At, 1, 1); PG8_STAGE(PG8_SA(1, 0), a3, voffA);
;             PG8_BAR; PG8_WAIT_L(0); PG8_MMA(1, 0, At, B0); PG8_BAR; PG8_SCHED;
;             PG8_STAGE(PG8_SB(1, 1), b3 + hstep, voffB);
;             PG8_WAIT_V(6); PG8_BAR; PG8_MMA(1, 1, At, B1); PG8_BAR;
;         }
	s_waitcnt lgkmcnt(0)
	s_waitcnt lgkmcnt(0)
	v_mfma_f32_16x16x32_bf16 v[124:127], v[144:147], v[172:175], v[124:127]
	v_mfma_f32_16x16x32_bf16 v[116:119], v[164:167], v[172:175], v[116:119]
	v_mfma_f32_16x16x32_bf16 v[108:111], v[144:147], v[204:207], v[108:111]
	v_mfma_f32_16x16x32_bf16 v[100:103], v[164:167], v[204:207], v[100:103]
	v_mfma_f32_16x16x32_bf16 v[92:95], v[144:147], v[212:215], v[92:95]
	v_mfma_f32_16x16x32_bf16 v[84:87], v[164:167], v[212:215], v[84:87]
	v_mfma_f32_16x16x32_bf16 v[76:79], v[144:147], v[220:223], v[76:79]
	v_mfma_f32_16x16x32_bf16 v[68:71], v[164:167], v[220:223], v[68:71]
	v_mfma_f32_16x16x32_bf16 v[124:127], v[160:163], v[200:203], v[124:127]
	v_mfma_f32_16x16x32_bf16 v[116:119], v[168:171], v[200:203], v[116:119]
	v_mfma_f32_16x16x32_bf16 v[108:111], v[160:163], v[208:211], v[108:111]
	v_mfma_f32_16x16x32_bf16 v[100:103], v[168:171], v[208:211], v[100:103]
	v_mfma_f32_16x16x32_bf16 v[92:95], v[160:163], v[216:219], v[92:95]
	v_mfma_f32_16x16x32_bf16 v[84:87], v[168:171], v[216:219], v[84:87]
	v_mfma_f32_16x16x32_bf16 v[76:79], v[160:163], v[224:227], v[76:79]
	v_mfma_f32_16x16x32_bf16 v[68:71], v[168:171], v[224:227], v[68:71]
	s_barrier
	s_add_i32 s22, 0, 0x1c000
	s_add_i32 s23, s45, s29
	s_mov_b32 m0, s23
	ds_read_b128 v[228:231], v129 offset:49152
	ds_read_b128 v[232:235], v129 offset:50176
	ds_read_b128 v[236:239], v129 offset:51200
	ds_read_b128 v[240:243], v129 offset:52224
	global_load_lds_dwordx4 v148, s[84:85]
	s_add_i32 m0, s23, 0x2000
	s_nop 0
	global_load_lds_dwordx4 v128, s[84:85]
	s_barrier
	s_waitcnt lgkmcnt(0)
	s_waitcnt lgkmcnt(0)
	v_mfma_f32_16x16x32_bf16 v[120:123], v[228:231], v[172:175], v[120:123]
	v_mfma_f32_16x16x32_bf16 v[112:115], v[236:239], v[172:175], v[112:115]
	v_mfma_f32_16x16x32_bf16 v[104:107], v[228:231], v[204:207], v[104:107]
	v_mfma_f32_16x16x32_bf16 v[96:99], v[236:239], v[204:207], v[96:99]
	v_mfma_f32_16x16x32_bf16 v[88:91], v[228:231], v[212:215], v[88:91]
	v_mfma_f32_16x16x32_bf16 v[80:83], v[236:239], v[212:215], v[80:83]
	v_mfma_f32_16x16x32_bf16 v[72:75], v[228:231], v[220:223], v[72:75]
	v_mfma_f32_16x16x32_bf16 v[64:67], v[236:239], v[220:223], v[64:67]
	v_mfma_f32_16x16x32_bf16 v[120:123], v[232:235], v[200:203], v[120:123]
	v_mfma_f32_16x16x32_bf16 v[112:115], v[240:243], v[200:203], v[112:115]
	v_mfma_f32_16x16x32_bf16 v[104:107], v[232:235], v[208:211], v[104:107]
	v_mfma_f32_16x16x32_bf16 v[96:99], v[240:243], v[208:211], v[96:99]
	v_mfma_f32_16x16x32_bf16 v[88:91], v[232:235], v[216:219], v[88:91]
	v_mfma_f32_16x16x32_bf16 v[80:83], v[240:243], v[216:219], v[80:83]
	v_mfma_f32_16x16x32_bf16 v[72:75], v[232:235], v[224:227], v[72:75]
	v_mfma_f32_16x16x32_bf16 v[64:67], v[240:243], v[224:227], v[64:67]
	s_mov_b32 m0, s35
	s_barrier
	ds_read_b128 v[172:175], v143 offset:49152
	ds_read_b128 v[200:203], v143 offset:50176
	ds_read_b128 v[204:207], v143 offset:51200
	ds_read_b128 v[208:211], v143 offset:52224
	ds_read_b128 v[212:215], v143 offset:53248
	ds_read_b128 v[216:219], v143 offset:54272
	ds_read_b128 v[220:223], v143 offset:55296
	ds_read_b128 v[224:227], v143 offset:56320
	global_load_lds_dwordx4 v132, s[86:87]
	s_mov_b32 m0, s36
	s_nop 0
	global_load_lds_dwordx4 v130, s[86:87]
	s_barrier
	s_waitcnt lgkmcnt(0)
	s_waitcnt lgkmcnt(0)
	v_mfma_f32_16x16x32_bf16 v[60:63], v[144:147], v[172:175], v[60:63]
	v_mfma_f32_16x16x32_bf16 v[52:55], v[164:167], v[172:175], v[52:55]
	v_mfma_f32_16x16x32_bf16 v[44:47], v[144:147], v[204:207], v[44:47]
	v_mfma_f32_16x16x32_bf16 v[36:39], v[164:167], v[204:207], v[36:39]
	v_mfma_f32_16x16x32_bf16 v[28:31], v[144:147], v[212:215], v[28:31]
	v_mfma_f32_16x16x32_bf16 v[20:23], v[164:167], v[212:215], v[20:23]
	v_mfma_f32_16x16x32_bf16 v[12:15], v[144:147], v[220:223], v[12:15]
	v_mfma_f32_16x16x32_bf16 v[4:7], v[164:167], v[220:223], v[4:7]
	v_mfma_f32_16x16x32_bf16 v[60:63], v[160:163], v[200:203], v[60:63]
	v_mfma_f32_16x16x32_bf16 v[52:55], v[168:171], v[200:203], v[52:55]
	v_mfma_f32_16x16x32_bf16 v[44:47], v[160:163], v[208:211], v[44:47]
	v_mfma_f32_16x16x32_bf16 v[36:39], v[168:171], v[208:211], v[36:39]
	v_mfma_f32_16x16x32_bf16 v[28:31], v[160:163], v[216:219], v[28:31]
	v_mfma_f32_16x16x32_bf16 v[20:23], v[168:171], v[216:219], v[20:23]
	v_mfma_f32_16x16x32_bf16 v[12:15], v[160:163], v[224:227], v[12:15]
	v_mfma_f32_16x16x32_bf16 v[4:7], v[168:171], v[224:227], v[4:7]
	s_barrier
	s_add_u32 s20, s20, 0x80080
	s_addc_u32 s21, s21, 0
	s_add_i32 s22, s22, s29
	s_mov_b32 m0, s22
	s_nop 0
	global_load_lds_dwordx4 v148, s[20:21]
	s_add_i32 m0, s22, 0x2000
	s_nop 0
	global_load_lds_dwordx4 v128, s[20:21]
	s_waitcnt vmcnt(6)
	s_barrier
	v_mfma_f32_16x16x32_bf16 v[56:59], v[228:231], v[172:175], v[56:59]
	v_mfma_f32_16x16x32_bf16 v[48:51], v[236:239], v[172:175], v[48:51]
	v_mfma_f32_16x16x32_bf16 v[40:43], v[228:231], v[204:207], v[40:43]
	v_mfma_f32_16x16x32_bf16 v[32:35], v[236:239], v[204:207], v[32:35]
	v_mfma_f32_16x16x32_bf16 v[24:27], v[228:231], v[212:215], v[24:27]
	v_mfma_f32_16x16x32_bf16 v[16:19], v[236:239], v[212:215], v[16:19]
	v_mfma_f32_16x16x32_bf16 v[8:11], v[228:231], v[220:223], v[8:11]
	v_mfma_f32_16x16x32_bf16 v[0:3], v[236:239], v[220:223], v[0:3]
	v_mfma_f32_16x16x32_bf16 v[56:59], v[232:235], v[200:203], v[56:59]
	v_mfma_f32_16x16x32_bf16 v[48:51], v[240:243], v[200:203], v[48:51]
	v_mfma_f32_16x16x32_bf16 v[40:43], v[232:235], v[208:211], v[40:43]
	v_mfma_f32_16x16x32_bf16 v[32:35], v[240:243], v[208:211], v[32:35]
	v_mfma_f32_16x16x32_bf16 v[24:27], v[232:235], v[216:219], v[24:27]
	v_mfma_f32_16x16x32_bf16 v[16:19], v[240:243], v[216:219], v[16:19]
	v_mfma_f32_16x16x32_bf16 v[8:11], v[232:235], v[224:227], v[8:11]
	v_mfma_f32_16x16x32_bf16 v[0:3], v[240:243], v[224:227], v[0:3]
	s_add_i32 s44, s44, 2
	s_add_u32 s16, s16, 0x100
	s_addc_u32 s17, s17, 0
	s_add_u32 s42, s42, 0x100
	s_addc_u32 s43, s43, 0
	s_cmp_gt_u32 s44, 29
	s_barrier
; __device__ __forceinline__ unsigned cvt_pk_bf16(float lo, float hi) { unsigned r; asm("v_cvt_pk_bf16_f32 %0, %1, %2" : "=v"(r) : "v"(lo), "v"(hi)); return r; }
;     __device__ __forceinline__ void operator()(const f32x4 (&acc)[2][2][4][2], const Unit& u, int wr, int wc, int fr, int fq) const {
;         const int row0 = u.pm * BM + wr * 64 + fr, col0 = u.pn * HALF + wc * 32 + 8 * fq;
; #pragma unroll
;         for (int ai = 0; ai < 2; ++ai)
; #pragma unroll
;             for (int m = 0; m < 4; ++m) { bf16_t* rowp = O + (size_t)(row0 + ai * HALF + m * 16) * ldc + col0;
;                 float h[8];
; #pragma unroll
;                 for (int n = 0; n < 2; ++n)
; #pragma unroll
;                     for (int j = 0; j < 4; ++j) { const float g = acc[ai][0][m][n][j], up = acc[ai][1][m][n][j];
;                         const float e = __builtin_amdgcn_exp2f(-1.4426950408889634f * g);
;                         h[n * 4 + j] = g * __builtin_amdgcn_rcpf(1.0f + e) * up; }
;                 u32x4 w; w.x = cvt_pk_bf16(h[0], h[1]); w.y = cvt_pk_bf16(h[2], h[3]); w.z = cvt_pk_bf16(h[4], h[5]); w.w = cvt_pk_bf16(h[6], h[7]);
;                 *(u32x4*)rowp = w; }
	s_cbranch_scc0 .LBB0_213
	v_mul_f32_e32 v145, 0xbfb8aa3b, v124
	v_exp_f32_e32 v145, v145
	v_lshl_or_b32 v146, s38, 7, v142
	v_lshl_add_u32 v144, s39, 8, v140
	v_ashrrev_i32_e32 v147, 31, v146
	v_add_f32_e32 v145, 1.0, v145
	v_rcp_f32_e32 v145, v145
	v_mov_b64_e32 v[138:139], s[4:5]
	s_movk_i32 s7, 0x2c00
	v_mad_i64_i32 v[160:161], s[16:17], v144, s7, v[138:139]
	v_mul_f32_e32 v124, v124, v145
	v_mul_f32_e32 v120, v120, v124
	v_mul_f32_e32 v124, 0xbfb8aa3b, v125
	v_exp_f32_e32 v124, v124
	s_and_b64 vcc, exec, s[0:1]
	s_mov_b32 s38, s6
	s_mov_b32 s39, s10
	v_add_f32_e32 v124, 1.0, v124
	v_rcp_f32_e32 v124, v124
	s_mov_b64 s[20:21], s[14:15]
	v_mul_f32_e32 v124, v125, v124
	v_mul_f32_e32 v121, v121, v124
	v_mul_f32_e32 v124, 0xbfb8aa3b, v126
	v_exp_f32_e32 v124, v124
	s_nop 0
	v_add_f32_e32 v124, 1.0, v124
	v_rcp_f32_e32 v124, v124
	s_nop 0
	v_mul_f32_e32 v124, v126, v124
	v_mul_f32_e32 v122, v122, v124
	v_mul_f32_e32 v124, 0xbfb8aa3b, v127
	v_exp_f32_e32 v124, v124
	s_nop 0
	v_add_f32_e32 v124, 1.0, v124
	v_rcp_f32_e32 v124, v124
	s_nop 0
	v_mul_f32_e32 v124, v127, v124
	v_mul_f32_e32 v123, v123, v124
	v_mul_f32_e32 v124, 0xbfb8aa3b, v116
	v_exp_f32_e32 v124, v124
	s_nop 0
	v_add_f32_e32 v124, 1.0, v124
	v_rcp_f32_e32 v124, v124
	s_nop 0
	v_mul_f32_e32 v116, v116, v124
	v_mul_f32_e32 v116, v112, v116
	v_mul_f32_e32 v112, 0xbfb8aa3b, v117
	v_exp_f32_e32 v112, v112
	s_nop 0
	v_add_f32_e32 v112, 1.0, v112
	v_rcp_f32_e32 v112, v112
	s_nop 0
	v_mul_f32_e32 v112, v117, v112
	v_mul_f32_e32 v117, v113, v112
	v_mul_f32_e32 v112, 0xbfb8aa3b, v118
	v_exp_f32_e32 v112, v112
	v_cvt_pk_bf16_f32 v116, v116, v117
	s_nop 0
	v_add_f32_e32 v112, 1.0, v112
	v_rcp_f32_e32 v112, v112
	s_nop 0
	v_mul_f32_e32 v112, v118, v112
	v_mul_f32_e32 v124, v114, v112
	v_mul_f32_e32 v112, 0xbfb8aa3b, v119
	v_exp_f32_e32 v112, v112
	v_cvt_pk_bf16_f32 v114, v120, v121
	s_nop 0
	v_add_f32_e32 v112, 1.0, v112
	v_rcp_f32_e32 v112, v112
	s_nop 0
	v_mul_f32_e32 v112, v119, v112
	v_mul_f32_e32 v125, v115, v112
	v_lshlrev_b64 v[112:113], 1, v[146:147]
	v_lshl_add_u64 v[118:119], v[160:161], 0, v[112:113]
	v_cvt_pk_bf16_f32 v115, v122, v123
	v_cvt_pk_bf16_f32 v117, v124, v125
	global_store_dwordx4 v[118:119], v[114:117], off
	s_nop 1
	v_mul_f32_e32 v116, 0xbfb8aa3b, v108
	v_exp_f32_e32 v116, v116
	v_or_b32_e32 v114, 16, v144
	v_mad_i64_i32 v[114:115], s[16:17], v114, s7, v[138:139]
	v_add_f32_e32 v116, 1.0, v116
	v_rcp_f32_e32 v116, v116
	s_nop 0
	v_mul_f32_e32 v108, v108, v116
	v_mul_f32_e32 v104, v104, v108
	v_mul_f32_e32 v108, 0xbfb8aa3b, v109
	v_exp_f32_e32 v108, v108
	s_nop 0
	v_add_f32_e32 v108, 1.0, v108
	v_rcp_f32_e32 v108, v108
	s_nop 0
	v_mul_f32_e32 v108, v109, v108
	v_mul_f32_e32 v105, v105, v108
	v_mul_f32_e32 v108, 0xbfb8aa3b, v110
	v_exp_f32_e32 v108, v108
	s_nop 0
	v_add_f32_e32 v108, 1.0, v108
	v_rcp_f32_e32 v108, v108
	s_nop 0
	v_mul_f32_e32 v108, v110, v108
	v_mul_f32_e32 v106, v106, v108
	v_mul_f32_e32 v108, 0xbfb8aa3b, v111
	v_exp_f32_e32 v108, v108
	s_nop 0
	v_add_f32_e32 v108, 1.0, v108
	v_rcp_f32_e32 v108, v108
	s_nop 0
	v_mul_f32_e32 v108, v111, v108
	v_mul_f32_e32 v107, v107, v108
	v_mul_f32_e32 v108, 0xbfb8aa3b, v100
	v_exp_f32_e32 v108, v108
	s_nop 0
	v_add_f32_e32 v108, 1.0, v108
	v_rcp_f32_e32 v108, v108
	s_nop 0
	v_mul_f32_e32 v100, v100, v108
	v_mul_f32_e32 v108, v96, v100
	v_mul_f32_e32 v96, 0xbfb8aa3b, v101
	v_exp_f32_e32 v96, v96
	s_nop 0
	v_add_f32_e32 v96, 1.0, v96
	v_rcp_f32_e32 v96, v96
	s_nop 0
	v_mul_f32_e32 v96, v101, v96
	v_mul_f32_e32 v109, v97, v96
	v_mul_f32_e32 v96, 0xbfb8aa3b, v102
	v_exp_f32_e32 v96, v96
	v_lshl_add_u64 v[100:101], v[114:115], 0, v[112:113]
	v_cvt_pk_bf16_f32 v97, v106, v107
	v_add_f32_e32 v96, 1.0, v96
	v_rcp_f32_e32 v96, v96
	s_nop 0
	v_mul_f32_e32 v96, v102, v96
	v_mul_f32_e32 v102, v98, v96
	v_mul_f32_e32 v96, 0xbfb8aa3b, v103
	v_exp_f32_e32 v96, v96
	v_cvt_pk_bf16_f32 v98, v108, v109
	s_nop 0
	v_add_f32_e32 v96, 1.0, v96
	v_rcp_f32_e32 v96, v96
	s_nop 0
	v_mul_f32_e32 v96, v103, v96
	v_mul_f32_e32 v99, v99, v96
	v_cvt_pk_bf16_f32 v96, v104, v105
	v_cvt_pk_bf16_f32 v99, v102, v99
	global_store_dwordx4 v[100:101], v[96:99], off
	s_nop 1
	v_mul_f32_e32 v98, 0xbfb8aa3b, v92
	v_exp_f32_e32 v98, v98
	v_or_b32_e32 v96, 32, v144
	v_mad_i64_i32 v[96:97], s[16:17], v96, s7, v[138:139]
	v_add_f32_e32 v98, 1.0, v98
	v_rcp_f32_e32 v98, v98
	s_nop 0
	v_mul_f32_e32 v92, v92, v98
	v_mul_f32_e32 v88, v88, v92
	v_mul_f32_e32 v92, 0xbfb8aa3b, v93
	v_exp_f32_e32 v92, v92
	s_nop 0
	v_add_f32_e32 v92, 1.0, v92
	v_rcp_f32_e32 v92, v92
	s_nop 0
	v_mul_f32_e32 v92, v93, v92
	v_mul_f32_e32 v89, v89, v92
	v_mul_f32_e32 v92, 0xbfb8aa3b, v94
	v_exp_f32_e32 v92, v92
	s_nop 0
	v_add_f32_e32 v92, 1.0, v92
	v_rcp_f32_e32 v92, v92
	s_nop 0
	v_mul_f32_e32 v92, v94, v92
	v_mul_f32_e32 v90, v90, v92
	v_mul_f32_e32 v92, 0xbfb8aa3b, v95
	v_exp_f32_e32 v92, v92
	s_nop 0
	v_add_f32_e32 v92, 1.0, v92
	v_rcp_f32_e32 v92, v92
	s_nop 0
	v_mul_f32_e32 v92, v95, v92
	v_mul_f32_e32 v91, v91, v92
	v_mul_f32_e32 v92, 0xbfb8aa3b, v84
	v_exp_f32_e32 v92, v92
	s_nop 0
	v_add_f32_e32 v92, 1.0, v92
	v_rcp_f32_e32 v92, v92
	s_nop 0
	v_mul_f32_e32 v84, v84, v92
	v_mul_f32_e32 v92, v80, v84
	v_mul_f32_e32 v80, 0xbfb8aa3b, v85
	v_exp_f32_e32 v80, v80
	s_nop 0
	v_add_f32_e32 v80, 1.0, v80
	v_rcp_f32_e32 v80, v80
	s_nop 0
	v_mul_f32_e32 v80, v85, v80
	v_mul_f32_e32 v93, v81, v80
	v_mul_f32_e32 v80, 0xbfb8aa3b, v86
	v_exp_f32_e32 v80, v80
	v_lshl_add_u64 v[84:85], v[96:97], 0, v[112:113]
	v_cvt_pk_bf16_f32 v81, v90, v91
	v_add_f32_e32 v80, 1.0, v80
	v_rcp_f32_e32 v80, v80
	s_nop 0
	v_mul_f32_e32 v80, v86, v80
	v_mul_f32_e32 v86, v82, v80
	v_mul_f32_e32 v80, 0xbfb8aa3b, v87
; __device__ __forceinline__ unsigned cvt_pk_bf16(float lo, float hi) { unsigned r; asm("v_cvt_pk_bf16_f32 %0, %1, %2" : "=v"(r) : "v"(lo), "v"(hi)); return r; }
;     __device__ __forceinline__ void operator()(const f32x4 (&acc)[2][2][4][2], const Unit& u, int wr, int wc, int fr, int fq) const {
;         const int row0 = u.pm * BM + wr * 64 + fr, col0 = u.pn * HALF + wc * 32 + 8 * fq;
; #pragma unroll
;         for (int ai = 0; ai < 2; ++ai)
; #pragma unroll
;             for (int m = 0; m < 4; ++m) { bf16_t* rowp = O + (size_t)(row0 + ai * HALF + m * 16) * ldc + col0;
;                 float h[8];
; #pragma unroll
;                 for (int n = 0; n < 2; ++n)
; #pragma unroll
;                     for (int j = 0; j < 4; ++j) { const float g = acc[ai][0][m][n][j], up = acc[ai][1][m][n][j];
;                         const float e = __builtin_amdgcn_exp2f(-1.4426950408889634f * g);
;                         h[n * 4 + j] = g * __builtin_amdgcn_rcpf(1.0f + e) * up; }
;                 u32x4 w; w.x = cvt_pk_bf16(h[0], h[1]); w.y = cvt_pk_bf16(h[2], h[3]); w.z = cvt_pk_bf16(h[4], h[5]); w.w = cvt_pk_bf16(h[6], h[7]);
;                 *(u32x4*)rowp = w; }
	v_exp_f32_e32 v80, v80
	v_cvt_pk_bf16_f32 v82, v92, v93
	s_nop 0
	v_add_f32_e32 v80, 1.0, v80
	v_rcp_f32_e32 v80, v80
	s_nop 0
	v_mul_f32_e32 v80, v87, v80
	v_mul_f32_e32 v83, v83, v80
	v_cvt_pk_bf16_f32 v80, v88, v89
	v_cvt_pk_bf16_f32 v83, v86, v83
	global_store_dwordx4 v[84:85], v[80:83], off
	s_nop 1
	v_mul_f32_e32 v82, 0xbfb8aa3b, v76
	v_exp_f32_e32 v82, v82
	v_or_b32_e32 v80, 48, v144
	v_mad_i64_i32 v[80:81], s[16:17], v80, s7, v[138:139]
	v_add_f32_e32 v82, 1.0, v82
	v_rcp_f32_e32 v82, v82
	s_nop 0
	v_mul_f32_e32 v76, v76, v82
	v_mul_f32_e32 v72, v72, v76
	v_mul_f32_e32 v76, 0xbfb8aa3b, v77
	v_exp_f32_e32 v76, v76
	s_nop 0
	v_add_f32_e32 v76, 1.0, v76
	v_rcp_f32_e32 v76, v76
	s_nop 0
	v_mul_f32_e32 v76, v77, v76
	v_mul_f32_e32 v73, v73, v76
	v_mul_f32_e32 v76, 0xbfb8aa3b, v78
	v_exp_f32_e32 v76, v76
	s_nop 0
	v_add_f32_e32 v76, 1.0, v76
	v_rcp_f32_e32 v76, v76
	s_nop 0
	v_mul_f32_e32 v76, v78, v76
	v_mul_f32_e32 v74, v74, v76
	v_mul_f32_e32 v76, 0xbfb8aa3b, v79
	v_exp_f32_e32 v76, v76
	s_nop 0
	v_add_f32_e32 v76, 1.0, v76
	v_rcp_f32_e32 v76, v76
	s_nop 0
	v_mul_f32_e32 v76, v79, v76
	v_mul_f32_e32 v75, v75, v76
	v_mul_f32_e32 v76, 0xbfb8aa3b, v68
	v_exp_f32_e32 v76, v76
	s_nop 0
	v_add_f32_e32 v76, 1.0, v76
	v_rcp_f32_e32 v76, v76
	s_nop 0
	v_mul_f32_e32 v68, v68, v76
	v_mul_f32_e32 v76, v64, v68
	v_mul_f32_e32 v64, 0xbfb8aa3b, v69
	v_exp_f32_e32 v64, v64
	s_nop 0
	v_add_f32_e32 v64, 1.0, v64
	v_rcp_f32_e32 v64, v64
	s_nop 0
	v_mul_f32_e32 v64, v69, v64
	v_mul_f32_e32 v77, v65, v64
	v_mul_f32_e32 v64, 0xbfb8aa3b, v70
	v_exp_f32_e32 v64, v64
	v_lshl_add_u64 v[68:69], v[80:81], 0, v[112:113]
	v_cvt_pk_bf16_f32 v65, v74, v75
	v_add_f32_e32 v64, 1.0, v64
	v_rcp_f32_e32 v64, v64
	s_nop 0
	v_mul_f32_e32 v64, v70, v64
	v_mul_f32_e32 v70, v66, v64
	v_mul_f32_e32 v64, 0xbfb8aa3b, v71
	v_exp_f32_e32 v64, v64
	v_cvt_pk_bf16_f32 v66, v76, v77
	s_nop 0
	v_add_f32_e32 v64, 1.0, v64
	v_rcp_f32_e32 v64, v64
	s_nop 0
	v_mul_f32_e32 v64, v71, v64
	v_mul_f32_e32 v67, v67, v64
	v_cvt_pk_bf16_f32 v64, v72, v73
	v_cvt_pk_bf16_f32 v67, v70, v67
	global_store_dwordx4 v[68:69], v[64:67], off
	s_nop 1
	v_mul_f32_e32 v66, 0xbfb8aa3b, v60
	v_exp_f32_e32 v66, v66
	v_add_u32_e32 v64, 0x80, v144
	v_mad_i64_i32 v[64:65], s[16:17], v64, s7, v[138:139]
	v_add_f32_e32 v66, 1.0, v66
	v_rcp_f32_e32 v66, v66
	s_nop 0
	v_mul_f32_e32 v60, v60, v66
	v_mul_f32_e32 v56, v56, v60
	v_mul_f32_e32 v60, 0xbfb8aa3b, v61
	v_exp_f32_e32 v60, v60
	s_nop 0
	v_add_f32_e32 v60, 1.0, v60
	v_rcp_f32_e32 v60, v60
	s_nop 0
	v_mul_f32_e32 v60, v61, v60
	v_mul_f32_e32 v57, v57, v60
	v_mul_f32_e32 v60, 0xbfb8aa3b, v62
	v_exp_f32_e32 v60, v60
	s_nop 0
	v_add_f32_e32 v60, 1.0, v60
	v_rcp_f32_e32 v60, v60
	s_nop 0
	v_mul_f32_e32 v60, v62, v60
	v_mul_f32_e32 v58, v58, v60
	v_mul_f32_e32 v60, 0xbfb8aa3b, v63
	v_exp_f32_e32 v60, v60
	s_nop 0
	v_add_f32_e32 v60, 1.0, v60
	v_rcp_f32_e32 v60, v60
	s_nop 0
	v_mul_f32_e32 v60, v63, v60
	v_mul_f32_e32 v59, v59, v60
	v_mul_f32_e32 v60, 0xbfb8aa3b, v52
	v_exp_f32_e32 v60, v60
	s_nop 0
	v_add_f32_e32 v60, 1.0, v60
	v_rcp_f32_e32 v60, v60
	s_nop 0
	v_mul_f32_e32 v52, v52, v60
	v_mul_f32_e32 v60, v48, v52
	v_mul_f32_e32 v48, 0xbfb8aa3b, v53
	v_exp_f32_e32 v48, v48
	s_nop 0
	v_add_f32_e32 v48, 1.0, v48
	v_rcp_f32_e32 v48, v48
	s_nop 0
	v_mul_f32_e32 v48, v53, v48
	v_mul_f32_e32 v61, v49, v48
	v_mul_f32_e32 v48, 0xbfb8aa3b, v54
	v_exp_f32_e32 v48, v48
	v_lshl_add_u64 v[52:53], v[64:65], 0, v[112:113]
	v_cvt_pk_bf16_f32 v49, v58, v59
	v_add_f32_e32 v48, 1.0, v48
	v_rcp_f32_e32 v48, v48
	s_nop 0
	v_mul_f32_e32 v48, v54, v48
	v_mul_f32_e32 v54, v50, v48
	v_mul_f32_e32 v48, 0xbfb8aa3b, v55
	v_exp_f32_e32 v48, v48
	v_cvt_pk_bf16_f32 v50, v60, v61
	s_nop 0
	v_add_f32_e32 v48, 1.0, v48
	v_rcp_f32_e32 v48, v48
	s_nop 0
	v_mul_f32_e32 v48, v55, v48
	v_mul_f32_e32 v51, v51, v48
	v_cvt_pk_bf16_f32 v48, v56, v57
	v_cvt_pk_bf16_f32 v51, v54, v51
	global_store_dwordx4 v[52:53], v[48:51], off
	s_nop 1
	v_mul_f32_e32 v50, 0xbfb8aa3b, v44
	v_exp_f32_e32 v50, v50
	v_add_u32_e32 v48, 0x90, v144
	v_mad_i64_i32 v[48:49], s[16:17], v48, s7, v[138:139]
	v_add_f32_e32 v50, 1.0, v50
	v_rcp_f32_e32 v50, v50
	s_nop 0
	v_mul_f32_e32 v44, v44, v50
	v_mul_f32_e32 v40, v40, v44
	v_mul_f32_e32 v44, 0xbfb8aa3b, v45
	v_exp_f32_e32 v44, v44
	s_nop 0
	v_add_f32_e32 v44, 1.0, v44
	v_rcp_f32_e32 v44, v44
	s_nop 0
	v_mul_f32_e32 v44, v45, v44
	v_mul_f32_e32 v41, v41, v44
	v_mul_f32_e32 v44, 0xbfb8aa3b, v46
	v_exp_f32_e32 v44, v44
	s_nop 0
	v_add_f32_e32 v44, 1.0, v44
	v_rcp_f32_e32 v44, v44
	s_nop 0
	v_mul_f32_e32 v44, v46, v44
	v_mul_f32_e32 v42, v42, v44
	v_mul_f32_e32 v44, 0xbfb8aa3b, v47
	v_exp_f32_e32 v44, v44
	s_nop 0
	v_add_f32_e32 v44, 1.0, v44
	v_rcp_f32_e32 v44, v44
	s_nop 0
; __device__ __forceinline__ unsigned cvt_pk_bf16(float lo, float hi) { unsigned r; asm("v_cvt_pk_bf16_f32 %0, %1, %2" : "=v"(r) : "v"(lo), "v"(hi)); return r; }
; #define PG8_WAIT_V(n) asm volatile("s_waitcnt vmcnt(" #n ")" ::: "memory")
; #define PG8_BAR __builtin_amdgcn_s_barrier()
;     __device__ __forceinline__ void operator()(const f32x4 (&acc)[2][2][4][2], const Unit& u, int wr, int wc, int fr, int fq) const {
;         const int row0 = u.pm * BM + wr * 64 + fr, col0 = u.pn * HALF + wc * 32 + 8 * fq;
; #pragma unroll
;         for (int ai = 0; ai < 2; ++ai)
; #pragma unroll
;             for (int m = 0; m < 4; ++m) { bf16_t* rowp = O + (size_t)(row0 + ai * HALF + m * 16) * ldc + col0;
;                 float h[8];
; #pragma unroll
;                 for (int n = 0; n < 2; ++n)
; #pragma unroll
;                     for (int j = 0; j < 4; ++j) { const float g = acc[ai][0][m][n][j], up = acc[ai][1][m][n][j];
;                         const float e = __builtin_amdgcn_exp2f(-1.4426950408889634f * g);
;                         h[n * 4 + j] = g * __builtin_amdgcn_rcpf(1.0f + e) * up; }
;                 u32x4 w; w.x = cvt_pk_bf16(h[0], h[1]); w.y = cvt_pk_bf16(h[2], h[3]); w.z = cvt_pk_bf16(h[4], h[5]); w.w = cvt_pk_bf16(h[6], h[7]);
;                 *(u32x4*)rowp = w; }
; template <class Epi, class Sched>
; __device__ __forceinline__ void gemm_phase(LAS unsigned char* lds, const Gemm g, const Sched& S, const Epi& E) {
;     ...
;     PG8_WAIT_V(0);
;     if (wr == 0) PG8_BAR;
;     PG8_BAR;
	v_mul_f32_e32 v44, v47, v44
	v_mul_f32_e32 v43, v43, v44
	v_mul_f32_e32 v44, 0xbfb8aa3b, v36
	v_exp_f32_e32 v44, v44
	s_nop 0
	v_add_f32_e32 v44, 1.0, v44
	v_rcp_f32_e32 v44, v44
	s_nop 0
	v_mul_f32_e32 v36, v36, v44
	v_mul_f32_e32 v44, v32, v36
	v_mul_f32_e32 v32, 0xbfb8aa3b, v37
	v_exp_f32_e32 v32, v32
	s_nop 0
	v_add_f32_e32 v32, 1.0, v32
	v_rcp_f32_e32 v32, v32
	s_nop 0
	v_mul_f32_e32 v32, v37, v32
	v_mul_f32_e32 v45, v33, v32
	v_mul_f32_e32 v32, 0xbfb8aa3b, v38
	v_exp_f32_e32 v32, v32
	v_lshl_add_u64 v[36:37], v[48:49], 0, v[112:113]
	v_cvt_pk_bf16_f32 v33, v42, v43
	v_add_f32_e32 v32, 1.0, v32
	v_rcp_f32_e32 v32, v32
	s_nop 0
	v_mul_f32_e32 v32, v38, v32
	v_mul_f32_e32 v38, v34, v32
	v_mul_f32_e32 v32, 0xbfb8aa3b, v39
	v_exp_f32_e32 v32, v32
	v_cvt_pk_bf16_f32 v34, v44, v45
	s_nop 0
	v_add_f32_e32 v32, 1.0, v32
	v_rcp_f32_e32 v32, v32
	s_nop 0
	v_mul_f32_e32 v32, v39, v32
	v_mul_f32_e32 v35, v35, v32
	v_cvt_pk_bf16_f32 v32, v40, v41
	v_cvt_pk_bf16_f32 v35, v38, v35
	global_store_dwordx4 v[36:37], v[32:35], off
	s_nop 1
	v_mul_f32_e32 v34, 0xbfb8aa3b, v28
	v_exp_f32_e32 v34, v34
	v_add_u32_e32 v32, 0xa0, v144
	v_mad_i64_i32 v[32:33], s[16:17], v32, s7, v[138:139]
	v_add_f32_e32 v34, 1.0, v34
	v_rcp_f32_e32 v34, v34
	s_nop 0
	v_mul_f32_e32 v28, v28, v34
	v_mul_f32_e32 v24, v24, v28
	v_mul_f32_e32 v28, 0xbfb8aa3b, v29
	v_exp_f32_e32 v28, v28
	s_nop 0
	v_add_f32_e32 v28, 1.0, v28
	v_rcp_f32_e32 v28, v28
	s_nop 0
	v_mul_f32_e32 v28, v29, v28
	v_mul_f32_e32 v25, v25, v28
	v_mul_f32_e32 v28, 0xbfb8aa3b, v30
	v_exp_f32_e32 v28, v28
	s_nop 0
	v_add_f32_e32 v28, 1.0, v28
	v_rcp_f32_e32 v28, v28
	s_nop 0
	v_mul_f32_e32 v28, v30, v28
	v_mul_f32_e32 v26, v26, v28
	v_mul_f32_e32 v28, 0xbfb8aa3b, v31
	v_exp_f32_e32 v28, v28
	s_nop 0
	v_add_f32_e32 v28, 1.0, v28
	v_rcp_f32_e32 v28, v28
	s_nop 0
	v_mul_f32_e32 v28, v31, v28
	v_mul_f32_e32 v27, v27, v28
	v_mul_f32_e32 v28, 0xbfb8aa3b, v20
	v_exp_f32_e32 v28, v28
	s_nop 0
	v_add_f32_e32 v28, 1.0, v28
	v_rcp_f32_e32 v28, v28
	s_nop 0
	v_mul_f32_e32 v20, v20, v28
	v_mul_f32_e32 v28, v16, v20
	v_mul_f32_e32 v16, 0xbfb8aa3b, v21
	v_exp_f32_e32 v16, v16
	s_nop 0
	v_add_f32_e32 v16, 1.0, v16
	v_rcp_f32_e32 v16, v16
	s_nop 0
	v_mul_f32_e32 v16, v21, v16
	v_mul_f32_e32 v29, v17, v16
	v_mul_f32_e32 v16, 0xbfb8aa3b, v22
	v_exp_f32_e32 v16, v16
	v_lshl_add_u64 v[20:21], v[32:33], 0, v[112:113]
	v_cvt_pk_bf16_f32 v17, v26, v27
	v_add_f32_e32 v16, 1.0, v16
	v_rcp_f32_e32 v16, v16
	s_nop 0
	v_mul_f32_e32 v16, v22, v16
	v_mul_f32_e32 v22, v18, v16
	v_mul_f32_e32 v16, 0xbfb8aa3b, v23
	v_exp_f32_e32 v16, v16
	v_cvt_pk_bf16_f32 v18, v28, v29
	s_nop 0
	v_add_f32_e32 v16, 1.0, v16
	v_rcp_f32_e32 v16, v16
	s_nop 0
	v_mul_f32_e32 v16, v23, v16
	v_mul_f32_e32 v19, v19, v16
	v_cvt_pk_bf16_f32 v16, v24, v25
	v_cvt_pk_bf16_f32 v19, v22, v19
	global_store_dwordx4 v[20:21], v[16:19], off
	s_nop 1
	v_mul_f32_e32 v18, 0xbfb8aa3b, v12
	v_exp_f32_e32 v18, v18
	v_add_u32_e32 v16, 0xb0, v144
	v_mad_i64_i32 v[16:17], s[16:17], v16, s7, v[138:139]
	v_add_f32_e32 v18, 1.0, v18
	v_rcp_f32_e32 v18, v18
	s_mov_b64 s[16:17], s[12:13]
	v_mul_f32_e32 v12, v12, v18
	v_mul_f32_e32 v8, v8, v12
	v_mul_f32_e32 v12, 0xbfb8aa3b, v13
	v_exp_f32_e32 v12, v12
	s_nop 0
	v_add_f32_e32 v12, 1.0, v12
	v_rcp_f32_e32 v12, v12
	s_nop 0
	v_mul_f32_e32 v12, v13, v12
	v_mul_f32_e32 v9, v9, v12
	v_mul_f32_e32 v12, 0xbfb8aa3b, v14
	v_exp_f32_e32 v12, v12
	s_nop 0
	v_add_f32_e32 v12, 1.0, v12
	v_rcp_f32_e32 v12, v12
	s_nop 0
	v_mul_f32_e32 v12, v14, v12
	v_mul_f32_e32 v10, v10, v12
	v_mul_f32_e32 v12, 0xbfb8aa3b, v15
	v_exp_f32_e32 v12, v12
	s_nop 0
	v_add_f32_e32 v12, 1.0, v12
	v_rcp_f32_e32 v12, v12
	s_nop 0
	v_mul_f32_e32 v12, v15, v12
	v_mul_f32_e32 v11, v11, v12
	v_mul_f32_e32 v12, 0xbfb8aa3b, v4
	v_exp_f32_e32 v12, v12
	s_nop 0
	v_add_f32_e32 v12, 1.0, v12
	v_rcp_f32_e32 v12, v12
	s_nop 0
	v_mul_f32_e32 v4, v4, v12
	v_mul_f32_e32 v12, v0, v4
	v_mul_f32_e32 v0, 0xbfb8aa3b, v5
	v_exp_f32_e32 v0, v0
	s_nop 0
	v_add_f32_e32 v0, 1.0, v0
	v_rcp_f32_e32 v0, v0
	s_nop 0
	v_mul_f32_e32 v0, v5, v0
	v_mul_f32_e32 v13, v1, v0
	v_mul_f32_e32 v0, 0xbfb8aa3b, v6
	v_exp_f32_e32 v0, v0
	v_lshl_add_u64 v[4:5], v[16:17], 0, v[112:113]
	v_cvt_pk_bf16_f32 v1, v10, v11
	v_add_f32_e32 v0, 1.0, v0
	v_rcp_f32_e32 v0, v0
	s_nop 0
	v_mul_f32_e32 v0, v6, v0
	v_mul_f32_e32 v6, v2, v0
	v_mul_f32_e32 v0, 0xbfb8aa3b, v7
	v_exp_f32_e32 v0, v0
	v_cvt_pk_bf16_f32 v2, v12, v13
	s_nop 0
	v_add_f32_e32 v0, 1.0, v0
	v_rcp_f32_e32 v0, v0
	s_nop 0
	v_mul_f32_e32 v0, v7, v0
	v_mul_f32_e32 v3, v3, v0
	v_cvt_pk_bf16_f32 v0, v8, v9
	v_cvt_pk_bf16_f32 v3, v6, v3
	global_store_dwordx4 v[4:5], v[0:3], off
	s_cbranch_vccz .LBB0_210
	s_waitcnt vmcnt(0)
	s_cmpk_gt_u32 s24, 0xff
	s_cbranch_scc1 .LBB0_217
	s_barrier

; #define PG8_STAGE(bufoff, gbase, voff) do { _Pragma("unroll") for (int _i = 0; _i < 2; ++_i) \
;         __builtin_amdgcn_global_load_lds((const unsigned*)((const char*)(gbase) + (voff)[_i]), (LAS unsigned*)(lds + (bufoff) + ldsw + _i * 8192), 16, 0, 0); } while (0)
; #define PG8_LDA(dst, b, h) do { _Pragma("unroll") for (int m = 0; m < 4; ++m) _Pragma("unroll") for (int k = 0; k < 2; ++k) dst[m][k] = *(const LAS bf16x8*)(lds + PG8_SA(b, h) + aoff + m * 2048 + k * 1024); } while (0)
; #define PG8_LDB(dst, b, h) do { _Pragma("unroll") for (int n = 0; n < 2; ++n) _Pragma("unroll") for (int k = 0; k < 2; ++k) dst[n][k] = *(const LAS bf16x8*)(lds + PG8_SB(b, h) + boff + n * 2048 + k * 1024); } while (0)
; #define PG8_MMA(ai, bj, At, Bt) do { __builtin_amdgcn_s_setprio(1); _Pragma("unroll") for (int m = 0; m < 4; ++m) _Pragma("unroll") for (int n = 0; n < 2; ++n) _Pragma("unroll") for (int k = 0; k < 2; ++k) \
;         acc[ai][bj][m][n] = __builtin_amdgcn_mfma_f32_16x16x32_bf16(Bt[n][k], At[m][k], acc[ai][bj][m][n], 0, 0, 0); __builtin_amdgcn_s_setprio(0); } while (0)
; #define PG8_WAIT_V(n) asm volatile("s_waitcnt vmcnt(" #n ")" ::: "memory")
; #define PG8_WAIT_L(n) asm volatile("s_waitcnt lgkmcnt(" #n ")" ::: "memory")
; #define PG8_BAR __builtin_amdgcn_s_barrier()
; #define PG8_SCHED __builtin_amdgcn_sched_barrier(0)
; template <class Epi, class Sched>
; __device__ __forceinline__ void gemm_phase(LAS unsigned char* lds, const Gemm g, const Sched& S, const Epi& E) {
;     ...
;             PG8_LDB(B0, 0, 0); PG8_SCHED; PG8_LDA(At, 0, 0); PG8_STAGE(PG8_SA(1, 1), a1 + hstep, voffA);
;             PG8_WAIT_L(8); PG8_BAR; PG8_WAIT_L(0); PG8_MMA(0, 0, At, B0); PG8_BAR; PG8_SCHED;
;             PG8_LDB(B1, 0, 1); PG8_STAGE(PG8_SB(0, 0), b2, voffB);
;             PG8_BAR; PG8_WAIT_L(0); PG8_MMA(0, 1, At, B1); PG8_BAR;
;             PG8_LDA(At, 0, 1); PG8_STAGE(PG8_SA(0, 0), a2, voffA);
;             PG8_BAR; PG8_WAIT_L(0); PG8_MMA(1, 0, At, B0); PG8_BAR; PG8_SCHED;
;             PG8_STAGE(PG8_SB(0, 1), b2 + hstep, voffB);
;             PG8_WAIT_V(6); PG8_BAR; PG8_MMA(1, 1, At, B1); PG8_BAR;
;     ...
;         for (int a = 0; a < 2; ++a)
; #pragma unroll
;             for (int b = 0; b < 2; ++b)
; #pragma unroll
;                 for (int m = 0; m < 4; ++m)
; #pragma unroll
;                     for (int n = 0; n < 2; ++n) acc[a][b][m][n] = (f32x4){0.f, 0.f, 0.f, 0.f};
.LBB0_266:
	s_add_i32 s11, s45, -2
	s_waitcnt lgkmcnt(0)
	s_add_u32 s13, s20, 0x100
	v_mov_b32_e32 v0, 0
	s_addc_u32 s15, s21, 0
	s_mov_b32 s22, 0
	v_mov_b32_e32 v1, v0
	v_mov_b32_e32 v2, v0
	v_mov_b32_e32 v3, v0
	v_mov_b32_e32 v4, v0
	v_mov_b32_e32 v5, v0
	v_mov_b32_e32 v6, v0
	v_mov_b32_e32 v7, v0
	v_mov_b32_e32 v8, v0
	v_mov_b32_e32 v9, v0
	v_mov_b32_e32 v10, v0
	v_mov_b32_e32 v11, v0
	v_mov_b32_e32 v12, v0
	v_mov_b32_e32 v13, v0
	v_mov_b32_e32 v14, v0
	v_mov_b32_e32 v15, v0
	v_mov_b32_e32 v24, v0
	v_mov_b32_e32 v25, v0
	v_mov_b32_e32 v26, v0
	v_mov_b32_e32 v27, v0
	v_mov_b32_e32 v28, v0
	v_mov_b32_e32 v29, v0
	v_mov_b32_e32 v30, v0
	v_mov_b32_e32 v31, v0
	v_mov_b32_e32 v40, v0
	v_mov_b32_e32 v41, v0
	v_mov_b32_e32 v42, v0
	v_mov_b32_e32 v43, v0
	v_mov_b32_e32 v44, v0
	v_mov_b32_e32 v45, v0
	v_mov_b32_e32 v46, v0
	v_mov_b32_e32 v47, v0
	v_mov_b32_e32 v16, v0
	v_mov_b32_e32 v17, v0
	v_mov_b32_e32 v18, v0
	v_mov_b32_e32 v19, v0
	v_mov_b32_e32 v20, v0
	v_mov_b32_e32 v21, v0
	v_mov_b32_e32 v22, v0
	v_mov_b32_e32 v23, v0
	v_mov_b32_e32 v32, v0
	v_mov_b32_e32 v33, v0
	v_mov_b32_e32 v34, v0
	v_mov_b32_e32 v35, v0
	v_mov_b32_e32 v36, v0
	v_mov_b32_e32 v37, v0
	v_mov_b32_e32 v38, v0
	v_mov_b32_e32 v39, v0
	v_mov_b32_e32 v48, v0
	v_mov_b32_e32 v49, v0
	v_mov_b32_e32 v50, v0
	v_mov_b32_e32 v51, v0
	v_mov_b32_e32 v52, v0
	v_mov_b32_e32 v53, v0
	v_mov_b32_e32 v54, v0
	v_mov_b32_e32 v55, v0
	v_mov_b32_e32 v56, v0
	v_mov_b32_e32 v57, v0
	v_mov_b32_e32 v58, v0
	v_mov_b32_e32 v59, v0
	v_mov_b32_e32 v60, v0
	v_mov_b32_e32 v61, v0
	v_mov_b32_e32 v62, v0
	v_mov_b32_e32 v63, v0
	v_mov_b32_e32 v64, v0
	v_mov_b32_e32 v65, v0
	v_mov_b32_e32 v66, v0
	v_mov_b32_e32 v67, v0
	v_mov_b32_e32 v68, v0
	v_mov_b32_e32 v69, v0
	v_mov_b32_e32 v70, v0
	v_mov_b32_e32 v71, v0
	v_mov_b32_e32 v72, v0
	v_mov_b32_e32 v73, v0
	v_mov_b32_e32 v74, v0
	v_mov_b32_e32 v75, v0
	v_mov_b32_e32 v76, v0
	v_mov_b32_e32 v77, v0
	v_mov_b32_e32 v78, v0
	v_mov_b32_e32 v79, v0
	v_mov_b32_e32 v88, v0
	v_mov_b32_e32 v89, v0
	v_mov_b32_e32 v90, v0
	v_mov_b32_e32 v91, v0
	v_mov_b32_e32 v92, v0
	v_mov_b32_e32 v93, v0
	v_mov_b32_e32 v94, v0
	v_mov_b32_e32 v95, v0
	v_mov_b32_e32 v104, v0
	v_mov_b32_e32 v105, v0
	v_mov_b32_e32 v106, v0
	v_mov_b32_e32 v107, v0
	v_mov_b32_e32 v108, v0
	v_mov_b32_e32 v109, v0
	v_mov_b32_e32 v110, v0
	v_mov_b32_e32 v111, v0
	v_mov_b32_e32 v80, v0
	v_mov_b32_e32 v81, v0
	v_mov_b32_e32 v82, v0
	v_mov_b32_e32 v83, v0
	v_mov_b32_e32 v84, v0
	v_mov_b32_e32 v85, v0
	v_mov_b32_e32 v86, v0
	v_mov_b32_e32 v87, v0
	v_mov_b32_e32 v96, v0
	v_mov_b32_e32 v97, v0
	v_mov_b32_e32 v98, v0
	v_mov_b32_e32 v99, v0
	v_mov_b32_e32 v100, v0
	v_mov_b32_e32 v101, v0
	v_mov_b32_e32 v102, v0
	v_mov_b32_e32 v103, v0
	v_mov_b32_e32 v112, v0
	v_mov_b32_e32 v113, v0
	v_mov_b32_e32 v114, v0
	v_mov_b32_e32 v115, v0
	v_mov_b32_e32 v116, v0
	v_mov_b32_e32 v117, v0
	v_mov_b32_e32 v118, v0
	v_mov_b32_e32 v119, v0
	v_mov_b32_e32 v120, v0
	v_mov_b32_e32 v121, v0
	v_mov_b32_e32 v122, v0
	v_mov_b32_e32 v123, v0
	v_mov_b32_e32 v124, v0
	v_mov_b32_e32 v125, v0
	v_mov_b32_e32 v126, v0
	v_mov_b32_e32 v127, v0
	v_add_u32_e32 v161, 0x10000, v201
.LBB0_267:
	s_add_i32 s47, s22, 2
	s_add_u32 s20, s16, 0x100
	s_addc_u32 s21, s17, 0
	s_add_i32 s48, 0, 0x10000
	ds_read_b128 v[128:131], v161
	ds_read_b128 v[132:135], v161 offset:1024
	ds_read_b128 v[136:139], v161 offset:2048
	ds_read_b128 v[140:143], v161 offset:3072
	s_cmp_eq_u32 s11, s22
	s_cselect_b32 s22, s4, s13
	s_cselect_b32 s25, s7, s21
	s_cselect_b32 s24, s6, s20
	s_cselect_b32 s23, s5, s15
	s_add_i32 m0, s33, 0xc000
	ds_read_b128 v[144:147], v203
	ds_read_b128 v[166:169], v203 offset:1024
	ds_read_b128 v[170:173], v203 offset:2048
	ds_read_b128 v[174:177], v203 offset:3072
	ds_read_b128 v[204:207], v203 offset:4096
	ds_read_b128 v[208:211], v203 offset:5120
	ds_read_b128 v[212:215], v203 offset:6144
	ds_read_b128 v[216:219], v203 offset:7168
	global_load_lds_dwordx4 v162, s[16:17]
	s_add_i32 m0, s33, 0xe000
	s_nop 0
	global_load_lds_dwordx4 v164, s[16:17]
	s_waitcnt lgkmcnt(8)
	s_barrier
	s_waitcnt lgkmcnt(0)
	s_waitcnt lgkmcnt(0)
	v_mfma_f32_16x16x32_bf16 v[124:127], v[128:131], v[144:147], v[124:127]
	v_mfma_f32_16x16x32_bf16 v[120:123], v[136:139], v[144:147], v[120:123]
	v_mfma_f32_16x16x32_bf16 v[116:119], v[128:131], v[170:173], v[116:119]
	v_mfma_f32_16x16x32_bf16 v[112:115], v[136:139], v[170:173], v[112:115]
	v_mfma_f32_16x16x32_bf16 v[100:103], v[128:131], v[204:207], v[100:103]
	v_mfma_f32_16x16x32_bf16 v[96:99], v[136:139], v[204:207], v[96:99]
	v_mfma_f32_16x16x32_bf16 v[84:87], v[128:131], v[212:215], v[84:87]
	v_mfma_f32_16x16x32_bf16 v[80:83], v[136:139], v[212:215], v[80:83]
	v_mfma_f32_16x16x32_bf16 v[124:127], v[132:135], v[166:169], v[124:127]
	v_mfma_f32_16x16x32_bf16 v[120:123], v[140:143], v[166:169], v[120:123]
	v_mfma_f32_16x16x32_bf16 v[116:119], v[132:135], v[174:177], v[116:119]
	v_mfma_f32_16x16x32_bf16 v[112:115], v[140:143], v[174:177], v[112:115]
	v_mfma_f32_16x16x32_bf16 v[100:103], v[132:135], v[208:211], v[100:103]
	v_mfma_f32_16x16x32_bf16 v[96:99], v[140:143], v[208:211], v[96:99]
	v_mfma_f32_16x16x32_bf16 v[84:87], v[132:135], v[216:219], v[84:87]
	v_mfma_f32_16x16x32_bf16 v[80:83], v[140:143], v[216:219], v[80:83]
	s_barrier
	s_add_i32 s49, 0, 0x14000
	s_add_i32 s16, s48, s31
	ds_read_b128 v[220:223], v161 offset:16384
	ds_read_b128 v[224:227], v161 offset:17408
	ds_read_b128 v[228:231], v161 offset:18432
	ds_read_b128 v[232:235], v161 offset:19456
	s_add_u32 s84, s22, 0x80
	s_addc_u32 s85, s23, 0
	s_mov_b32 m0, s16
	s_nop 0
	global_load_lds_dwordx4 v148, s[22:23]
	s_add_i32 m0, s16, 0x2000
	s_nop 0
	global_load_lds_dwordx4 v160, s[22:23]
	s_barrier
; #define PG8_STAGE(bufoff, gbase, voff) do { _Pragma("unroll") for (int _i = 0; _i < 2; ++_i) \
;         __builtin_amdgcn_global_load_lds((const unsigned*)((const char*)(gbase) + (voff)[_i]), (LAS unsigned*)(lds + (bufoff) + ldsw + _i * 8192), 16, 0, 0); } while (0)
; #define PG8_LDA(dst, b, h) do { _Pragma("unroll") for (int m = 0; m < 4; ++m) _Pragma("unroll") for (int k = 0; k < 2; ++k) dst[m][k] = *(const LAS bf16x8*)(lds + PG8_SA(b, h) + aoff + m * 2048 + k * 1024); } while (0)
; #define PG8_LDB(dst, b, h) do { _Pragma("unroll") for (int n = 0; n < 2; ++n) _Pragma("unroll") for (int k = 0; k < 2; ++k) dst[n][k] = *(const LAS bf16x8*)(lds + PG8_SB(b, h) + boff + n * 2048 + k * 1024); } while (0)
; #define PG8_MMA(ai, bj, At, Bt) do { __builtin_amdgcn_s_setprio(1); _Pragma("unroll") for (int m = 0; m < 4; ++m) _Pragma("unroll") for (int n = 0; n < 2; ++n) _Pragma("unroll") for (int k = 0; k < 2; ++k) \
;         acc[ai][bj][m][n] = __builtin_amdgcn_mfma_f32_16x16x32_bf16(Bt[n][k], At[m][k], acc[ai][bj][m][n], 0, 0, 0); __builtin_amdgcn_s_setprio(0); } while (0)
; #define PG8_WAIT_V(n) asm volatile("s_waitcnt vmcnt(" #n ")" ::: "memory")
; #define PG8_WAIT_L(n) asm volatile("s_waitcnt lgkmcnt(" #n ")" ::: "memory")
; #define PG8_BAR __builtin_amdgcn_s_barrier()
; #define PG8_SCHED __builtin_amdgcn_sched_barrier(0)
; template <class Epi, class Sched>
; __device__ __forceinline__ void gemm_phase(LAS unsigned char* lds, const Gemm g, const Sched& S, const Epi& E) {
;     ...
;             PG8_BAR; PG8_WAIT_L(0); PG8_MMA(1, 0, At, B0); PG8_BAR; PG8_SCHED;
;             PG8_STAGE(PG8_SB(0, 1), b2 + hstep, voffB);
;             PG8_WAIT_V(6); PG8_BAR; PG8_MMA(1, 1, At, B1); PG8_BAR;
;             PG8_LDB(B0, 1, 0); PG8_SCHED; PG8_LDA(At, 1, 0); PG8_STAGE(PG8_SA(0, 1), a2 + hstep, voffA);
;             PG8_WAIT_L(8); PG8_BAR; PG8_WAIT_L(0); PG8_MMA(0, 0, At, B0); PG8_BAR; PG8_SCHED;
;             PG8_LDB(B1, 1, 1); PG8_STAGE(PG8_SB(1, 0), b3, voffB);
;             PG8_BAR; PG8_WAIT_L(0); PG8_MMA(0, 1, At, B1); PG8_BAR;
;             PG8_LDA(At, 1, 1); PG8_STAGE(PG8_SA(1, 0), a3, voffA);
;             PG8_BAR; PG8_WAIT_L(0); PG8_MMA(1, 0, At, B0); PG8_BAR; PG8_SCHED;
	s_waitcnt lgkmcnt(0)
	s_waitcnt lgkmcnt(0)
	v_mfma_f32_16x16x32_bf16 v[108:111], v[220:223], v[144:147], v[108:111]
	v_mfma_f32_16x16x32_bf16 v[104:107], v[228:231], v[144:147], v[104:107]
	v_mfma_f32_16x16x32_bf16 v[92:95], v[220:223], v[170:173], v[92:95]
	v_mfma_f32_16x16x32_bf16 v[88:91], v[228:231], v[170:173], v[88:91]
	v_mfma_f32_16x16x32_bf16 v[76:79], v[220:223], v[204:207], v[76:79]
	v_mfma_f32_16x16x32_bf16 v[72:75], v[228:231], v[204:207], v[72:75]
	v_mfma_f32_16x16x32_bf16 v[68:71], v[220:223], v[212:215], v[68:71]
	v_mfma_f32_16x16x32_bf16 v[64:67], v[228:231], v[212:215], v[64:67]
	v_mfma_f32_16x16x32_bf16 v[108:111], v[224:227], v[166:169], v[108:111]
	v_mfma_f32_16x16x32_bf16 v[104:107], v[232:235], v[166:169], v[104:107]
	v_mfma_f32_16x16x32_bf16 v[92:95], v[224:227], v[174:177], v[92:95]
	v_mfma_f32_16x16x32_bf16 v[88:91], v[232:235], v[174:177], v[88:91]
	v_mfma_f32_16x16x32_bf16 v[76:79], v[224:227], v[208:211], v[76:79]
	v_mfma_f32_16x16x32_bf16 v[72:75], v[232:235], v[208:211], v[72:75]
	v_mfma_f32_16x16x32_bf16 v[68:71], v[224:227], v[216:219], v[68:71]
	v_mfma_f32_16x16x32_bf16 v[64:67], v[232:235], v[216:219], v[64:67]
	s_mov_b32 m0, s33
	s_add_u32 s86, s24, 0x80
	s_addc_u32 s87, s25, 0
	s_barrier
	ds_read_b128 v[144:147], v203 offset:16384
	ds_read_b128 v[166:169], v203 offset:17408
	ds_read_b128 v[170:173], v203 offset:18432
	ds_read_b128 v[174:177], v203 offset:19456
	ds_read_b128 v[204:207], v203 offset:20480
	ds_read_b128 v[208:211], v203 offset:21504
	ds_read_b128 v[212:215], v203 offset:22528
	ds_read_b128 v[216:219], v203 offset:23552
	global_load_lds_dwordx4 v148, s[24:25]
	s_mov_b32 m0, s34
	s_nop 0
	global_load_lds_dwordx4 v160, s[24:25]
	s_barrier
	s_waitcnt lgkmcnt(0)
	s_waitcnt lgkmcnt(0)
	v_mfma_f32_16x16x32_bf16 v[60:63], v[128:131], v[144:147], v[60:63]
	v_mfma_f32_16x16x32_bf16 v[56:59], v[136:139], v[144:147], v[56:59]
	v_mfma_f32_16x16x32_bf16 v[52:55], v[128:131], v[170:173], v[52:55]
	v_mfma_f32_16x16x32_bf16 v[48:51], v[136:139], v[170:173], v[48:51]
	v_mfma_f32_16x16x32_bf16 v[36:39], v[128:131], v[204:207], v[36:39]
	v_mfma_f32_16x16x32_bf16 v[32:35], v[136:139], v[204:207], v[32:35]
	v_mfma_f32_16x16x32_bf16 v[20:23], v[128:131], v[212:215], v[20:23]
	v_mfma_f32_16x16x32_bf16 v[16:19], v[136:139], v[212:215], v[16:19]
	v_mfma_f32_16x16x32_bf16 v[60:63], v[132:135], v[166:169], v[60:63]
	v_mfma_f32_16x16x32_bf16 v[56:59], v[140:143], v[166:169], v[56:59]
	v_mfma_f32_16x16x32_bf16 v[52:55], v[132:135], v[174:177], v[52:55]
	v_mfma_f32_16x16x32_bf16 v[48:51], v[140:143], v[174:177], v[48:51]
	v_mfma_f32_16x16x32_bf16 v[36:39], v[132:135], v[208:211], v[36:39]
	v_mfma_f32_16x16x32_bf16 v[32:35], v[140:143], v[208:211], v[32:35]
	v_mfma_f32_16x16x32_bf16 v[20:23], v[132:135], v[216:219], v[20:23]
	v_mfma_f32_16x16x32_bf16 v[16:19], v[140:143], v[216:219], v[16:19]
	s_barrier
	s_add_u32 s16, s22, 0x80000
	s_addc_u32 s17, s23, 0
	s_add_i32 s48, s49, s31
	s_mov_b32 m0, s48
	s_nop 0
	global_load_lds_dwordx4 v148, s[16:17]
	s_add_i32 m0, s48, 0x2000
	s_nop 0
	global_load_lds_dwordx4 v160, s[16:17]
	s_waitcnt vmcnt(6)
	s_barrier
	v_mfma_f32_16x16x32_bf16 v[44:47], v[220:223], v[144:147], v[44:47]
	v_mfma_f32_16x16x32_bf16 v[40:43], v[228:231], v[144:147], v[40:43]
	v_mfma_f32_16x16x32_bf16 v[28:31], v[220:223], v[170:173], v[28:31]
	v_mfma_f32_16x16x32_bf16 v[24:27], v[228:231], v[170:173], v[24:27]
	v_mfma_f32_16x16x32_bf16 v[12:15], v[220:223], v[204:207], v[12:15]
	v_mfma_f32_16x16x32_bf16 v[8:11], v[228:231], v[204:207], v[8:11]
	v_mfma_f32_16x16x32_bf16 v[4:7], v[220:223], v[212:215], v[4:7]
	v_mfma_f32_16x16x32_bf16 v[0:3], v[228:231], v[212:215], v[0:3]
	v_mfma_f32_16x16x32_bf16 v[44:47], v[224:227], v[166:169], v[44:47]
	v_mfma_f32_16x16x32_bf16 v[40:43], v[232:235], v[166:169], v[40:43]
	v_mfma_f32_16x16x32_bf16 v[28:31], v[224:227], v[174:177], v[28:31]
	v_mfma_f32_16x16x32_bf16 v[24:27], v[232:235], v[174:177], v[24:27]
	v_mfma_f32_16x16x32_bf16 v[12:15], v[224:227], v[208:211], v[12:15]
	v_mfma_f32_16x16x32_bf16 v[8:11], v[232:235], v[208:211], v[8:11]
	v_mfma_f32_16x16x32_bf16 v[4:7], v[224:227], v[216:219], v[4:7]
	v_mfma_f32_16x16x32_bf16 v[0:3], v[232:235], v[216:219], v[0:3]
	s_add_i32 s48, 0, 0x18000
	s_barrier
	ds_read_b128 v[128:131], v161 offset:32768
	ds_read_b128 v[132:135], v161 offset:33792
	ds_read_b128 v[136:139], v161 offset:34816
	ds_read_b128 v[140:143], v161 offset:35840
	s_add_u32 s16, s24, 0x80000
	s_addc_u32 s17, s25, 0
	s_mov_b32 m0, s35
	ds_read_b128 v[144:147], v203 offset:32768
	ds_read_b128 v[166:169], v203 offset:33792
	ds_read_b128 v[170:173], v203 offset:34816
	ds_read_b128 v[174:177], v203 offset:35840
	ds_read_b128 v[204:207], v203 offset:36864
	ds_read_b128 v[208:211], v203 offset:37888
	ds_read_b128 v[212:215], v203 offset:38912
	ds_read_b128 v[216:219], v203 offset:39936
	global_load_lds_dwordx4 v148, s[16:17]
	s_mov_b32 m0, s36
	s_nop 0
	global_load_lds_dwordx4 v160, s[16:17]
	s_waitcnt lgkmcnt(8)
	s_barrier
	s_waitcnt lgkmcnt(0)
	s_waitcnt lgkmcnt(0)
	v_mfma_f32_16x16x32_bf16 v[124:127], v[128:131], v[144:147], v[124:127]
	v_mfma_f32_16x16x32_bf16 v[120:123], v[136:139], v[144:147], v[120:123]
	v_mfma_f32_16x16x32_bf16 v[116:119], v[128:131], v[170:173], v[116:119]
	v_mfma_f32_16x16x32_bf16 v[112:115], v[136:139], v[170:173], v[112:115]
	v_mfma_f32_16x16x32_bf16 v[100:103], v[128:131], v[204:207], v[100:103]
	v_mfma_f32_16x16x32_bf16 v[96:99], v[136:139], v[204:207], v[96:99]
	v_mfma_f32_16x16x32_bf16 v[84:87], v[128:131], v[212:215], v[84:87]
	v_mfma_f32_16x16x32_bf16 v[80:83], v[136:139], v[212:215], v[80:83]
	v_mfma_f32_16x16x32_bf16 v[124:127], v[132:135], v[166:169], v[124:127]
	v_mfma_f32_16x16x32_bf16 v[120:123], v[140:143], v[166:169], v[120:123]
	v_mfma_f32_16x16x32_bf16 v[116:119], v[132:135], v[174:177], v[116:119]
	v_mfma_f32_16x16x32_bf16 v[112:115], v[140:143], v[174:177], v[112:115]
	v_mfma_f32_16x16x32_bf16 v[100:103], v[132:135], v[208:211], v[100:103]
	v_mfma_f32_16x16x32_bf16 v[96:99], v[140:143], v[208:211], v[96:99]
	v_mfma_f32_16x16x32_bf16 v[84:87], v[132:135], v[216:219], v[84:87]
	v_mfma_f32_16x16x32_bf16 v[80:83], v[140:143], v[216:219], v[80:83]
	s_barrier
; #define PG8_STAGE(bufoff, gbase, voff) do { _Pragma("unroll") for (int _i = 0; _i < 2; ++_i) \
;         __builtin_amdgcn_global_load_lds((const unsigned*)((const char*)(gbase) + (voff)[_i]), (LAS unsigned*)(lds + (bufoff) + ldsw + _i * 8192), 16, 0, 0); } while (0)
; #define PG8_LDA(dst, b, h) do { _Pragma("unroll") for (int m = 0; m < 4; ++m) _Pragma("unroll") for (int k = 0; k < 2; ++k) dst[m][k] = *(const LAS bf16x8*)(lds + PG8_SA(b, h) + aoff + m * 2048 + k * 1024); } while (0)
; #define PG8_LDB(dst, b, h) do { _Pragma("unroll") for (int n = 0; n < 2; ++n) _Pragma("unroll") for (int k = 0; k < 2; ++k) dst[n][k] = *(const LAS bf16x8*)(lds + PG8_SB(b, h) + boff + n * 2048 + k * 1024); } while (0)
; #define PG8_MMA(ai, bj, At, Bt) do { __builtin_amdgcn_s_setprio(1); _Pragma("unroll") for (int m = 0; m < 4; ++m) _Pragma("unroll") for (int n = 0; n < 2; ++n) _Pragma("unroll") for (int k = 0; k < 2; ++k) \
;         acc[ai][bj][m][n] = __builtin_amdgcn_mfma_f32_16x16x32_bf16(Bt[n][k], At[m][k], acc[ai][bj][m][n], 0, 0, 0); __builtin_amdgcn_s_setprio(0); } while (0)
; #define PG8_WAIT_V(n) asm volatile("s_waitcnt vmcnt(" #n ")" ::: "memory")
; #define PG8_WAIT_L(n) asm volatile("s_waitcnt lgkmcnt(" #n ")" ::: "memory")
; #define PG8_BAR __builtin_amdgcn_s_barrier()
; #define PG8_SCHED __builtin_amdgcn_sched_barrier(0)
;     __device__ __forceinline__ void operator()(const f32x4 (&acc)[2][2][4][2], const Unit& u, int wr, int wc, int fr, int fq) const {
;         const int row0 = u.pm * BM + wr * 64 + fr, col0 = u.pn * BM + wc * 32 + 4 * fq;
;         if (u.slice >= 0) {
; template <class Epi, class Sched>
; __device__ __forceinline__ void gemm_phase(LAS unsigned char* lds, const Gemm g, const Sched& S, const Epi& E) {
;     ...
;             PG8_LDB(B1, 1, 1); PG8_STAGE(PG8_SB(1, 0), b3, voffB);
;             PG8_BAR; PG8_WAIT_L(0); PG8_MMA(0, 1, At, B1); PG8_BAR;
;             PG8_LDA(At, 1, 1); PG8_STAGE(PG8_SA(1, 0), a3, voffA);
;             PG8_BAR; PG8_WAIT_L(0); PG8_MMA(1, 0, At, B0); PG8_BAR; PG8_SCHED;
;             PG8_STAGE(PG8_SB(1, 1), b3 + hstep, voffB);
;             PG8_WAIT_V(6); PG8_BAR; PG8_MMA(1, 1, At, B1); PG8_BAR;
	s_add_i32 s24, 0, 0x1c000
	s_add_i32 s16, s48, s31
	s_mov_b32 m0, s16
	ds_read_b128 v[220:223], v161 offset:49152
	ds_read_b128 v[224:227], v161 offset:50176
	ds_read_b128 v[228:231], v161 offset:51200
	ds_read_b128 v[232:235], v161 offset:52224
	global_load_lds_dwordx4 v148, s[84:85]
	s_add_i32 m0, s16, 0x2000
	s_nop 0
	global_load_lds_dwordx4 v160, s[84:85]
	s_barrier
	s_waitcnt lgkmcnt(0)
	s_waitcnt lgkmcnt(0)
	v_mfma_f32_16x16x32_bf16 v[108:111], v[220:223], v[144:147], v[108:111]
	v_mfma_f32_16x16x32_bf16 v[104:107], v[228:231], v[144:147], v[104:107]
	v_mfma_f32_16x16x32_bf16 v[92:95], v[220:223], v[170:173], v[92:95]
	v_mfma_f32_16x16x32_bf16 v[88:91], v[228:231], v[170:173], v[88:91]
	v_mfma_f32_16x16x32_bf16 v[76:79], v[220:223], v[204:207], v[76:79]
	v_mfma_f32_16x16x32_bf16 v[72:75], v[228:231], v[204:207], v[72:75]
	v_mfma_f32_16x16x32_bf16 v[68:71], v[220:223], v[212:215], v[68:71]
	v_mfma_f32_16x16x32_bf16 v[64:67], v[228:231], v[212:215], v[64:67]
	v_mfma_f32_16x16x32_bf16 v[108:111], v[224:227], v[166:169], v[108:111]
	v_mfma_f32_16x16x32_bf16 v[104:107], v[232:235], v[166:169], v[104:107]
	v_mfma_f32_16x16x32_bf16 v[92:95], v[224:227], v[174:177], v[92:95]
	v_mfma_f32_16x16x32_bf16 v[88:91], v[232:235], v[174:177], v[88:91]
	v_mfma_f32_16x16x32_bf16 v[76:79], v[224:227], v[208:211], v[76:79]
	v_mfma_f32_16x16x32_bf16 v[72:75], v[232:235], v[208:211], v[72:75]
	v_mfma_f32_16x16x32_bf16 v[68:71], v[224:227], v[216:219], v[68:71]
	v_mfma_f32_16x16x32_bf16 v[64:67], v[232:235], v[216:219], v[64:67]
	s_mov_b32 m0, s39
	s_barrier
	ds_read_b128 v[144:147], v203 offset:49152
	ds_read_b128 v[166:169], v203 offset:50176
	ds_read_b128 v[170:173], v203 offset:51200
	ds_read_b128 v[174:177], v203 offset:52224
	ds_read_b128 v[204:207], v203 offset:53248
	ds_read_b128 v[208:211], v203 offset:54272
	ds_read_b128 v[212:215], v203 offset:55296
	ds_read_b128 v[216:219], v203 offset:56320
	global_load_lds_dwordx4 v148, s[86:87]
	s_mov_b32 m0, s40
	s_nop 0
	global_load_lds_dwordx4 v160, s[86:87]
	s_barrier
	s_waitcnt lgkmcnt(0)
	s_waitcnt lgkmcnt(0)
	v_mfma_f32_16x16x32_bf16 v[60:63], v[128:131], v[144:147], v[60:63]
	v_mfma_f32_16x16x32_bf16 v[56:59], v[136:139], v[144:147], v[56:59]
	v_mfma_f32_16x16x32_bf16 v[52:55], v[128:131], v[170:173], v[52:55]
	v_mfma_f32_16x16x32_bf16 v[48:51], v[136:139], v[170:173], v[48:51]
	v_mfma_f32_16x16x32_bf16 v[36:39], v[128:131], v[204:207], v[36:39]
	v_mfma_f32_16x16x32_bf16 v[32:35], v[136:139], v[204:207], v[32:35]
	v_mfma_f32_16x16x32_bf16 v[20:23], v[128:131], v[212:215], v[20:23]
	v_mfma_f32_16x16x32_bf16 v[16:19], v[136:139], v[212:215], v[16:19]
	v_mfma_f32_16x16x32_bf16 v[60:63], v[132:135], v[166:169], v[60:63]
	v_mfma_f32_16x16x32_bf16 v[56:59], v[140:143], v[166:169], v[56:59]
	v_mfma_f32_16x16x32_bf16 v[52:55], v[132:135], v[174:177], v[52:55]
	v_mfma_f32_16x16x32_bf16 v[48:51], v[140:143], v[174:177], v[48:51]
	v_mfma_f32_16x16x32_bf16 v[36:39], v[132:135], v[208:211], v[36:39]
	v_mfma_f32_16x16x32_bf16 v[32:35], v[140:143], v[208:211], v[32:35]
	v_mfma_f32_16x16x32_bf16 v[20:23], v[132:135], v[216:219], v[20:23]
	v_mfma_f32_16x16x32_bf16 v[16:19], v[140:143], v[216:219], v[16:19]
	s_barrier
	s_add_u32 s16, s22, 0x80080
	s_addc_u32 s17, s23, 0
	s_add_i32 s22, s24, s31
	s_mov_b32 m0, s22
	s_nop 0
	global_load_lds_dwordx4 v148, s[16:17]
	s_add_i32 m0, s22, 0x2000
	s_nop 0
	global_load_lds_dwordx4 v160, s[16:17]
	s_waitcnt vmcnt(6)
	s_barrier
	v_mfma_f32_16x16x32_bf16 v[44:47], v[220:223], v[144:147], v[44:47]
	v_mfma_f32_16x16x32_bf16 v[40:43], v[228:231], v[144:147], v[40:43]
	v_mfma_f32_16x16x32_bf16 v[28:31], v[220:223], v[170:173], v[28:31]
	v_mfma_f32_16x16x32_bf16 v[24:27], v[228:231], v[170:173], v[24:27]
	v_mfma_f32_16x16x32_bf16 v[12:15], v[220:223], v[204:207], v[12:15]
	v_mfma_f32_16x16x32_bf16 v[8:11], v[228:231], v[204:207], v[8:11]
	v_mfma_f32_16x16x32_bf16 v[4:7], v[220:223], v[212:215], v[4:7]
	v_mfma_f32_16x16x32_bf16 v[0:3], v[228:231], v[212:215], v[0:3]
	v_mfma_f32_16x16x32_bf16 v[44:47], v[224:227], v[166:169], v[44:47]
	v_mfma_f32_16x16x32_bf16 v[40:43], v[232:235], v[166:169], v[40:43]
	v_mfma_f32_16x16x32_bf16 v[28:31], v[224:227], v[174:177], v[28:31]
	v_mfma_f32_16x16x32_bf16 v[24:27], v[232:235], v[174:177], v[24:27]
	v_mfma_f32_16x16x32_bf16 v[12:15], v[224:227], v[208:211], v[12:15]
	v_mfma_f32_16x16x32_bf16 v[8:11], v[232:235], v[208:211], v[8:11]
	v_mfma_f32_16x16x32_bf16 v[4:7], v[224:227], v[216:219], v[4:7]
	v_mfma_f32_16x16x32_bf16 v[0:3], v[232:235], v[216:219], v[0:3]
	s_add_u32 s13, s13, 0x100
	s_addc_u32 s15, s15, 0
	s_cmp_ge_i32 s47, s45
	s_mov_b64 s[16:17], s[20:21]
	s_mov_b32 s22, s47
	s_barrier
	s_cbranch_scc0 .LBB0_267
	v_lshl_add_u32 v166, s46, 8, v200
	v_lshl_or_b32 v168, s44, 8, v202
	s_mov_b64 s[16:17], -1
	s_cmp_lt_i32 s82, 0
	v_ashrrev_i32_e32 v169, 31, v168
	v_ashrrev_i32_e32 v167, 31, v166
	s_cbranch_scc0 .LBB0_270
;     __device__ __forceinline__ void operator()(const f32x4 (&acc)[2][2][4][2], const Unit& u, int wr, int wc, int fr, int fq) const {
;     ...
;         const float* base = (u.pm < 32) ? base_lo : base_hi;
; #pragma unroll
;         for (int ai = 0; ai < 2; ++ai) {
;             f32x4 bs[4][2][2];
; #pragma unroll
;             for (int m = 0; m < 4; ++m) { const size_t off = (size_t)(row0 + ai * HALF + m * 16) * DM + col0;
; #pragma unroll
;                 for (int bj = 0; bj < 2; ++bj)
; #pragma unroll
;                     for (int n = 0; n < 2; ++n) bs[m][bj][n] = *(const f32x4*)(base + off + bj * HALF + n * 16); }
; #pragma unroll
;             for (int m = 0; m < 4; ++m) { const size_t off = (size_t)(row0 + ai * HALF + m * 16) * DM + col0;
; #pragma unroll
;                 for (int bj = 0; bj < 2; ++bj)
; #pragma unroll
;                     for (int n = 0; n < 2; ++n) *(f32x4*)(out + off + bj * HALF + n * 16) = bs[m][bj][n] + scale * acc[ai][bj][m][n]; }
;             asm volatile("" ::: "memory");
	v_lshlrev_b64 v[170:171], 2, v[168:169]
	v_lshl_add_u64 v[172:173], s[60:61], 0, v[170:171]
	v_lshlrev_b64 v[174:175], 13, v[166:167]
	v_lshl_add_u64 v[128:129], v[172:173], 0, v[174:175]
	global_load_dwordx4 v[204:207], v[128:129], off
	global_load_dwordx4 v[208:211], v[128:129], off offset:64
	global_load_dwordx4 v[212:215], v[128:129], off offset:512
	global_load_dwordx4 v[216:219], v[128:129], off offset:576
	v_or_b32_e32 v128, 16, v166
	v_ashrrev_i32_e32 v129, 31, v128
	v_lshlrev_b64 v[188:189], 13, v[128:129]
	v_lshl_add_u64 v[128:129], v[172:173], 0, v[188:189]
	global_load_dwordx4 v[220:223], v[128:129], off
	global_load_dwordx4 v[224:227], v[128:129], off offset:64
	global_load_dwordx4 v[228:231], v[128:129], off offset:512
	global_load_dwordx4 v[232:235], v[128:129], off offset:576
	v_or_b32_e32 v128, 32, v166
	v_ashrrev_i32_e32 v129, 31, v128
	v_lshlrev_b64 v[190:191], 13, v[128:129]
	v_lshl_add_u64 v[128:129], v[172:173], 0, v[190:191]
	global_load_dwordx4 v[236:239], v[128:129], off
	global_load_dwordx4 v[240:243], v[128:129], off offset:64
	global_load_dwordx4 v[144:147], v[128:129], off offset:512
	global_load_dwordx4 v[140:143], v[128:129], off offset:576
	v_or_b32_e32 v128, 48, v166
	v_ashrrev_i32_e32 v129, 31, v128
	v_lshlrev_b64 v[176:177], 13, v[128:129]
	v_lshl_add_u64 v[128:129], v[172:173], 0, v[176:177]
	global_load_dwordx4 v[244:247], v[128:129], off
	global_load_dwordx4 v[136:139], v[128:129], off offset:64
	global_load_dwordx4 v[132:135], v[128:129], off offset:512
	s_nop 0
	global_load_dwordx4 v[128:131], v[128:129], off offset:576
	v_lshl_add_u64 v[248:249], s[60:61], 0, v[174:175]
	v_lshl_add_u64 v[248:249], v[248:249], 0, v[170:171]
	v_lshl_add_u64 v[188:189], s[60:61], 0, v[188:189]
	v_lshl_add_u64 v[188:189], v[188:189], 0, v[170:171]
	s_mov_b64 s[16:17], 0x100000
	s_waitcnt vmcnt(0)
	v_pk_add_f32 v[206:207], v[206:207], v[126:127]
	v_pk_add_f32 v[204:205], v[204:205], v[124:125]
	global_store_dwordx4 v[248:249], v[204:207], off
	v_pk_add_f32 v[146:147], v[146:147], v[78:79]
	s_nop 0
	v_pk_add_f32 v[206:207], v[210:211], v[122:123]
	v_pk_add_f32 v[204:205], v[208:209], v[120:121]
	global_store_dwordx4 v[248:249], v[204:207], off offset:64
	v_pk_add_f32 v[144:145], v[144:145], v[76:77]
	v_pk_add_f32 v[142:143], v[142:143], v[74:75]
	v_pk_add_f32 v[206:207], v[214:215], v[110:111]
	v_pk_add_f32 v[204:205], v[212:213], v[108:109]
	global_store_dwordx4 v[248:249], v[204:207], off offset:512
	v_pk_add_f32 v[140:141], v[140:141], v[72:73]
	v_pk_add_f32 v[138:139], v[138:139], v[82:83]
	v_pk_add_f32 v[206:207], v[218:219], v[106:107]
	v_pk_add_f32 v[204:205], v[216:217], v[104:105]
	global_store_dwordx4 v[248:249], v[204:207], off offset:576
	v_pk_add_f32 v[136:137], v[136:137], v[80:81]
	v_pk_add_f32 v[134:135], v[134:135], v[70:71]
	v_pk_add_f32 v[206:207], v[222:223], v[118:119]
	v_pk_add_f32 v[204:205], v[220:221], v[116:117]
	global_store_dwordx4 v[188:189], v[204:207], off
	v_pk_add_f32 v[132:133], v[132:133], v[68:69]
	v_pk_add_f32 v[130:131], v[130:131], v[66:67]
	v_pk_add_f32 v[206:207], v[226:227], v[114:115]
	v_pk_add_f32 v[204:205], v[224:225], v[112:113]
	global_store_dwordx4 v[188:189], v[204:207], off offset:64
	v_pk_add_f32 v[128:129], v[128:129], v[64:65]
	s_nop 0
	v_pk_add_f32 v[206:207], v[230:231], v[94:95]
	v_pk_add_f32 v[204:205], v[228:229], v[92:93]
	global_store_dwordx4 v[188:189], v[204:207], off offset:512
	s_nop 1
	v_pk_add_f32 v[206:207], v[234:235], v[90:91]
	v_pk_add_f32 v[204:205], v[232:233], v[88:89]
	global_store_dwordx4 v[188:189], v[204:207], off offset:576
	v_lshl_add_u64 v[188:189], s[60:61], 0, v[190:191]
	v_lshl_add_u64 v[188:189], v[188:189], 0, v[170:171]
	v_pk_add_f32 v[206:207], v[238:239], v[102:103]
	v_pk_add_f32 v[204:205], v[236:237], v[100:101]
	global_store_dwordx4 v[188:189], v[144:147], off offset:512
	global_store_dwordx4 v[188:189], v[204:207], off
	global_store_dwordx4 v[188:189], v[140:143], off offset:576
	v_lshl_add_u64 v[144:145], s[60:61], 0, v[176:177]
	v_pk_add_f32 v[206:207], v[242:243], v[98:99]
	v_pk_add_f32 v[204:205], v[240:241], v[96:97]
	v_pk_add_f32 v[142:143], v[246:247], v[86:87]
	v_pk_add_f32 v[140:141], v[244:245], v[84:85]
	v_lshl_add_u64 v[144:145], v[144:145], 0, v[170:171]
	global_store_dwordx4 v[188:189], v[204:207], off offset:64
	global_store_dwordx4 v[144:145], v[140:143], off
	global_store_dwordx4 v[144:145], v[136:139], off offset:64
	global_store_dwordx4 v[144:145], v[132:135], off offset:512
	global_store_dwordx4 v[144:145], v[128:131], off offset:576
	v_lshl_add_u64 v[146:147], v[174:175], 0, s[16:17]
	s_mov_b64 s[16:17], 0x120000
	v_lshl_add_u64 v[128:129], v[172:173], 0, v[146:147]
	global_load_dwordx4 v[142:145], v[128:129], off
	global_load_dwordx4 v[204:207], v[128:129], off offset:64
	global_load_dwordx4 v[208:211], v[128:129], off offset:512
	global_load_dwordx4 v[212:215], v[128:129], off offset:576
	v_lshl_add_u64 v[176:177], v[174:175], 0, s[16:17]
	v_lshl_add_u64 v[128:129], v[172:173], 0, v[176:177]
	global_load_dwordx4 v[216:219], v[128:129], off
	global_load_dwordx4 v[220:223], v[128:129], off offset:64
	global_load_dwordx4 v[224:227], v[128:129], off offset:512
	global_load_dwordx4 v[228:231], v[128:129], off offset:576
	s_mov_b64 s[16:17], 0x140000
	v_lshl_add_u64 v[188:189], v[174:175], 0, s[16:17]
	s_mov_b64 s[16:17], 0x160000
	v_lshl_add_u64 v[128:129], v[172:173], 0, v[188:189]
	v_lshl_add_u64 v[140:141], v[174:175], 0, s[16:17]
	global_load_dwordx4 v[232:235], v[128:129], off
	global_load_dwordx4 v[236:239], v[128:129], off offset:64
	global_load_dwordx4 v[240:243], v[128:129], off offset:512
	global_load_dwordx4 v[244:247], v[128:129], off offset:576
	v_lshl_add_u64 v[128:129], v[172:173], 0, v[140:141]
	global_load_dwordx4 v[172:175], v[128:129], off
	global_load_dwordx4 v[136:139], v[128:129], off offset:64
	global_load_dwordx4 v[132:135], v[128:129], off offset:512
	s_nop 0
	global_load_dwordx4 v[128:131], v[128:129], off offset:576
	v_lshl_add_u64 v[146:147], s[60:61], 0, v[146:147]
	v_lshl_add_u64 v[146:147], v[146:147], 0, v[170:171]
	v_lshl_add_u64 v[140:141], s[60:61], 0, v[140:141]
	v_lshl_add_u64 v[140:141], v[140:141], 0, v[170:171]
	s_mov_b64 s[16:17], 0
	s_waitcnt vmcnt(0)
;     __device__ __forceinline__ void operator()(const f32x4 (&acc)[2][2][4][2], const Unit& u, int wr, int wc, int fr, int fq) const {
;     ...
;         const float* base = (u.pm < 32) ? base_lo : base_hi;
; #pragma unroll
;         for (int ai = 0; ai < 2; ++ai) {
;             f32x4 bs[4][2][2];
; #pragma unroll
;             for (int m = 0; m < 4; ++m) { const size_t off = (size_t)(row0 + ai * HALF + m * 16) * DM + col0;
; #pragma unroll
;                 for (int bj = 0; bj < 2; ++bj)
; #pragma unroll
;                     for (int n = 0; n < 2; ++n) bs[m][bj][n] = *(const f32x4*)(base + off + bj * HALF + n * 16); }
; #pragma unroll
;             for (int m = 0; m < 4; ++m) { const size_t off = (size_t)(row0 + ai * HALF + m * 16) * DM + col0;
; #pragma unroll
;                 for (int bj = 0; bj < 2; ++bj)
; #pragma unroll
;                     for (int n = 0; n < 2; ++n) *(f32x4*)(out + off + bj * HALF + n * 16) = bs[m][bj][n] + scale * acc[ai][bj][m][n]; }
;             asm volatile("" ::: "memory");
	v_pk_add_f32 v[144:145], v[62:63], v[144:145]
	v_pk_add_f32 v[142:143], v[60:61], v[142:143]
	global_store_dwordx4 v[146:147], v[142:145], off
	v_pk_add_f32 v[138:139], v[18:19], v[138:139]
	s_nop 0
	v_pk_add_f32 v[144:145], v[58:59], v[206:207]
	v_pk_add_f32 v[142:143], v[56:57], v[204:205]
	global_store_dwordx4 v[146:147], v[142:145], off offset:64
	v_pk_add_f32 v[136:137], v[16:17], v[136:137]
	v_pk_add_f32 v[134:135], v[6:7], v[134:135]
	v_pk_add_f32 v[144:145], v[46:47], v[210:211]
	v_pk_add_f32 v[142:143], v[44:45], v[208:209]
	global_store_dwordx4 v[146:147], v[142:145], off offset:512
	v_pk_add_f32 v[132:133], v[4:5], v[132:133]
	v_pk_add_f32 v[130:131], v[2:3], v[130:131]
	v_pk_add_f32 v[144:145], v[42:43], v[214:215]
	v_pk_add_f32 v[142:143], v[40:41], v[212:213]
	global_store_dwordx4 v[146:147], v[142:145], off offset:576
	v_lshl_add_u64 v[146:147], s[60:61], 0, v[176:177]
	v_lshl_add_u64 v[146:147], v[146:147], 0, v[170:171]
	v_pk_add_f32 v[144:145], v[54:55], v[218:219]
	v_pk_add_f32 v[142:143], v[52:53], v[216:217]
	global_store_dwordx4 v[146:147], v[142:145], off
	v_pk_add_f32 v[128:129], v[0:1], v[128:129]
	global_store_dwordx4 v[140:141], v[136:139], off offset:64
	v_pk_add_f32 v[144:145], v[50:51], v[222:223]
	v_pk_add_f32 v[142:143], v[48:49], v[220:221]
	global_store_dwordx4 v[146:147], v[142:145], off offset:64
	global_store_dwordx4 v[140:141], v[132:135], off offset:512
	global_store_dwordx4 v[140:141], v[128:131], off offset:576
	v_pk_add_f32 v[144:145], v[30:31], v[226:227]
	v_pk_add_f32 v[142:143], v[28:29], v[224:225]
	global_store_dwordx4 v[146:147], v[142:145], off offset:512
	s_nop 1
	v_pk_add_f32 v[144:145], v[26:27], v[230:231]
	v_pk_add_f32 v[142:143], v[24:25], v[228:229]
	global_store_dwordx4 v[146:147], v[142:145], off offset:576
	v_lshl_add_u64 v[146:147], s[60:61], 0, v[188:189]
	v_lshl_add_u64 v[146:147], v[146:147], 0, v[170:171]
	v_pk_add_f32 v[144:145], v[38:39], v[234:235]
	v_pk_add_f32 v[142:143], v[36:37], v[232:233]
	global_store_dwordx4 v[146:147], v[142:145], off
	s_nop 1
	v_pk_add_f32 v[144:145], v[34:35], v[238:239]
	v_pk_add_f32 v[142:143], v[32:33], v[236:237]
	global_store_dwordx4 v[146:147], v[142:145], off offset:64
	s_nop 1
	v_pk_add_f32 v[144:145], v[14:15], v[242:243]
	v_pk_add_f32 v[142:143], v[12:13], v[240:241]
	global_store_dwordx4 v[146:147], v[142:145], off offset:512
	s_nop 1
	v_pk_add_f32 v[144:145], v[10:11], v[246:247]
	v_pk_add_f32 v[142:143], v[8:9], v[244:245]
	global_store_dwordx4 v[146:147], v[142:145], off offset:576
	s_nop 1
	v_pk_add_f32 v[144:145], v[22:23], v[174:175]
	v_pk_add_f32 v[142:143], v[20:21], v[172:173]
	global_store_dwordx4 v[140:141], v[142:145], off
